# GEMM phase heads: vmcnt(8)+lgkmcnt(0) merged into one s_waitcnt and the redundant lgkmcnt(0) after s_setprio 1 dropped (44 sites), on v32
# speedup vs baseline: 1.0003x; 1.0003x over previous
; #define PG8_STAGE(bufoff, gbase, voff) do { _Pragma("unroll") for (int _i = 0; _i < 2; ++_i) \
;         __builtin_amdgcn_global_load_lds((const unsigned*)((const char*)(gbase) + (voff)[_i]), (LAS unsigned*)(lds + (bufoff) + ldsw + _i * 8192), 16, 0, 0); } while (0)
; #define PG8_LDA(dst, b, h) do { _Pragma("unroll") for (int m = 0; m < 4; ++m) _Pragma("unroll") for (int k = 0; k < 2; ++k) dst[m][k] = *(const LAS bf16x8*)(lds + PG8_SA(b, h) + aoff + m * 2048 + k * 1024); } while (0)
; #define PG8_LDB(dst, b, h) do { _Pragma("unroll") for (int n = 0; n < 2; ++n) _Pragma("unroll") for (int k = 0; k < 2; ++k) dst[n][k] = *(const LAS bf16x8*)(lds + PG8_SB(b, h) + boff + n * 2048 + k * 1024); } while (0)
; #define PG8_MMA(ai, bj, At, Bt) do { __builtin_amdgcn_s_setprio(1); _Pragma("unroll") for (int m = 0; m < 4; ++m) _Pragma("unroll") for (int n = 0; n < 2; ++n) _Pragma("unroll") for (int k = 0; k < 2; ++k) \
;         acc[ai][bj][m][n] = __builtin_amdgcn_mfma_f32_16x16x32_bf16(Bt[n][k], At[m][k], acc[ai][bj][m][n], 0, 0, 0); __builtin_amdgcn_s_setprio(0); } while (0)
; #define PG8_WAIT_V(n) asm volatile("s_waitcnt vmcnt(" #n ")" ::: "memory")
; #define PG8_WAIT_L(n) asm volatile("s_waitcnt lgkmcnt(" #n ")" ::: "memory")
; #define PG8_BAR __builtin_amdgcn_s_barrier()
; #define PG8_SCHED __builtin_amdgcn_sched_barrier(0)
; template <class Epi>
; __device__ __forceinline__ void gemm_phase(LAS unsigned char* lds, const Gemm g, const StaticOrder& S, const Epi& E) {
;     ...
;             PG8_LDB(B0, 0, 0); PG8_LDB(B1, 0, 1); PG8_SCHED; PG8_LDA(At, 0, 0); PG8_STAGE(PG8_SA(1, 1), a1 + hstepA, voffA);
;             PG8_WAIT_V(8); PG8_WAIT_L(0); PG8_BAR; PG8_MMA(0, 0, At, B0); PG8_MMA(0, 1, At, B1); PG8_BAR; PG8_SCHED;
;             PG8_LDA(At, 0, 1); PG8_STAGE(PG8_SB(0, 0), b2, voffB); PG8_STAGE(PG8_SB(0, 1), b2 + hstepB, voffB); PG8_STAGE(PG8_SA(0, 0), a2, voffA);
;             PG8_WAIT_V(8); PG8_WAIT_L(0); PG8_BAR; PG8_MMA(1, 0, At, B0); PG8_MMA(1, 1, At, B1); PG8_BAR; PG8_SCHED;
.LBB0_245:
	ds_read_b128 v[152:155], v148
	ds_read_b128 v[156:159], v148 offset:1024
	ds_read_b128 v[160:163], v148 offset:2048
	ds_read_b128 v[164:167], v148 offset:3072
	ds_read_b128 v[168:171], v149
	ds_read_b128 v[172:175], v149 offset:1024
	ds_read_b128 v[176:179], v149 offset:2048
	ds_read_b128 v[180:183], v149 offset:3072
	s_add_i32 s64, s26, 2
	s_add_u32 s27, s24, 0xfff80080
	s_addc_u32 s30, s25, -1
	s_cmp_eq_u32 s54, s26
	s_cselect_b32 s26, s61, s62
	s_cselect_b32 s31, s15, s30
	s_cselect_b32 s30, s17, s27
	s_cselect_b32 s27, s60, s63
	v_lshl_add_u64 v[220:221], s[24:25], 0, v[138:139]
	s_add_i32 m0, s44, 0xc000
	ds_read_b128 v[184:187], v150
	ds_read_b128 v[188:191], v150 offset:1024
	ds_read_b128 v[192:195], v150 offset:2048
	ds_read_b128 v[196:199], v150 offset:3072
	ds_read_b128 v[200:203], v150 offset:4096
	ds_read_b128 v[208:211], v150 offset:5120
	ds_read_b128 v[212:215], v150 offset:6144
	ds_read_b128 v[216:219], v150 offset:7168
	global_load_lds_dwordx4 v[220:221], off
	v_lshl_add_u64 v[220:221], s[24:25], 0, v[140:141]
	s_add_i32 m0, s44, 0xe000
	s_nop 0
	global_load_lds_dwordx4 v[220:221], off
	s_waitcnt vmcnt(8) lgkmcnt(0)
	s_barrier
	s_setprio 1
	v_mfma_f32_16x16x32_bf16 v[120:123], v[152:155], v[184:187], v[120:123]
	v_mfma_f32_16x16x32_bf16 v[120:123], v[156:159], v[188:191], v[120:123]
	v_mfma_f32_16x16x32_bf16 v[116:119], v[164:167], v[188:191], v[116:119]
	v_mfma_f32_16x16x32_bf16 v[116:119], v[160:163], v[184:187], v[116:119]
	v_mfma_f32_16x16x32_bf16 v[124:127], v[168:171], v[184:187], v[124:127]
	v_mfma_f32_16x16x32_bf16 v[124:127], v[172:175], v[188:191], v[124:127]
	v_mfma_f32_16x16x32_bf16 v[112:115], v[180:183], v[188:191], v[112:115]
	v_mfma_f32_16x16x32_bf16 v[112:115], v[176:179], v[184:187], v[112:115]
	v_mfma_f32_16x16x32_bf16 v[96:99], v[176:179], v[192:195], v[96:99]
	v_mfma_f32_16x16x32_bf16 v[96:99], v[180:183], v[196:199], v[96:99]
	v_mfma_f32_16x16x32_bf16 v[104:107], v[172:175], v[196:199], v[104:107]
	v_mfma_f32_16x16x32_bf16 v[104:107], v[168:171], v[192:195], v[104:107]
	v_mfma_f32_16x16x32_bf16 v[100:103], v[160:163], v[192:195], v[100:103]
	v_mfma_f32_16x16x32_bf16 v[100:103], v[164:167], v[196:199], v[100:103]
	v_mfma_f32_16x16x32_bf16 v[108:111], v[156:159], v[196:199], v[108:111]
	v_mfma_f32_16x16x32_bf16 v[108:111], v[152:155], v[192:195], v[108:111]
	s_setprio 0
	s_setprio 1
	v_mfma_f32_16x16x32_bf16 v[92:95], v[152:155], v[200:203], v[92:95]
	v_mfma_f32_16x16x32_bf16 v[92:95], v[156:159], v[208:211], v[92:95]
	v_mfma_f32_16x16x32_bf16 v[84:87], v[164:167], v[208:211], v[84:87]
	v_mfma_f32_16x16x32_bf16 v[84:87], v[160:163], v[200:203], v[84:87]
	v_mfma_f32_16x16x32_bf16 v[88:91], v[168:171], v[200:203], v[88:91]
	v_mfma_f32_16x16x32_bf16 v[88:91], v[172:175], v[208:211], v[88:91]
	v_mfma_f32_16x16x32_bf16 v[80:83], v[180:183], v[208:211], v[80:83]
	v_mfma_f32_16x16x32_bf16 v[80:83], v[176:179], v[200:203], v[80:83]
	v_mfma_f32_16x16x32_bf16 v[64:67], v[176:179], v[212:215], v[64:67]
	v_mfma_f32_16x16x32_bf16 v[64:67], v[180:183], v[216:219], v[64:67]
	v_mfma_f32_16x16x32_bf16 v[72:75], v[172:175], v[216:219], v[72:75]
	v_mfma_f32_16x16x32_bf16 v[72:75], v[168:171], v[212:215], v[72:75]
	v_mfma_f32_16x16x32_bf16 v[68:71], v[160:163], v[212:215], v[68:71]
	v_mfma_f32_16x16x32_bf16 v[68:71], v[164:167], v[216:219], v[68:71]
	v_mfma_f32_16x16x32_bf16 v[76:79], v[156:159], v[216:219], v[76:79]
	v_mfma_f32_16x16x32_bf16 v[76:79], v[152:155], v[212:215], v[76:79]
	s_setprio 0
	s_barrier
	s_add_i32 s65, s57, s33
	v_lshl_add_u64 v[220:221], s[26:27], 0, v[132:133]
	s_mov_b32 m0, s65
	ds_read_b128 v[184:187], v150 offset:16384
	ds_read_b128 v[188:191], v150 offset:17408
	ds_read_b128 v[192:195], v150 offset:18432
	ds_read_b128 v[196:199], v150 offset:19456
	ds_read_b128 v[200:203], v150 offset:20480
	ds_read_b128 v[208:211], v150 offset:21504
	ds_read_b128 v[212:215], v150 offset:22528
	ds_read_b128 v[216:219], v150 offset:23552
	global_load_lds_dwordx4 v[220:221], off
	s_add_i32 m0, s65, 0x2000
	s_add_u32 s66, s26, 0x80000
	v_lshl_add_u64 v[222:223], s[26:27], 0, v[128:129]
	s_addc_u32 s67, s27, 0
	s_add_i32 s65, s58, s33
	global_load_lds_dwordx4 v[222:223], off
	v_lshl_add_u64 v[224:225], s[66:67], 0, v[132:133]
	s_mov_b32 m0, s65
	v_lshl_add_u64 v[226:227], s[30:31], 0, v[130:131]
	global_load_lds_dwordx4 v[224:225], off
	v_lshl_add_u64 v[224:225], s[66:67], 0, v[128:129]
	s_add_i32 m0, s65, 0x2000
	s_nop 0
	global_load_lds_dwordx4 v[224:225], off
	v_lshl_add_u64 v[224:225], s[30:31], 0, v[134:135]
	s_mov_b32 m0, s44
	s_nop 0
	global_load_lds_dwordx4 v[224:225], off
	s_mov_b32 m0, s45
	s_nop 0
	global_load_lds_dwordx4 v[226:227], off
	s_waitcnt vmcnt(8) lgkmcnt(0)
	s_barrier
; #define PG8_STAGE(bufoff, gbase, voff) do { _Pragma("unroll") for (int _i = 0; _i < 2; ++_i) \
;         __builtin_amdgcn_global_load_lds((const unsigned*)((const char*)(gbase) + (voff)[_i]), (LAS unsigned*)(lds + (bufoff) + ldsw + _i * 8192), 16, 0, 0); } while (0)
; #define PG8_LDA(dst, b, h) do { _Pragma("unroll") for (int m = 0; m < 4; ++m) _Pragma("unroll") for (int k = 0; k < 2; ++k) dst[m][k] = *(const LAS bf16x8*)(lds + PG8_SA(b, h) + aoff + m * 2048 + k * 1024); } while (0)
; #define PG8_LDB(dst, b, h) do { _Pragma("unroll") for (int n = 0; n < 2; ++n) _Pragma("unroll") for (int k = 0; k < 2; ++k) dst[n][k] = *(const LAS bf16x8*)(lds + PG8_SB(b, h) + boff + n * 2048 + k * 1024); } while (0)
; #define PG8_MMA(ai, bj, At, Bt) do { __builtin_amdgcn_s_setprio(1); _Pragma("unroll") for (int m = 0; m < 4; ++m) _Pragma("unroll") for (int n = 0; n < 2; ++n) _Pragma("unroll") for (int k = 0; k < 2; ++k) \
;         acc[ai][bj][m][n] = __builtin_amdgcn_mfma_f32_16x16x32_bf16(Bt[n][k], At[m][k], acc[ai][bj][m][n], 0, 0, 0); __builtin_amdgcn_s_setprio(0); } while (0)
; #define PG8_WAIT_V(n) asm volatile("s_waitcnt vmcnt(" #n ")" ::: "memory")
; #define PG8_WAIT_L(n) asm volatile("s_waitcnt lgkmcnt(" #n ")" ::: "memory")
; #define PG8_BAR __builtin_amdgcn_s_barrier()
; #define PG8_SCHED __builtin_amdgcn_sched_barrier(0)
; template <class Epi>
; __device__ __forceinline__ void gemm_phase(LAS unsigned char* lds, const Gemm g, const StaticOrder& S, const Epi& E) {
;     ...
;             PG8_WAIT_V(8); PG8_WAIT_L(0); PG8_BAR; PG8_MMA(1, 0, At, B0); PG8_MMA(1, 1, At, B1); PG8_BAR; PG8_SCHED;
;             PG8_LDB(B0, 1, 0); PG8_LDB(B1, 1, 1); PG8_SCHED; PG8_LDA(At, 1, 0); PG8_STAGE(PG8_SA(0, 1), a2 + hstepA, voffA);
;             PG8_WAIT_V(8); PG8_WAIT_L(0); PG8_BAR; PG8_MMA(0, 0, At, B0); PG8_MMA(0, 1, At, B1); PG8_BAR; PG8_SCHED;
	s_setprio 1
	v_mfma_f32_16x16x32_bf16 v[60:63], v[152:155], v[184:187], v[60:63]
	v_mfma_f32_16x16x32_bf16 v[60:63], v[156:159], v[188:191], v[60:63]
	v_mfma_f32_16x16x32_bf16 v[52:55], v[164:167], v[188:191], v[52:55]
	v_mfma_f32_16x16x32_bf16 v[52:55], v[160:163], v[184:187], v[52:55]
	v_mfma_f32_16x16x32_bf16 v[56:59], v[168:171], v[184:187], v[56:59]
	v_mfma_f32_16x16x32_bf16 v[56:59], v[172:175], v[188:191], v[56:59]
	v_mfma_f32_16x16x32_bf16 v[48:51], v[180:183], v[188:191], v[48:51]
	v_mfma_f32_16x16x32_bf16 v[48:51], v[176:179], v[184:187], v[48:51]
	v_mfma_f32_16x16x32_bf16 v[32:35], v[176:179], v[192:195], v[32:35]
	v_mfma_f32_16x16x32_bf16 v[32:35], v[180:183], v[196:199], v[32:35]
	v_mfma_f32_16x16x32_bf16 v[40:43], v[172:175], v[196:199], v[40:43]
	v_mfma_f32_16x16x32_bf16 v[40:43], v[168:171], v[192:195], v[40:43]
	v_mfma_f32_16x16x32_bf16 v[36:39], v[160:163], v[192:195], v[36:39]
	v_mfma_f32_16x16x32_bf16 v[36:39], v[164:167], v[196:199], v[36:39]
	v_mfma_f32_16x16x32_bf16 v[44:47], v[156:159], v[196:199], v[44:47]
	v_mfma_f32_16x16x32_bf16 v[44:47], v[152:155], v[192:195], v[44:47]
	s_setprio 0
	s_setprio 1
	v_mfma_f32_16x16x32_bf16 v[28:31], v[152:155], v[200:203], v[28:31]
	v_mfma_f32_16x16x32_bf16 v[28:31], v[156:159], v[208:211], v[28:31]
	v_mfma_f32_16x16x32_bf16 v[20:23], v[164:167], v[208:211], v[20:23]
	v_mfma_f32_16x16x32_bf16 v[20:23], v[160:163], v[200:203], v[20:23]
	v_mfma_f32_16x16x32_bf16 v[24:27], v[168:171], v[200:203], v[24:27]
	v_mfma_f32_16x16x32_bf16 v[24:27], v[172:175], v[208:211], v[24:27]
	v_mfma_f32_16x16x32_bf16 v[16:19], v[180:183], v[208:211], v[16:19]
	v_mfma_f32_16x16x32_bf16 v[16:19], v[176:179], v[200:203], v[16:19]
	v_mfma_f32_16x16x32_bf16 v[0:3], v[176:179], v[212:215], v[0:3]
	v_mfma_f32_16x16x32_bf16 v[0:3], v[180:183], v[216:219], v[0:3]
	v_mfma_f32_16x16x32_bf16 v[8:11], v[172:175], v[216:219], v[8:11]
	v_mfma_f32_16x16x32_bf16 v[8:11], v[168:171], v[212:215], v[8:11]
	v_mfma_f32_16x16x32_bf16 v[4:7], v[160:163], v[212:215], v[4:7]
	v_mfma_f32_16x16x32_bf16 v[4:7], v[164:167], v[216:219], v[4:7]
	v_mfma_f32_16x16x32_bf16 v[12:15], v[156:159], v[216:219], v[12:15]
	v_mfma_f32_16x16x32_bf16 v[12:15], v[152:155], v[212:215], v[12:15]
	s_setprio 0
	s_barrier
	s_add_i32 s65, 0, 0x18000
	v_add_u32_e32 v151, s65, v146
	s_add_i32 s66, 0, 0x1c000
	ds_read_b128 v[152:155], v151
	ds_read_b128 v[156:159], v151 offset:1024
	ds_read_b128 v[160:163], v151 offset:2048
	ds_read_b128 v[164:167], v151 offset:3072
	v_add_u32_e32 v151, s66, v146
	ds_read_b128 v[168:171], v151
	ds_read_b128 v[172:175], v151 offset:1024
	ds_read_b128 v[176:179], v151 offset:2048
	ds_read_b128 v[180:183], v151 offset:3072
	s_add_u32 s30, s30, 0x80000
	s_addc_u32 s31, s31, 0
	s_mov_b32 m0, s46
	v_lshl_add_u64 v[230:231], s[30:31], 0, v[134:135]
	ds_read_b128 v[184:187], v150 offset:32768
	ds_read_b128 v[188:191], v150 offset:33792
	ds_read_b128 v[192:195], v150 offset:34816
	ds_read_b128 v[196:199], v150 offset:35840
	ds_read_b128 v[200:203], v150 offset:36864
	ds_read_b128 v[208:211], v150 offset:37888
	ds_read_b128 v[212:215], v150 offset:38912
	ds_read_b128 v[216:219], v150 offset:39936
	global_load_lds_dwordx4 v[230:231], off
	v_lshl_add_u64 v[230:231], s[30:31], 0, v[130:131]
	s_mov_b32 m0, s47
	s_nop 0
	global_load_lds_dwordx4 v[230:231], off
	s_waitcnt vmcnt(8) lgkmcnt(0)
	s_barrier
	s_setprio 1
	v_mfma_f32_16x16x32_bf16 v[120:123], v[152:155], v[184:187], v[120:123]
	v_mfma_f32_16x16x32_bf16 v[120:123], v[156:159], v[188:191], v[120:123]
	v_mfma_f32_16x16x32_bf16 v[116:119], v[164:167], v[188:191], v[116:119]
	v_mfma_f32_16x16x32_bf16 v[116:119], v[160:163], v[184:187], v[116:119]
	v_mfma_f32_16x16x32_bf16 v[124:127], v[168:171], v[184:187], v[124:127]
	v_mfma_f32_16x16x32_bf16 v[124:127], v[172:175], v[188:191], v[124:127]
	v_mfma_f32_16x16x32_bf16 v[112:115], v[180:183], v[188:191], v[112:115]
	v_mfma_f32_16x16x32_bf16 v[112:115], v[176:179], v[184:187], v[112:115]
	v_mfma_f32_16x16x32_bf16 v[96:99], v[176:179], v[192:195], v[96:99]
	v_mfma_f32_16x16x32_bf16 v[96:99], v[180:183], v[196:199], v[96:99]
	v_mfma_f32_16x16x32_bf16 v[104:107], v[172:175], v[196:199], v[104:107]
	v_mfma_f32_16x16x32_bf16 v[104:107], v[168:171], v[192:195], v[104:107]
	v_mfma_f32_16x16x32_bf16 v[100:103], v[160:163], v[192:195], v[100:103]
	v_mfma_f32_16x16x32_bf16 v[100:103], v[164:167], v[196:199], v[100:103]
	v_mfma_f32_16x16x32_bf16 v[108:111], v[156:159], v[196:199], v[108:111]
	v_mfma_f32_16x16x32_bf16 v[108:111], v[152:155], v[192:195], v[108:111]
	s_setprio 0
	s_setprio 1
	v_mfma_f32_16x16x32_bf16 v[92:95], v[152:155], v[200:203], v[92:95]
	v_mfma_f32_16x16x32_bf16 v[92:95], v[156:159], v[208:211], v[92:95]
	v_mfma_f32_16x16x32_bf16 v[84:87], v[164:167], v[208:211], v[84:87]
	v_mfma_f32_16x16x32_bf16 v[84:87], v[160:163], v[200:203], v[84:87]
	v_mfma_f32_16x16x32_bf16 v[88:91], v[168:171], v[200:203], v[88:91]
	v_mfma_f32_16x16x32_bf16 v[88:91], v[172:175], v[208:211], v[88:91]
	v_mfma_f32_16x16x32_bf16 v[80:83], v[180:183], v[208:211], v[80:83]
	v_mfma_f32_16x16x32_bf16 v[80:83], v[176:179], v[200:203], v[80:83]
	v_mfma_f32_16x16x32_bf16 v[64:67], v[176:179], v[212:215], v[64:67]
	v_mfma_f32_16x16x32_bf16 v[64:67], v[180:183], v[216:219], v[64:67]
	v_mfma_f32_16x16x32_bf16 v[72:75], v[172:175], v[216:219], v[72:75]
	v_mfma_f32_16x16x32_bf16 v[72:75], v[168:171], v[212:215], v[72:75]
	v_mfma_f32_16x16x32_bf16 v[68:71], v[160:163], v[212:215], v[68:71]
	v_mfma_f32_16x16x32_bf16 v[68:71], v[164:167], v[216:219], v[68:71]
	v_mfma_f32_16x16x32_bf16 v[76:79], v[156:159], v[216:219], v[76:79]
	v_mfma_f32_16x16x32_bf16 v[76:79], v[152:155], v[212:215], v[76:79]
	s_setprio 0
	s_barrier
; #define PG8_STAGE(bufoff, gbase, voff) do { _Pragma("unroll") for (int _i = 0; _i < 2; ++_i) \
;         __builtin_amdgcn_global_load_lds((const unsigned*)((const char*)(gbase) + (voff)[_i]), (LAS unsigned*)(lds + (bufoff) + ldsw + _i * 8192), 16, 0, 0); } while (0)
; #define PG8_LDA(dst, b, h) do { _Pragma("unroll") for (int m = 0; m < 4; ++m) _Pragma("unroll") for (int k = 0; k < 2; ++k) dst[m][k] = *(const LAS bf16x8*)(lds + PG8_SA(b, h) + aoff + m * 2048 + k * 1024); } while (0)
; #define PG8_MMA(ai, bj, At, Bt) do { __builtin_amdgcn_s_setprio(1); _Pragma("unroll") for (int m = 0; m < 4; ++m) _Pragma("unroll") for (int n = 0; n < 2; ++n) _Pragma("unroll") for (int k = 0; k < 2; ++k) \
;         acc[ai][bj][m][n] = __builtin_amdgcn_mfma_f32_16x16x32_bf16(Bt[n][k], At[m][k], acc[ai][bj][m][n], 0, 0, 0); __builtin_amdgcn_s_setprio(0); } while (0)
; #define PG8_WAIT_V(n) asm volatile("s_waitcnt vmcnt(" #n ")" ::: "memory")
; #define PG8_WAIT_L(n) asm volatile("s_waitcnt lgkmcnt(" #n ")" ::: "memory")
; #define PG8_BAR __builtin_amdgcn_s_barrier()
; #define PG8_SCHED __builtin_amdgcn_sched_barrier(0)
; template <class Epi>
; __device__ __forceinline__ void gemm_phase(LAS unsigned char* lds, const Gemm g, const StaticOrder& S, const Epi& E) {
;     ...
;             PG8_LDA(At, 1, 1); PG8_STAGE(PG8_SB(1, 0), b3, voffB); PG8_STAGE(PG8_SB(1, 1), b3 + hstepB, voffB); PG8_STAGE(PG8_SA(1, 0), a3, voffA);
;             PG8_WAIT_V(8); PG8_WAIT_L(0); PG8_BAR; PG8_MMA(1, 0, At, B0); PG8_MMA(1, 1, At, B1); PG8_BAR; PG8_SCHED;
	s_add_i32 s30, s65, s33
	v_lshl_add_u64 v[220:221], v[220:221], 0, s[8:9]
	s_mov_b32 m0, s30
	ds_read_b128 v[184:187], v150 offset:49152
	ds_read_b128 v[188:191], v150 offset:50176
	ds_read_b128 v[192:195], v150 offset:51200
	ds_read_b128 v[196:199], v150 offset:52224
	ds_read_b128 v[200:203], v150 offset:53248
	ds_read_b128 v[208:211], v150 offset:54272
	ds_read_b128 v[212:215], v150 offset:55296
	ds_read_b128 v[216:219], v150 offset:56320
	global_load_lds_dwordx4 v[220:221], off
	s_add_i32 m0, s30, 0x2000
	s_add_u32 s26, s26, 0x80080
	v_lshl_add_u64 v[220:221], v[222:223], 0, s[8:9]
	s_addc_u32 s27, s27, 0
	s_add_i32 s30, s66, s33
	global_load_lds_dwordx4 v[220:221], off
	v_lshl_add_u64 v[220:221], s[26:27], 0, v[132:133]
	s_mov_b32 m0, s30
	s_nop 0
	global_load_lds_dwordx4 v[220:221], off
	v_lshl_add_u64 v[220:221], s[26:27], 0, v[128:129]
	s_add_i32 m0, s30, 0x2000
	s_nop 0
	global_load_lds_dwordx4 v[220:221], off
	v_lshl_add_u64 v[220:221], v[224:225], 0, s[8:9]
	s_mov_b32 m0, s52
	s_nop 0
	global_load_lds_dwordx4 v[220:221], off
	v_lshl_add_u64 v[220:221], v[226:227], 0, s[8:9]
	s_mov_b32 m0, s53
	s_nop 0
	global_load_lds_dwordx4 v[220:221], off
	s_waitcnt vmcnt(8) lgkmcnt(0)
	s_barrier
	s_setprio 1
	v_mfma_f32_16x16x32_bf16 v[60:63], v[152:155], v[184:187], v[60:63]
	v_mfma_f32_16x16x32_bf16 v[60:63], v[156:159], v[188:191], v[60:63]
	v_mfma_f32_16x16x32_bf16 v[52:55], v[164:167], v[188:191], v[52:55]
	v_mfma_f32_16x16x32_bf16 v[52:55], v[160:163], v[184:187], v[52:55]
	v_mfma_f32_16x16x32_bf16 v[56:59], v[168:171], v[184:187], v[56:59]
	v_mfma_f32_16x16x32_bf16 v[56:59], v[172:175], v[188:191], v[56:59]
	v_mfma_f32_16x16x32_bf16 v[48:51], v[180:183], v[188:191], v[48:51]
	v_mfma_f32_16x16x32_bf16 v[48:51], v[176:179], v[184:187], v[48:51]
	v_mfma_f32_16x16x32_bf16 v[32:35], v[176:179], v[192:195], v[32:35]
	v_mfma_f32_16x16x32_bf16 v[32:35], v[180:183], v[196:199], v[32:35]
	v_mfma_f32_16x16x32_bf16 v[40:43], v[172:175], v[196:199], v[40:43]
	v_mfma_f32_16x16x32_bf16 v[40:43], v[168:171], v[192:195], v[40:43]
	v_mfma_f32_16x16x32_bf16 v[36:39], v[160:163], v[192:195], v[36:39]
	v_mfma_f32_16x16x32_bf16 v[36:39], v[164:167], v[196:199], v[36:39]
	v_mfma_f32_16x16x32_bf16 v[44:47], v[156:159], v[196:199], v[44:47]
	v_mfma_f32_16x16x32_bf16 v[44:47], v[152:155], v[192:195], v[44:47]
	s_setprio 0
	s_setprio 1
	v_mfma_f32_16x16x32_bf16 v[28:31], v[152:155], v[200:203], v[28:31]
	v_mfma_f32_16x16x32_bf16 v[28:31], v[156:159], v[208:211], v[28:31]
	v_mfma_f32_16x16x32_bf16 v[20:23], v[164:167], v[208:211], v[20:23]
	v_mfma_f32_16x16x32_bf16 v[20:23], v[160:163], v[200:203], v[20:23]
	v_mfma_f32_16x16x32_bf16 v[24:27], v[168:171], v[200:203], v[24:27]
	v_mfma_f32_16x16x32_bf16 v[24:27], v[172:175], v[208:211], v[24:27]
	v_mfma_f32_16x16x32_bf16 v[16:19], v[180:183], v[208:211], v[16:19]
	v_mfma_f32_16x16x32_bf16 v[16:19], v[176:179], v[200:203], v[16:19]
	v_mfma_f32_16x16x32_bf16 v[0:3], v[176:179], v[212:215], v[0:3]
	v_mfma_f32_16x16x32_bf16 v[0:3], v[180:183], v[216:219], v[0:3]
	v_mfma_f32_16x16x32_bf16 v[8:11], v[172:175], v[216:219], v[8:11]
	v_mfma_f32_16x16x32_bf16 v[8:11], v[168:171], v[212:215], v[8:11]
	v_mfma_f32_16x16x32_bf16 v[4:7], v[160:163], v[212:215], v[4:7]
	v_mfma_f32_16x16x32_bf16 v[4:7], v[164:167], v[216:219], v[4:7]
	v_mfma_f32_16x16x32_bf16 v[12:15], v[156:159], v[216:219], v[12:15]
	v_mfma_f32_16x16x32_bf16 v[12:15], v[152:155], v[212:215], v[12:15]
	s_setprio 0
	s_barrier
	s_add_u32 s24, s24, 0x100
	s_addc_u32 s25, s25, 0
	s_add_u32 s62, s62, 0x100
	s_addc_u32 s63, s63, 0
	s_cmp_ge_i32 s64, s49
	s_mov_b32 s26, s64
	s_cbranch_scc0 .LBB0_245

; #define PG8_STAGE(bufoff, gbase, voff) do { _Pragma("unroll") for (int _i = 0; _i < 2; ++_i) \
;         __builtin_amdgcn_global_load_lds((const unsigned*)((const char*)(gbase) + (voff)[_i]), (LAS unsigned*)(lds + (bufoff) + ldsw + _i * 8192), 16, 0, 0); } while (0)
; #define PG8_LDA(dst, b, h) do { _Pragma("unroll") for (int m = 0; m < 4; ++m) _Pragma("unroll") for (int k = 0; k < 2; ++k) dst[m][k] = *(const LAS bf16x8*)(lds + PG8_SA(b, h) + aoff + m * 2048 + k * 1024); } while (0)
; #define PG8_LDB(dst, b, h) do { _Pragma("unroll") for (int n = 0; n < 2; ++n) _Pragma("unroll") for (int k = 0; k < 2; ++k) dst[n][k] = *(const LAS bf16x8*)(lds + PG8_SB(b, h) + boff + n * 2048 + k * 1024); } while (0)
; #define PG8_MMA(ai, bj, At, Bt) do { __builtin_amdgcn_s_setprio(1); _Pragma("unroll") for (int m = 0; m < 4; ++m) _Pragma("unroll") for (int n = 0; n < 2; ++n) _Pragma("unroll") for (int k = 0; k < 2; ++k) \
;         acc[ai][bj][m][n] = __builtin_amdgcn_mfma_f32_16x16x32_bf16(Bt[n][k], At[m][k], acc[ai][bj][m][n], 0, 0, 0); __builtin_amdgcn_s_setprio(0); } while (0)
; #define PG8_WAIT_V(n) asm volatile("s_waitcnt vmcnt(" #n ")" ::: "memory")
; #define PG8_WAIT_L(n) asm volatile("s_waitcnt lgkmcnt(" #n ")" ::: "memory")
; #define PG8_BAR __builtin_amdgcn_s_barrier()
; #define PG8_SCHED __builtin_amdgcn_sched_barrier(0)
; template <class Epi>
; __device__ __forceinline__ void gemm_phase(LAS unsigned char* lds, const Gemm g, const StaticOrder& S, const Epi& E) {
;     ...
;             PG8_LDB(B0, 0, 0); PG8_LDB(B1, 0, 1); PG8_SCHED; PG8_LDA(At, 0, 0); PG8_STAGE(PG8_SA(1, 1), a1 + hstepA, voffA);
;             PG8_WAIT_V(8); PG8_WAIT_L(0); PG8_BAR; PG8_MMA(0, 0, At, B0); PG8_MMA(0, 1, At, B1); PG8_BAR; PG8_SCHED;
;             PG8_LDA(At, 0, 1); PG8_STAGE(PG8_SB(0, 0), b2, voffB); PG8_STAGE(PG8_SB(0, 1), b2 + hstepB, voffB); PG8_STAGE(PG8_SA(0, 0), a2, voffA);
;             PG8_WAIT_V(8); PG8_WAIT_L(0); PG8_BAR; PG8_MMA(1, 0, At, B0); PG8_MMA(1, 1, At, B1); PG8_BAR; PG8_SCHED;
.LBB0_445:
	ds_read_b128 v[148:151], v218
	ds_read_b128 v[152:155], v218 offset:1024
	ds_read_b128 v[156:159], v218 offset:2048
	ds_read_b128 v[160:163], v218 offset:3072
	ds_read_b128 v[164:167], v219
	ds_read_b128 v[168:171], v219 offset:1024
	ds_read_b128 v[172:175], v219 offset:2048
	ds_read_b128 v[176:179], v219 offset:3072
	s_add_i32 s65, s34, 2
	s_add_u32 s30, s4, 0x100
	s_addc_u32 s31, s5, 0
	s_cmp_eq_u32 s49, s34
	s_cselect_b32 s34, s26, s1
	s_cselect_b32 s37, s11, s31
	s_cselect_b32 s36, s10, s30
	s_cselect_b32 s35, s27, s64
	v_lshl_add_u64 v[216:217], s[4:5], 0, v[140:141]
	s_add_i32 m0, s41, 0xc000
	ds_read_b128 v[180:183], v220
	ds_read_b128 v[184:187], v220 offset:1024
	ds_read_b128 v[188:191], v220 offset:2048
	ds_read_b128 v[192:195], v220 offset:3072
	ds_read_b128 v[196:199], v220 offset:4096
	ds_read_b128 v[200:203], v220 offset:5120
	ds_read_b128 v[208:211], v220 offset:6144
	ds_read_b128 v[212:215], v220 offset:7168
	global_load_lds_dwordx4 v[216:217], off
	v_lshl_add_u64 v[216:217], s[4:5], 0, v[142:143]
	s_add_i32 m0, s41, 0xe000
	s_nop 0
	global_load_lds_dwordx4 v[216:217], off
	s_waitcnt vmcnt(8) lgkmcnt(0)
	s_barrier
	s_setprio 1
	v_mfma_f32_16x16x32_bf16 v[124:127], v[148:151], v[180:183], v[124:127]
	v_mfma_f32_16x16x32_bf16 v[124:127], v[152:155], v[184:187], v[124:127]
	v_mfma_f32_16x16x32_bf16 v[120:123], v[160:163], v[184:187], v[120:123]
	v_mfma_f32_16x16x32_bf16 v[120:123], v[156:159], v[180:183], v[120:123]
	v_mfma_f32_16x16x32_bf16 v[108:111], v[164:167], v[180:183], v[108:111]
	v_mfma_f32_16x16x32_bf16 v[108:111], v[168:171], v[184:187], v[108:111]
	v_mfma_f32_16x16x32_bf16 v[100:103], v[176:179], v[184:187], v[100:103]
	v_mfma_f32_16x16x32_bf16 v[100:103], v[172:175], v[180:183], v[100:103]
	v_mfma_f32_16x16x32_bf16 v[84:87], v[172:175], v[188:191], v[84:87]
	v_mfma_f32_16x16x32_bf16 v[84:87], v[176:179], v[192:195], v[84:87]
	v_mfma_f32_16x16x32_bf16 v[92:95], v[168:171], v[192:195], v[92:95]
	v_mfma_f32_16x16x32_bf16 v[92:95], v[164:167], v[188:191], v[92:95]
	v_mfma_f32_16x16x32_bf16 v[112:115], v[156:159], v[188:191], v[112:115]
	v_mfma_f32_16x16x32_bf16 v[112:115], v[160:163], v[192:195], v[112:115]
	v_mfma_f32_16x16x32_bf16 v[116:119], v[152:155], v[192:195], v[116:119]
	v_mfma_f32_16x16x32_bf16 v[116:119], v[148:151], v[188:191], v[116:119]
	s_setprio 0
	s_setprio 1
	v_mfma_f32_16x16x32_bf16 v[104:107], v[148:151], v[196:199], v[104:107]
	v_mfma_f32_16x16x32_bf16 v[104:107], v[152:155], v[200:203], v[104:107]
	v_mfma_f32_16x16x32_bf16 v[96:99], v[160:163], v[200:203], v[96:99]
	v_mfma_f32_16x16x32_bf16 v[96:99], v[156:159], v[196:199], v[96:99]
	v_mfma_f32_16x16x32_bf16 v[76:79], v[164:167], v[196:199], v[76:79]
	v_mfma_f32_16x16x32_bf16 v[76:79], v[168:171], v[200:203], v[76:79]
	v_mfma_f32_16x16x32_bf16 v[72:75], v[176:179], v[200:203], v[72:75]
	v_mfma_f32_16x16x32_bf16 v[72:75], v[172:175], v[196:199], v[72:75]
	v_mfma_f32_16x16x32_bf16 v[64:67], v[172:175], v[208:211], v[64:67]
	v_mfma_f32_16x16x32_bf16 v[64:67], v[176:179], v[212:215], v[64:67]
	v_mfma_f32_16x16x32_bf16 v[68:71], v[168:171], v[212:215], v[68:71]
	v_mfma_f32_16x16x32_bf16 v[68:71], v[164:167], v[208:211], v[68:71]
	v_mfma_f32_16x16x32_bf16 v[80:83], v[156:159], v[208:211], v[80:83]
	v_mfma_f32_16x16x32_bf16 v[80:83], v[160:163], v[212:215], v[80:83]
	v_mfma_f32_16x16x32_bf16 v[88:91], v[152:155], v[212:215], v[88:91]
	v_mfma_f32_16x16x32_bf16 v[88:91], v[148:151], v[208:211], v[88:91]
	s_setprio 0
	s_barrier
	s_add_i32 s4, s54, s40
	v_lshl_add_u64 v[216:217], s[34:35], 0, v[130:131]
	s_mov_b32 m0, s4
	ds_read_b128 v[180:183], v220 offset:16384
	ds_read_b128 v[184:187], v220 offset:17408
	ds_read_b128 v[188:191], v220 offset:18432
	ds_read_b128 v[192:195], v220 offset:19456
	ds_read_b128 v[196:199], v220 offset:20480
	ds_read_b128 v[200:203], v220 offset:21504
	ds_read_b128 v[208:211], v220 offset:22528
	ds_read_b128 v[212:215], v220 offset:23552
	global_load_lds_dwordx4 v[216:217], off
	s_add_i32 m0, s4, 0x2000
	s_add_u32 s4, s34, 0x158000
	v_lshl_add_u64 v[222:223], s[34:35], 0, v[134:135]
	s_addc_u32 s5, s35, 0
	s_add_i32 s66, s55, s40
	global_load_lds_dwordx4 v[222:223], off
	v_lshl_add_u64 v[224:225], s[4:5], 0, v[130:131]
	s_mov_b32 m0, s66
	v_lshl_add_u64 v[226:227], s[36:37], 0, v[132:133]
	global_load_lds_dwordx4 v[224:225], off
	v_lshl_add_u64 v[224:225], s[4:5], 0, v[134:135]
	s_add_i32 m0, s66, 0x2000
	s_nop 0
	global_load_lds_dwordx4 v[224:225], off
	v_lshl_add_u64 v[224:225], s[36:37], 0, v[128:129]
	s_mov_b32 m0, s41
	s_nop 0
	global_load_lds_dwordx4 v[224:225], off
	s_mov_b32 m0, s42
	s_nop 0
	global_load_lds_dwordx4 v[226:227], off
	s_waitcnt vmcnt(8) lgkmcnt(0)
	s_barrier
; #define PG8_STAGE(bufoff, gbase, voff) do { _Pragma("unroll") for (int _i = 0; _i < 2; ++_i) \
;         __builtin_amdgcn_global_load_lds((const unsigned*)((const char*)(gbase) + (voff)[_i]), (LAS unsigned*)(lds + (bufoff) + ldsw + _i * 8192), 16, 0, 0); } while (0)
; #define PG8_LDA(dst, b, h) do { _Pragma("unroll") for (int m = 0; m < 4; ++m) _Pragma("unroll") for (int k = 0; k < 2; ++k) dst[m][k] = *(const LAS bf16x8*)(lds + PG8_SA(b, h) + aoff + m * 2048 + k * 1024); } while (0)
; #define PG8_LDB(dst, b, h) do { _Pragma("unroll") for (int n = 0; n < 2; ++n) _Pragma("unroll") for (int k = 0; k < 2; ++k) dst[n][k] = *(const LAS bf16x8*)(lds + PG8_SB(b, h) + boff + n * 2048 + k * 1024); } while (0)
; #define PG8_MMA(ai, bj, At, Bt) do { __builtin_amdgcn_s_setprio(1); _Pragma("unroll") for (int m = 0; m < 4; ++m) _Pragma("unroll") for (int n = 0; n < 2; ++n) _Pragma("unroll") for (int k = 0; k < 2; ++k) \
;         acc[ai][bj][m][n] = __builtin_amdgcn_mfma_f32_16x16x32_bf16(Bt[n][k], At[m][k], acc[ai][bj][m][n], 0, 0, 0); __builtin_amdgcn_s_setprio(0); } while (0)
; #define PG8_WAIT_V(n) asm volatile("s_waitcnt vmcnt(" #n ")" ::: "memory")
; #define PG8_WAIT_L(n) asm volatile("s_waitcnt lgkmcnt(" #n ")" ::: "memory")
; #define PG8_BAR __builtin_amdgcn_s_barrier()
; #define PG8_SCHED __builtin_amdgcn_sched_barrier(0)
; template <class Epi>
; __device__ __forceinline__ void gemm_phase(LAS unsigned char* lds, const Gemm g, const StaticOrder& S, const Epi& E) {
;     ...
;             PG8_WAIT_V(8); PG8_WAIT_L(0); PG8_BAR; PG8_MMA(1, 0, At, B0); PG8_MMA(1, 1, At, B1); PG8_BAR; PG8_SCHED;
;             PG8_LDB(B0, 1, 0); PG8_LDB(B1, 1, 1); PG8_SCHED; PG8_LDA(At, 1, 0); PG8_STAGE(PG8_SA(0, 1), a2 + hstepA, voffA);
;             PG8_WAIT_V(8); PG8_WAIT_L(0); PG8_BAR; PG8_MMA(0, 0, At, B0); PG8_MMA(0, 1, At, B1); PG8_BAR; PG8_SCHED;
	s_setprio 1
	v_mfma_f32_16x16x32_bf16 v[60:63], v[148:151], v[180:183], v[60:63]
	v_mfma_f32_16x16x32_bf16 v[60:63], v[152:155], v[184:187], v[60:63]
	v_mfma_f32_16x16x32_bf16 v[56:59], v[160:163], v[184:187], v[56:59]
	v_mfma_f32_16x16x32_bf16 v[56:59], v[156:159], v[180:183], v[56:59]
	v_mfma_f32_16x16x32_bf16 v[44:47], v[164:167], v[180:183], v[44:47]
	v_mfma_f32_16x16x32_bf16 v[44:47], v[168:171], v[184:187], v[44:47]
	v_mfma_f32_16x16x32_bf16 v[36:39], v[176:179], v[184:187], v[36:39]
	v_mfma_f32_16x16x32_bf16 v[36:39], v[172:175], v[180:183], v[36:39]
	v_mfma_f32_16x16x32_bf16 v[20:23], v[172:175], v[188:191], v[20:23]
	v_mfma_f32_16x16x32_bf16 v[20:23], v[176:179], v[192:195], v[20:23]
	v_mfma_f32_16x16x32_bf16 v[28:31], v[168:171], v[192:195], v[28:31]
	v_mfma_f32_16x16x32_bf16 v[28:31], v[164:167], v[188:191], v[28:31]
	v_mfma_f32_16x16x32_bf16 v[48:51], v[156:159], v[188:191], v[48:51]
	v_mfma_f32_16x16x32_bf16 v[48:51], v[160:163], v[192:195], v[48:51]
	v_mfma_f32_16x16x32_bf16 v[52:55], v[152:155], v[192:195], v[52:55]
	v_mfma_f32_16x16x32_bf16 v[52:55], v[148:151], v[188:191], v[52:55]
	s_setprio 0
	s_setprio 1
	v_mfma_f32_16x16x32_bf16 v[40:43], v[148:151], v[196:199], v[40:43]
	v_mfma_f32_16x16x32_bf16 v[40:43], v[152:155], v[200:203], v[40:43]
	v_mfma_f32_16x16x32_bf16 v[32:35], v[160:163], v[200:203], v[32:35]
	v_mfma_f32_16x16x32_bf16 v[32:35], v[156:159], v[196:199], v[32:35]
	v_mfma_f32_16x16x32_bf16 v[12:15], v[164:167], v[196:199], v[12:15]
	v_mfma_f32_16x16x32_bf16 v[12:15], v[168:171], v[200:203], v[12:15]
	v_mfma_f32_16x16x32_bf16 v[8:11], v[176:179], v[200:203], v[8:11]
	v_mfma_f32_16x16x32_bf16 v[8:11], v[172:175], v[196:199], v[8:11]
	v_mfma_f32_16x16x32_bf16 v[0:3], v[172:175], v[208:211], v[0:3]
	v_mfma_f32_16x16x32_bf16 v[0:3], v[176:179], v[212:215], v[0:3]
	v_mfma_f32_16x16x32_bf16 v[4:7], v[168:171], v[212:215], v[4:7]
	v_mfma_f32_16x16x32_bf16 v[4:7], v[164:167], v[208:211], v[4:7]
	v_mfma_f32_16x16x32_bf16 v[16:19], v[156:159], v[208:211], v[16:19]
	v_mfma_f32_16x16x32_bf16 v[16:19], v[160:163], v[212:215], v[16:19]
	v_mfma_f32_16x16x32_bf16 v[24:27], v[152:155], v[212:215], v[24:27]
	v_mfma_f32_16x16x32_bf16 v[24:27], v[148:151], v[208:211], v[24:27]
	s_setprio 0
	s_barrier
	s_add_i32 s66, 0, 0x18000
	s_add_i32 s67, 0, 0x1c000
	v_add_u32_e32 v160, s66, v207
	v_add_u32_e32 v176, s67, v207
	ds_read_b128 v[148:151], v160
	ds_read_b128 v[152:155], v160 offset:1024
	ds_read_b128 v[156:159], v160 offset:2048
	ds_read_b128 v[160:163], v160 offset:3072
	ds_read_b128 v[164:167], v176
	ds_read_b128 v[168:171], v176 offset:1024
	ds_read_b128 v[172:175], v176 offset:2048
	ds_read_b128 v[176:179], v176 offset:3072
	s_add_u32 s4, s36, 0x158000
	s_addc_u32 s5, s37, 0
	s_mov_b32 m0, s43
	v_lshl_add_u64 v[230:231], s[4:5], 0, v[128:129]
	ds_read_b128 v[180:183], v220 offset:32768
	ds_read_b128 v[184:187], v220 offset:33792
	ds_read_b128 v[188:191], v220 offset:34816
	ds_read_b128 v[192:195], v220 offset:35840
	ds_read_b128 v[196:199], v220 offset:36864
	ds_read_b128 v[200:203], v220 offset:37888
	ds_read_b128 v[208:211], v220 offset:38912
	ds_read_b128 v[212:215], v220 offset:39936
	global_load_lds_dwordx4 v[230:231], off
	v_lshl_add_u64 v[230:231], s[4:5], 0, v[132:133]
	s_mov_b32 m0, s44
	s_nop 0
	global_load_lds_dwordx4 v[230:231], off
	s_waitcnt vmcnt(8) lgkmcnt(0)
	s_barrier
	s_setprio 1
	v_mfma_f32_16x16x32_bf16 v[124:127], v[148:151], v[180:183], v[124:127]
	v_mfma_f32_16x16x32_bf16 v[124:127], v[152:155], v[184:187], v[124:127]
	v_mfma_f32_16x16x32_bf16 v[120:123], v[160:163], v[184:187], v[120:123]
	v_mfma_f32_16x16x32_bf16 v[120:123], v[156:159], v[180:183], v[120:123]
	v_mfma_f32_16x16x32_bf16 v[108:111], v[164:167], v[180:183], v[108:111]
	v_mfma_f32_16x16x32_bf16 v[108:111], v[168:171], v[184:187], v[108:111]
	v_mfma_f32_16x16x32_bf16 v[100:103], v[176:179], v[184:187], v[100:103]
	v_mfma_f32_16x16x32_bf16 v[100:103], v[172:175], v[180:183], v[100:103]
	v_mfma_f32_16x16x32_bf16 v[84:87], v[172:175], v[188:191], v[84:87]
	v_mfma_f32_16x16x32_bf16 v[84:87], v[176:179], v[192:195], v[84:87]
	v_mfma_f32_16x16x32_bf16 v[92:95], v[168:171], v[192:195], v[92:95]
	v_mfma_f32_16x16x32_bf16 v[92:95], v[164:167], v[188:191], v[92:95]
	v_mfma_f32_16x16x32_bf16 v[112:115], v[156:159], v[188:191], v[112:115]
	v_mfma_f32_16x16x32_bf16 v[112:115], v[160:163], v[192:195], v[112:115]
	v_mfma_f32_16x16x32_bf16 v[116:119], v[152:155], v[192:195], v[116:119]
	v_mfma_f32_16x16x32_bf16 v[116:119], v[148:151], v[188:191], v[116:119]
	s_setprio 0
	s_setprio 1
	v_mfma_f32_16x16x32_bf16 v[104:107], v[148:151], v[196:199], v[104:107]
	v_mfma_f32_16x16x32_bf16 v[104:107], v[152:155], v[200:203], v[104:107]
	v_mfma_f32_16x16x32_bf16 v[96:99], v[160:163], v[200:203], v[96:99]
	v_mfma_f32_16x16x32_bf16 v[96:99], v[156:159], v[196:199], v[96:99]
	v_mfma_f32_16x16x32_bf16 v[76:79], v[164:167], v[196:199], v[76:79]
	v_mfma_f32_16x16x32_bf16 v[76:79], v[168:171], v[200:203], v[76:79]
	v_mfma_f32_16x16x32_bf16 v[72:75], v[176:179], v[200:203], v[72:75]
	v_mfma_f32_16x16x32_bf16 v[72:75], v[172:175], v[196:199], v[72:75]
	v_mfma_f32_16x16x32_bf16 v[64:67], v[172:175], v[208:211], v[64:67]
	v_mfma_f32_16x16x32_bf16 v[64:67], v[176:179], v[212:215], v[64:67]
	v_mfma_f32_16x16x32_bf16 v[68:71], v[168:171], v[212:215], v[68:71]
	v_mfma_f32_16x16x32_bf16 v[68:71], v[164:167], v[208:211], v[68:71]
	v_mfma_f32_16x16x32_bf16 v[80:83], v[156:159], v[208:211], v[80:83]
	v_mfma_f32_16x16x32_bf16 v[80:83], v[160:163], v[212:215], v[80:83]
	v_mfma_f32_16x16x32_bf16 v[88:91], v[152:155], v[212:215], v[88:91]
	v_mfma_f32_16x16x32_bf16 v[88:91], v[148:151], v[208:211], v[88:91]
	s_setprio 0
	s_barrier
; #define PG8_STAGE(bufoff, gbase, voff) do { _Pragma("unroll") for (int _i = 0; _i < 2; ++_i) \
;         __builtin_amdgcn_global_load_lds((const unsigned*)((const char*)(gbase) + (voff)[_i]), (LAS unsigned*)(lds + (bufoff) + ldsw + _i * 8192), 16, 0, 0); } while (0)
; #define PG8_LDA(dst, b, h) do { _Pragma("unroll") for (int m = 0; m < 4; ++m) _Pragma("unroll") for (int k = 0; k < 2; ++k) dst[m][k] = *(const LAS bf16x8*)(lds + PG8_SA(b, h) + aoff + m * 2048 + k * 1024); } while (0)
; #define PG8_MMA(ai, bj, At, Bt) do { __builtin_amdgcn_s_setprio(1); _Pragma("unroll") for (int m = 0; m < 4; ++m) _Pragma("unroll") for (int n = 0; n < 2; ++n) _Pragma("unroll") for (int k = 0; k < 2; ++k) \
;         acc[ai][bj][m][n] = __builtin_amdgcn_mfma_f32_16x16x32_bf16(Bt[n][k], At[m][k], acc[ai][bj][m][n], 0, 0, 0); __builtin_amdgcn_s_setprio(0); } while (0)
; #define PG8_WAIT_V(n) asm volatile("s_waitcnt vmcnt(" #n ")" ::: "memory")
; #define PG8_WAIT_L(n) asm volatile("s_waitcnt lgkmcnt(" #n ")" ::: "memory")
; #define PG8_BAR __builtin_amdgcn_s_barrier()
; #define PG8_SCHED __builtin_amdgcn_sched_barrier(0)
; template <class Epi>
; __device__ __forceinline__ void gemm_phase(LAS unsigned char* lds, const Gemm g, const StaticOrder& S, const Epi& E) {
;     ...
;             PG8_LDA(At, 1, 1); PG8_STAGE(PG8_SB(1, 0), b3, voffB); PG8_STAGE(PG8_SB(1, 1), b3 + hstepB, voffB); PG8_STAGE(PG8_SA(1, 0), a3, voffA);
;             PG8_WAIT_V(8); PG8_WAIT_L(0); PG8_BAR; PG8_MMA(1, 0, At, B0); PG8_MMA(1, 1, At, B1); PG8_BAR; PG8_SCHED;
	s_add_i32 s4, s66, s40
	v_lshl_add_u64 v[216:217], v[216:217], 0, s[16:17]
	s_mov_b32 m0, s4
	ds_read_b128 v[180:183], v220 offset:49152
	ds_read_b128 v[184:187], v220 offset:50176
	ds_read_b128 v[188:191], v220 offset:51200
	ds_read_b128 v[192:195], v220 offset:52224
	ds_read_b128 v[196:199], v220 offset:53248
	ds_read_b128 v[200:203], v220 offset:54272
	ds_read_b128 v[208:211], v220 offset:55296
	ds_read_b128 v[212:215], v220 offset:56320
	global_load_lds_dwordx4 v[216:217], off
	s_add_i32 m0, s4, 0x2000
	s_add_u32 s4, s34, 0x158080
	v_lshl_add_u64 v[216:217], v[222:223], 0, s[16:17]
	s_addc_u32 s5, s35, 0
	s_add_i32 s34, s67, s40
	global_load_lds_dwordx4 v[216:217], off
	v_lshl_add_u64 v[216:217], s[4:5], 0, v[130:131]
	s_mov_b32 m0, s34
	s_nop 0
	global_load_lds_dwordx4 v[216:217], off
	v_lshl_add_u64 v[216:217], s[4:5], 0, v[134:135]
	s_add_i32 m0, s34, 0x2000
	s_nop 0
	global_load_lds_dwordx4 v[216:217], off
	v_lshl_add_u64 v[216:217], v[224:225], 0, s[16:17]
	s_mov_b32 m0, s47
	s_nop 0
	global_load_lds_dwordx4 v[216:217], off
	v_lshl_add_u64 v[216:217], v[226:227], 0, s[16:17]
	s_mov_b32 m0, s48
	s_nop 0
	global_load_lds_dwordx4 v[216:217], off
	s_waitcnt vmcnt(8) lgkmcnt(0)
	s_barrier
	s_setprio 1
	v_mfma_f32_16x16x32_bf16 v[60:63], v[148:151], v[180:183], v[60:63]
	v_mfma_f32_16x16x32_bf16 v[60:63], v[152:155], v[184:187], v[60:63]
	v_mfma_f32_16x16x32_bf16 v[56:59], v[160:163], v[184:187], v[56:59]
	v_mfma_f32_16x16x32_bf16 v[56:59], v[156:159], v[180:183], v[56:59]
	v_mfma_f32_16x16x32_bf16 v[44:47], v[164:167], v[180:183], v[44:47]
	v_mfma_f32_16x16x32_bf16 v[44:47], v[168:171], v[184:187], v[44:47]
	v_mfma_f32_16x16x32_bf16 v[36:39], v[176:179], v[184:187], v[36:39]
	v_mfma_f32_16x16x32_bf16 v[36:39], v[172:175], v[180:183], v[36:39]
	v_mfma_f32_16x16x32_bf16 v[20:23], v[172:175], v[188:191], v[20:23]
	v_mfma_f32_16x16x32_bf16 v[20:23], v[176:179], v[192:195], v[20:23]
	v_mfma_f32_16x16x32_bf16 v[28:31], v[168:171], v[192:195], v[28:31]
	v_mfma_f32_16x16x32_bf16 v[28:31], v[164:167], v[188:191], v[28:31]
	v_mfma_f32_16x16x32_bf16 v[48:51], v[156:159], v[188:191], v[48:51]
	v_mfma_f32_16x16x32_bf16 v[48:51], v[160:163], v[192:195], v[48:51]
	v_mfma_f32_16x16x32_bf16 v[52:55], v[152:155], v[192:195], v[52:55]
	v_mfma_f32_16x16x32_bf16 v[52:55], v[148:151], v[188:191], v[52:55]
	s_setprio 0
	s_setprio 1
	v_mfma_f32_16x16x32_bf16 v[40:43], v[148:151], v[196:199], v[40:43]
	v_mfma_f32_16x16x32_bf16 v[40:43], v[152:155], v[200:203], v[40:43]
	v_mfma_f32_16x16x32_bf16 v[32:35], v[160:163], v[200:203], v[32:35]
	v_mfma_f32_16x16x32_bf16 v[32:35], v[156:159], v[196:199], v[32:35]
	v_mfma_f32_16x16x32_bf16 v[12:15], v[164:167], v[196:199], v[12:15]
	v_mfma_f32_16x16x32_bf16 v[12:15], v[168:171], v[200:203], v[12:15]
	v_mfma_f32_16x16x32_bf16 v[8:11], v[176:179], v[200:203], v[8:11]
	v_mfma_f32_16x16x32_bf16 v[8:11], v[172:175], v[196:199], v[8:11]
	v_mfma_f32_16x16x32_bf16 v[0:3], v[172:175], v[208:211], v[0:3]
	v_mfma_f32_16x16x32_bf16 v[0:3], v[176:179], v[212:215], v[0:3]
	v_mfma_f32_16x16x32_bf16 v[4:7], v[168:171], v[212:215], v[4:7]
	v_mfma_f32_16x16x32_bf16 v[4:7], v[164:167], v[208:211], v[4:7]
	v_mfma_f32_16x16x32_bf16 v[16:19], v[156:159], v[208:211], v[16:19]
	v_mfma_f32_16x16x32_bf16 v[16:19], v[160:163], v[212:215], v[16:19]
	v_mfma_f32_16x16x32_bf16 v[24:27], v[152:155], v[212:215], v[24:27]
	v_mfma_f32_16x16x32_bf16 v[24:27], v[148:151], v[208:211], v[24:27]
	s_setprio 0
	s_barrier
	s_add_u32 s1, s1, 0x100
	s_addc_u32 s64, s64, 0
	s_cmp_ge_i32 s65, s46
	s_mov_b64 s[4:5], s[30:31]
	s_mov_b32 s34, s65
	s_cbranch_scc0 .LBB0_445
	v_pk_mul_f32 v[164:165], v[126:127], 0.5 op_sel_hi:[1,0]
	v_pk_mul_f32 v[200:201], v[124:125], 0.5 op_sel_hi:[1,0]
	v_pk_mul_f32 v[202:203], v[122:123], 0.5 op_sel_hi:[1,0]
	v_pk_mul_f32 v[208:209], v[120:121], 0.5 op_sel_hi:[1,0]
	v_pk_mul_f32 v[210:211], v[110:111], 0.5 op_sel_hi:[1,0]
	v_pk_mul_f32 v[212:213], v[108:109], 0.5 op_sel_hi:[1,0]
	v_pk_mul_f32 v[214:215], v[102:103], 0.5 op_sel_hi:[1,0]
	v_pk_mul_f32 v[216:217], v[100:101], 0.5 op_sel_hi:[1,0]
	v_pk_mul_f32 v[188:189], v[118:119], 0.5 op_sel_hi:[1,0]
	v_pk_mul_f32 v[186:187], v[116:117], 0.5 op_sel_hi:[1,0]
	v_pk_mul_f32 v[184:185], v[114:115], 0.5 op_sel_hi:[1,0]
	v_pk_mul_f32 v[182:183], v[112:113], 0.5 op_sel_hi:[1,0]
	v_pk_mul_f32 v[196:197], v[94:95], 0.5 op_sel_hi:[1,0]
	v_pk_mul_f32 v[194:195], v[92:93], 0.5 op_sel_hi:[1,0]
	v_pk_mul_f32 v[192:193], v[86:87], 0.5 op_sel_hi:[1,0]
	v_pk_mul_f32 v[190:191], v[84:85], 0.5 op_sel_hi:[1,0]
	v_pk_mul_f32 v[166:167], v[106:107], 0.5 op_sel_hi:[1,0]
	v_pk_mul_f32 v[168:169], v[104:105], 0.5 op_sel_hi:[1,0]
	v_pk_mul_f32 v[170:171], v[98:99], 0.5 op_sel_hi:[1,0]
	v_pk_mul_f32 v[172:173], v[96:97], 0.5 op_sel_hi:[1,0]
	v_pk_mul_f32 v[174:175], v[78:79], 0.5 op_sel_hi:[1,0]
	v_pk_mul_f32 v[176:177], v[76:77], 0.5 op_sel_hi:[1,0]
	v_pk_mul_f32 v[178:179], v[74:75], 0.5 op_sel_hi:[1,0]
	v_pk_mul_f32 v[180:181], v[72:73], 0.5 op_sel_hi:[1,0]
	v_pk_mul_f32 v[154:155], v[90:91], 0.5 op_sel_hi:[1,0]
	v_pk_mul_f32 v[152:153], v[88:89], 0.5 op_sel_hi:[1,0]
	v_pk_mul_f32 v[150:151], v[82:83], 0.5 op_sel_hi:[1,0]
	v_pk_mul_f32 v[148:149], v[80:81], 0.5 op_sel_hi:[1,0]
	v_pk_mul_f32 v[162:163], v[70:71], 0.5 op_sel_hi:[1,0]
	v_pk_mul_f32 v[160:161], v[68:69], 0.5 op_sel_hi:[1,0]
	v_pk_mul_f32 v[158:159], v[66:67], 0.5 op_sel_hi:[1,0]
	v_pk_mul_f32 v[156:157], v[64:65], 0.5 op_sel_hi:[1,0]
	v_pk_mul_f32 v[112:113], v[62:63], 0.5 op_sel_hi:[1,0]
	v_pk_mul_f32 v[114:115], v[60:61], 0.5 op_sel_hi:[1,0]
	v_pk_mul_f32 v[116:117], v[58:59], 0.5 op_sel_hi:[1,0]
	v_pk_mul_f32 v[118:119], v[56:57], 0.5 op_sel_hi:[1,0]
	v_pk_mul_f32 v[120:121], v[46:47], 0.5 op_sel_hi:[1,0]
	v_pk_mul_f32 v[122:123], v[44:45], 0.5 op_sel_hi:[1,0]
	v_pk_mul_f32 v[124:125], v[38:39], 0.5 op_sel_hi:[1,0]
	v_pk_mul_f32 v[126:127], v[36:37], 0.5 op_sel_hi:[1,0]
	v_pk_mul_f32 v[102:103], v[54:55], 0.5 op_sel_hi:[1,0]
	v_pk_mul_f32 v[100:101], v[52:53], 0.5 op_sel_hi:[1,0]
	v_pk_mul_f32 v[98:99], v[50:51], 0.5 op_sel_hi:[1,0]
	v_pk_mul_f32 v[96:97], v[48:49], 0.5 op_sel_hi:[1,0]
	v_pk_mul_f32 v[110:111], v[30:31], 0.5 op_sel_hi:[1,0]
	v_pk_mul_f32 v[108:109], v[28:29], 0.5 op_sel_hi:[1,0]
	v_pk_mul_f32 v[106:107], v[22:23], 0.5 op_sel_hi:[1,0]
	v_pk_mul_f32 v[104:105], v[20:21], 0.5 op_sel_hi:[1,0]
	v_pk_mul_f32 v[86:87], v[42:43], 0.5 op_sel_hi:[1,0]
	v_pk_mul_f32 v[84:85], v[40:41], 0.5 op_sel_hi:[1,0]
	v_pk_mul_f32 v[82:83], v[34:35], 0.5 op_sel_hi:[1,0]
	v_pk_mul_f32 v[80:81], v[32:33], 0.5 op_sel_hi:[1,0]
	v_pk_mul_f32 v[94:95], v[14:15], 0.5 op_sel_hi:[1,0]
	v_pk_mul_f32 v[92:93], v[12:13], 0.5 op_sel_hi:[1,0]
	v_pk_mul_f32 v[90:91], v[10:11], 0.5 op_sel_hi:[1,0]
	v_pk_mul_f32 v[88:89], v[8:9], 0.5 op_sel_hi:[1,0]
	v_pk_mul_f32 v[70:71], v[26:27], 0.5 op_sel_hi:[1,0]
	v_pk_mul_f32 v[68:69], v[24:25], 0.5 op_sel_hi:[1,0]
	v_pk_mul_f32 v[66:67], v[18:19], 0.5 op_sel_hi:[1,0]
	v_pk_mul_f32 v[64:65], v[16:17], 0.5 op_sel_hi:[1,0]
	v_pk_mul_f32 v[78:79], v[6:7], 0.5 op_sel_hi:[1,0]
	v_pk_mul_f32 v[76:77], v[4:5], 0.5 op_sel_hi:[1,0]
	v_pk_mul_f32 v[74:75], v[2:3], 0.5 op_sel_hi:[1,0]
	v_pk_mul_f32 v[72:73], v[0:1], 0.5 op_sel_hi:[1,0]

; #define PG8_STAGE(bufoff, gbase, voff) do { _Pragma("unroll") for (int _i = 0; _i < 2; ++_i) \
;         __builtin_amdgcn_global_load_lds((const unsigned*)((const char*)(gbase) + (voff)[_i]), (LAS unsigned*)(lds + (bufoff) + ldsw + _i * 8192), 16, 0, 0); } while (0)
; #define PG8_LDA(dst, b, h) do { _Pragma("unroll") for (int m = 0; m < 4; ++m) _Pragma("unroll") for (int k = 0; k < 2; ++k) dst[m][k] = *(const LAS bf16x8*)(lds + PG8_SA(b, h) + aoff + m * 2048 + k * 1024); } while (0)
; #define PG8_LDB(dst, b, h) do { _Pragma("unroll") for (int n = 0; n < 2; ++n) _Pragma("unroll") for (int k = 0; k < 2; ++k) dst[n][k] = *(const LAS bf16x8*)(lds + PG8_SB(b, h) + boff + n * 2048 + k * 1024); } while (0)
; #define PG8_MMA(ai, bj, At, Bt) do { __builtin_amdgcn_s_setprio(1); _Pragma("unroll") for (int m = 0; m < 4; ++m) _Pragma("unroll") for (int n = 0; n < 2; ++n) _Pragma("unroll") for (int k = 0; k < 2; ++k) \
;         acc[ai][bj][m][n] = __builtin_amdgcn_mfma_f32_16x16x32_bf16(Bt[n][k], At[m][k], acc[ai][bj][m][n], 0, 0, 0); __builtin_amdgcn_s_setprio(0); } while (0)
; #define PG8_WAIT_V(n) asm volatile("s_waitcnt vmcnt(" #n ")" ::: "memory")
; #define PG8_WAIT_L(n) asm volatile("s_waitcnt lgkmcnt(" #n ")" ::: "memory")
; #define PG8_BAR __builtin_amdgcn_s_barrier()
; #define PG8_SCHED __builtin_amdgcn_sched_barrier(0)
; template <class Epi>
; __device__ __forceinline__ void gemm_phase(LAS unsigned char* lds, const Gemm g, const StaticOrder& S, const Epi& E) {
;     ...
;             PG8_LDB(B0, 0, 0); PG8_LDB(B1, 0, 1); PG8_SCHED; PG8_LDA(At, 0, 0); PG8_STAGE(PG8_SA(1, 1), a1 + hstepA, voffA);
;             PG8_WAIT_V(8); PG8_WAIT_L(0); PG8_BAR; PG8_MMA(0, 0, At, B0); PG8_MMA(0, 1, At, B1); PG8_BAR; PG8_SCHED;
;             PG8_LDA(At, 0, 1); PG8_STAGE(PG8_SB(0, 0), b2, voffB); PG8_STAGE(PG8_SB(0, 1), b2 + hstepB, voffB); PG8_STAGE(PG8_SA(0, 0), a2, voffA);
;             PG8_WAIT_V(8); PG8_WAIT_L(0); PG8_BAR; PG8_MMA(1, 0, At, B0); PG8_MMA(1, 1, At, B1); PG8_BAR; PG8_SCHED;
.LBB0_541:
	ds_read_b128 v[148:151], v155
	ds_read_b128 v[160:163], v155 offset:1024
	ds_read_b128 v[164:167], v155 offset:2048
	ds_read_b128 v[168:171], v155 offset:3072
	ds_read_b128 v[172:175], v156
	ds_read_b128 v[176:179], v156 offset:1024
	ds_read_b128 v[180:183], v156 offset:2048
	ds_read_b128 v[184:187], v156 offset:3072
	s_add_i32 s35, s26, 2
	s_add_u32 s27, s8, 0xfff80080
	s_addc_u32 s30, s9, -1
	s_cmp_eq_u32 s49, s26
	s_cselect_b32 s26, s21, s33
	s_cselect_b32 s31, s1, s30
	s_cselect_b32 s30, s5, s27
	s_cselect_b32 s27, s19, s34
	v_lshl_add_u64 v[224:225], s[8:9], 0, v[140:141]
	s_add_i32 m0, s39, 0xc000
	ds_read_b128 v[188:191], v157
	ds_read_b128 v[192:195], v157 offset:1024
	ds_read_b128 v[196:199], v157 offset:2048
	ds_read_b128 v[200:203], v157 offset:3072
	ds_read_b128 v[208:211], v157 offset:4096
	ds_read_b128 v[212:215], v157 offset:5120
	ds_read_b128 v[216:219], v157 offset:6144
	ds_read_b128 v[220:223], v157 offset:7168
	global_load_lds_dwordx4 v[224:225], off
	v_lshl_add_u64 v[224:225], s[8:9], 0, v[142:143]
	s_add_i32 m0, s39, 0xe000
	s_nop 0
	global_load_lds_dwordx4 v[224:225], off
	s_waitcnt vmcnt(8) lgkmcnt(0)
	s_barrier
	s_setprio 1
	v_mfma_f32_16x16x32_bf16 v[120:123], v[148:151], v[188:191], v[120:123]
	v_mfma_f32_16x16x32_bf16 v[120:123], v[160:163], v[192:195], v[120:123]
	v_mfma_f32_16x16x32_bf16 v[124:127], v[168:171], v[192:195], v[124:127]
	v_mfma_f32_16x16x32_bf16 v[124:127], v[164:167], v[188:191], v[124:127]
	v_mfma_f32_16x16x32_bf16 v[116:119], v[172:175], v[188:191], v[116:119]
	v_mfma_f32_16x16x32_bf16 v[116:119], v[176:179], v[192:195], v[116:119]
	v_mfma_f32_16x16x32_bf16 v[112:115], v[184:187], v[192:195], v[112:115]
	v_mfma_f32_16x16x32_bf16 v[112:115], v[180:183], v[188:191], v[112:115]
	v_mfma_f32_16x16x32_bf16 v[96:99], v[180:183], v[196:199], v[96:99]
	v_mfma_f32_16x16x32_bf16 v[96:99], v[184:187], v[200:203], v[96:99]
	v_mfma_f32_16x16x32_bf16 v[100:103], v[176:179], v[200:203], v[100:103]
	v_mfma_f32_16x16x32_bf16 v[100:103], v[172:175], v[196:199], v[100:103]
	v_mfma_f32_16x16x32_bf16 v[104:107], v[164:167], v[196:199], v[104:107]
	v_mfma_f32_16x16x32_bf16 v[104:107], v[168:171], v[200:203], v[104:107]
	v_mfma_f32_16x16x32_bf16 v[108:111], v[160:163], v[200:203], v[108:111]
	v_mfma_f32_16x16x32_bf16 v[108:111], v[148:151], v[196:199], v[108:111]
	s_setprio 0
	s_setprio 1
	v_mfma_f32_16x16x32_bf16 v[92:95], v[148:151], v[208:211], v[92:95]
	v_mfma_f32_16x16x32_bf16 v[92:95], v[160:163], v[212:215], v[92:95]
	v_mfma_f32_16x16x32_bf16 v[88:91], v[168:171], v[212:215], v[88:91]
	v_mfma_f32_16x16x32_bf16 v[88:91], v[164:167], v[208:211], v[88:91]
	v_mfma_f32_16x16x32_bf16 v[84:87], v[172:175], v[208:211], v[84:87]
	v_mfma_f32_16x16x32_bf16 v[84:87], v[176:179], v[212:215], v[84:87]
	v_mfma_f32_16x16x32_bf16 v[80:83], v[184:187], v[212:215], v[80:83]
	v_mfma_f32_16x16x32_bf16 v[80:83], v[180:183], v[208:211], v[80:83]
	v_mfma_f32_16x16x32_bf16 v[64:67], v[180:183], v[216:219], v[64:67]
	v_mfma_f32_16x16x32_bf16 v[64:67], v[184:187], v[220:223], v[64:67]
	v_mfma_f32_16x16x32_bf16 v[68:71], v[176:179], v[220:223], v[68:71]
	v_mfma_f32_16x16x32_bf16 v[68:71], v[172:175], v[216:219], v[68:71]
	v_mfma_f32_16x16x32_bf16 v[72:75], v[164:167], v[216:219], v[72:75]
	v_mfma_f32_16x16x32_bf16 v[72:75], v[168:171], v[220:223], v[72:75]
	v_mfma_f32_16x16x32_bf16 v[76:79], v[160:163], v[220:223], v[76:79]
	v_mfma_f32_16x16x32_bf16 v[76:79], v[148:151], v[216:219], v[76:79]
	s_setprio 0
	s_barrier
	s_add_i32 s58, s54, s38
	v_lshl_add_u64 v[224:225], s[26:27], 0, v[130:131]
	s_mov_b32 m0, s58
	ds_read_b128 v[188:191], v157 offset:16384
	ds_read_b128 v[192:195], v157 offset:17408
	ds_read_b128 v[196:199], v157 offset:18432
	ds_read_b128 v[200:203], v157 offset:19456
	ds_read_b128 v[208:211], v157 offset:20480
	ds_read_b128 v[212:215], v157 offset:21504
	ds_read_b128 v[216:219], v157 offset:22528
	ds_read_b128 v[220:223], v157 offset:23552
	global_load_lds_dwordx4 v[224:225], off
	s_add_i32 m0, s58, 0x2000
	s_add_u32 s58, s26, 0x80000
	v_lshl_add_u64 v[226:227], s[26:27], 0, v[134:135]
	s_addc_u32 s59, s27, 0
	s_add_i32 s60, s55, s38
	global_load_lds_dwordx4 v[226:227], off
	v_lshl_add_u64 v[230:231], s[58:59], 0, v[130:131]
	s_mov_b32 m0, s60
	v_lshl_add_u64 v[232:233], s[30:31], 0, v[132:133]
	global_load_lds_dwordx4 v[230:231], off
	v_lshl_add_u64 v[230:231], s[58:59], 0, v[134:135]
	s_add_i32 m0, s60, 0x2000
	s_nop 0
	global_load_lds_dwordx4 v[230:231], off
	v_lshl_add_u64 v[230:231], s[30:31], 0, v[128:129]
	s_mov_b32 m0, s39
	s_nop 0
	global_load_lds_dwordx4 v[230:231], off
	s_mov_b32 m0, s40
	s_nop 0
	global_load_lds_dwordx4 v[232:233], off
	s_waitcnt vmcnt(8) lgkmcnt(0)
	s_barrier
; #define PG8_STAGE(bufoff, gbase, voff) do { _Pragma("unroll") for (int _i = 0; _i < 2; ++_i) \
;         __builtin_amdgcn_global_load_lds((const unsigned*)((const char*)(gbase) + (voff)[_i]), (LAS unsigned*)(lds + (bufoff) + ldsw + _i * 8192), 16, 0, 0); } while (0)
; #define PG8_LDA(dst, b, h) do { _Pragma("unroll") for (int m = 0; m < 4; ++m) _Pragma("unroll") for (int k = 0; k < 2; ++k) dst[m][k] = *(const LAS bf16x8*)(lds + PG8_SA(b, h) + aoff + m * 2048 + k * 1024); } while (0)
; #define PG8_LDB(dst, b, h) do { _Pragma("unroll") for (int n = 0; n < 2; ++n) _Pragma("unroll") for (int k = 0; k < 2; ++k) dst[n][k] = *(const LAS bf16x8*)(lds + PG8_SB(b, h) + boff + n * 2048 + k * 1024); } while (0)
; #define PG8_MMA(ai, bj, At, Bt) do { __builtin_amdgcn_s_setprio(1); _Pragma("unroll") for (int m = 0; m < 4; ++m) _Pragma("unroll") for (int n = 0; n < 2; ++n) _Pragma("unroll") for (int k = 0; k < 2; ++k) \
;         acc[ai][bj][m][n] = __builtin_amdgcn_mfma_f32_16x16x32_bf16(Bt[n][k], At[m][k], acc[ai][bj][m][n], 0, 0, 0); __builtin_amdgcn_s_setprio(0); } while (0)
; #define PG8_WAIT_V(n) asm volatile("s_waitcnt vmcnt(" #n ")" ::: "memory")
; #define PG8_WAIT_L(n) asm volatile("s_waitcnt lgkmcnt(" #n ")" ::: "memory")
; #define PG8_BAR __builtin_amdgcn_s_barrier()
; #define PG8_SCHED __builtin_amdgcn_sched_barrier(0)
; template <class Epi>
; __device__ __forceinline__ void gemm_phase(LAS unsigned char* lds, const Gemm g, const StaticOrder& S, const Epi& E) {
;     ...
;             PG8_WAIT_V(8); PG8_WAIT_L(0); PG8_BAR; PG8_MMA(1, 0, At, B0); PG8_MMA(1, 1, At, B1); PG8_BAR; PG8_SCHED;
;             PG8_LDB(B0, 1, 0); PG8_LDB(B1, 1, 1); PG8_SCHED; PG8_LDA(At, 1, 0); PG8_STAGE(PG8_SA(0, 1), a2 + hstepA, voffA);
;             PG8_WAIT_V(8); PG8_WAIT_L(0); PG8_BAR; PG8_MMA(0, 0, At, B0); PG8_MMA(0, 1, At, B1); PG8_BAR; PG8_SCHED;
	s_setprio 1
	v_mfma_f32_16x16x32_bf16 v[60:63], v[148:151], v[188:191], v[60:63]
	v_mfma_f32_16x16x32_bf16 v[60:63], v[160:163], v[192:195], v[60:63]
	v_mfma_f32_16x16x32_bf16 v[56:59], v[168:171], v[192:195], v[56:59]
	v_mfma_f32_16x16x32_bf16 v[56:59], v[164:167], v[188:191], v[56:59]
	v_mfma_f32_16x16x32_bf16 v[52:55], v[172:175], v[188:191], v[52:55]
	v_mfma_f32_16x16x32_bf16 v[52:55], v[176:179], v[192:195], v[52:55]
	v_mfma_f32_16x16x32_bf16 v[48:51], v[184:187], v[192:195], v[48:51]
	v_mfma_f32_16x16x32_bf16 v[48:51], v[180:183], v[188:191], v[48:51]
	v_mfma_f32_16x16x32_bf16 v[32:35], v[180:183], v[196:199], v[32:35]
	v_mfma_f32_16x16x32_bf16 v[32:35], v[184:187], v[200:203], v[32:35]
	v_mfma_f32_16x16x32_bf16 v[36:39], v[176:179], v[200:203], v[36:39]
	v_mfma_f32_16x16x32_bf16 v[36:39], v[172:175], v[196:199], v[36:39]
	v_mfma_f32_16x16x32_bf16 v[40:43], v[164:167], v[196:199], v[40:43]
	v_mfma_f32_16x16x32_bf16 v[40:43], v[168:171], v[200:203], v[40:43]
	v_mfma_f32_16x16x32_bf16 v[44:47], v[160:163], v[200:203], v[44:47]
	v_mfma_f32_16x16x32_bf16 v[44:47], v[148:151], v[196:199], v[44:47]
	s_setprio 0
	s_setprio 1
	v_mfma_f32_16x16x32_bf16 v[28:31], v[148:151], v[208:211], v[28:31]
	v_mfma_f32_16x16x32_bf16 v[28:31], v[160:163], v[212:215], v[28:31]
	v_mfma_f32_16x16x32_bf16 v[24:27], v[168:171], v[212:215], v[24:27]
	v_mfma_f32_16x16x32_bf16 v[24:27], v[164:167], v[208:211], v[24:27]
	v_mfma_f32_16x16x32_bf16 v[20:23], v[172:175], v[208:211], v[20:23]
	v_mfma_f32_16x16x32_bf16 v[20:23], v[176:179], v[212:215], v[20:23]
	v_mfma_f32_16x16x32_bf16 v[16:19], v[184:187], v[212:215], v[16:19]
	v_mfma_f32_16x16x32_bf16 v[16:19], v[180:183], v[208:211], v[16:19]
	v_mfma_f32_16x16x32_bf16 v[0:3], v[180:183], v[216:219], v[0:3]
	v_mfma_f32_16x16x32_bf16 v[0:3], v[184:187], v[220:223], v[0:3]
	v_mfma_f32_16x16x32_bf16 v[4:7], v[176:179], v[220:223], v[4:7]
	v_mfma_f32_16x16x32_bf16 v[4:7], v[172:175], v[216:219], v[4:7]
	v_mfma_f32_16x16x32_bf16 v[8:11], v[164:167], v[216:219], v[8:11]
	v_mfma_f32_16x16x32_bf16 v[8:11], v[168:171], v[220:223], v[8:11]
	v_mfma_f32_16x16x32_bf16 v[12:15], v[160:163], v[220:223], v[12:15]
	v_mfma_f32_16x16x32_bf16 v[12:15], v[148:151], v[216:219], v[12:15]
	s_setprio 0
	s_barrier
	s_add_i32 s58, 0, 0x18000
	v_add_u32_e32 v136, s58, v154
	s_add_i32 s59, 0, 0x1c000
	ds_read_b128 v[148:151], v136
	ds_read_b128 v[160:163], v136 offset:1024
	ds_read_b128 v[164:167], v136 offset:2048
	ds_read_b128 v[168:171], v136 offset:3072
	v_add_u32_e32 v136, s59, v154
	ds_read_b128 v[172:175], v136
	ds_read_b128 v[176:179], v136 offset:1024
	ds_read_b128 v[180:183], v136 offset:2048
	ds_read_b128 v[184:187], v136 offset:3072
	s_add_u32 s30, s30, 0x80000
	s_addc_u32 s31, s31, 0
	s_mov_b32 m0, s41
	v_lshl_add_u64 v[234:235], s[30:31], 0, v[128:129]
	ds_read_b128 v[188:191], v157 offset:32768
	ds_read_b128 v[192:195], v157 offset:33792
	ds_read_b128 v[196:199], v157 offset:34816
	ds_read_b128 v[200:203], v157 offset:35840
	ds_read_b128 v[208:211], v157 offset:36864
	ds_read_b128 v[212:215], v157 offset:37888
	ds_read_b128 v[216:219], v157 offset:38912
	ds_read_b128 v[220:223], v157 offset:39936
	global_load_lds_dwordx4 v[234:235], off
	v_lshl_add_u64 v[234:235], s[30:31], 0, v[132:133]
	s_mov_b32 m0, s42
	s_nop 0
	global_load_lds_dwordx4 v[234:235], off
	s_waitcnt vmcnt(8) lgkmcnt(0)
	s_barrier
	s_setprio 1
	v_mfma_f32_16x16x32_bf16 v[120:123], v[148:151], v[188:191], v[120:123]
	v_mfma_f32_16x16x32_bf16 v[120:123], v[160:163], v[192:195], v[120:123]
	v_mfma_f32_16x16x32_bf16 v[124:127], v[168:171], v[192:195], v[124:127]
	v_mfma_f32_16x16x32_bf16 v[124:127], v[164:167], v[188:191], v[124:127]
	v_mfma_f32_16x16x32_bf16 v[116:119], v[172:175], v[188:191], v[116:119]
	v_mfma_f32_16x16x32_bf16 v[116:119], v[176:179], v[192:195], v[116:119]
	v_mfma_f32_16x16x32_bf16 v[112:115], v[184:187], v[192:195], v[112:115]
	v_mfma_f32_16x16x32_bf16 v[112:115], v[180:183], v[188:191], v[112:115]
	v_mfma_f32_16x16x32_bf16 v[96:99], v[180:183], v[196:199], v[96:99]
	v_mfma_f32_16x16x32_bf16 v[96:99], v[184:187], v[200:203], v[96:99]
	v_mfma_f32_16x16x32_bf16 v[100:103], v[176:179], v[200:203], v[100:103]
	v_mfma_f32_16x16x32_bf16 v[100:103], v[172:175], v[196:199], v[100:103]
	v_mfma_f32_16x16x32_bf16 v[104:107], v[164:167], v[196:199], v[104:107]
	v_mfma_f32_16x16x32_bf16 v[104:107], v[168:171], v[200:203], v[104:107]
	v_mfma_f32_16x16x32_bf16 v[108:111], v[160:163], v[200:203], v[108:111]
	v_mfma_f32_16x16x32_bf16 v[108:111], v[148:151], v[196:199], v[108:111]
	s_setprio 0
	s_setprio 1
	v_mfma_f32_16x16x32_bf16 v[92:95], v[148:151], v[208:211], v[92:95]
	v_mfma_f32_16x16x32_bf16 v[92:95], v[160:163], v[212:215], v[92:95]
	v_mfma_f32_16x16x32_bf16 v[88:91], v[168:171], v[212:215], v[88:91]
	v_mfma_f32_16x16x32_bf16 v[88:91], v[164:167], v[208:211], v[88:91]
	v_mfma_f32_16x16x32_bf16 v[84:87], v[172:175], v[208:211], v[84:87]
	v_mfma_f32_16x16x32_bf16 v[84:87], v[176:179], v[212:215], v[84:87]
	v_mfma_f32_16x16x32_bf16 v[80:83], v[184:187], v[212:215], v[80:83]
	v_mfma_f32_16x16x32_bf16 v[80:83], v[180:183], v[208:211], v[80:83]
	v_mfma_f32_16x16x32_bf16 v[64:67], v[180:183], v[216:219], v[64:67]
	v_mfma_f32_16x16x32_bf16 v[64:67], v[184:187], v[220:223], v[64:67]
	v_mfma_f32_16x16x32_bf16 v[68:71], v[176:179], v[220:223], v[68:71]
	v_mfma_f32_16x16x32_bf16 v[68:71], v[172:175], v[216:219], v[68:71]
	v_mfma_f32_16x16x32_bf16 v[72:75], v[164:167], v[216:219], v[72:75]
	v_mfma_f32_16x16x32_bf16 v[72:75], v[168:171], v[220:223], v[72:75]
	v_mfma_f32_16x16x32_bf16 v[76:79], v[160:163], v[220:223], v[76:79]
	v_mfma_f32_16x16x32_bf16 v[76:79], v[148:151], v[216:219], v[76:79]
	s_setprio 0
	s_barrier
; #define PG8_STAGE(bufoff, gbase, voff) do { _Pragma("unroll") for (int _i = 0; _i < 2; ++_i) \
;         __builtin_amdgcn_global_load_lds((const unsigned*)((const char*)(gbase) + (voff)[_i]), (LAS unsigned*)(lds + (bufoff) + ldsw + _i * 8192), 16, 0, 0); } while (0)
; #define PG8_LDA(dst, b, h) do { _Pragma("unroll") for (int m = 0; m < 4; ++m) _Pragma("unroll") for (int k = 0; k < 2; ++k) dst[m][k] = *(const LAS bf16x8*)(lds + PG8_SA(b, h) + aoff + m * 2048 + k * 1024); } while (0)
; #define PG8_MMA(ai, bj, At, Bt) do { __builtin_amdgcn_s_setprio(1); _Pragma("unroll") for (int m = 0; m < 4; ++m) _Pragma("unroll") for (int n = 0; n < 2; ++n) _Pragma("unroll") for (int k = 0; k < 2; ++k) \
;         acc[ai][bj][m][n] = __builtin_amdgcn_mfma_f32_16x16x32_bf16(Bt[n][k], At[m][k], acc[ai][bj][m][n], 0, 0, 0); __builtin_amdgcn_s_setprio(0); } while (0)
; #define PG8_WAIT_V(n) asm volatile("s_waitcnt vmcnt(" #n ")" ::: "memory")
; #define PG8_WAIT_L(n) asm volatile("s_waitcnt lgkmcnt(" #n ")" ::: "memory")
; #define PG8_BAR __builtin_amdgcn_s_barrier()
; #define PG8_SCHED __builtin_amdgcn_sched_barrier(0)
; template <class Epi>
; __device__ __forceinline__ void gemm_phase(LAS unsigned char* lds, const Gemm g, const StaticOrder& S, const Epi& E) {
;     ...
;             PG8_LDA(At, 1, 1); PG8_STAGE(PG8_SB(1, 0), b3, voffB); PG8_STAGE(PG8_SB(1, 1), b3 + hstepB, voffB); PG8_STAGE(PG8_SA(1, 0), a3, voffA);
;             PG8_WAIT_V(8); PG8_WAIT_L(0); PG8_BAR; PG8_MMA(1, 0, At, B0); PG8_MMA(1, 1, At, B1); PG8_BAR; PG8_SCHED;
	s_add_i32 s30, s58, s38
	v_lshl_add_u64 v[224:225], v[224:225], 0, s[12:13]
	s_mov_b32 m0, s30
	ds_read_b128 v[188:191], v157 offset:49152
	ds_read_b128 v[192:195], v157 offset:50176
	ds_read_b128 v[196:199], v157 offset:51200
	ds_read_b128 v[200:203], v157 offset:52224
	ds_read_b128 v[208:211], v157 offset:53248
	ds_read_b128 v[212:215], v157 offset:54272
	ds_read_b128 v[216:219], v157 offset:55296
	ds_read_b128 v[220:223], v157 offset:56320
	global_load_lds_dwordx4 v[224:225], off
	s_add_i32 m0, s30, 0x2000
	s_add_u32 s26, s26, 0x80080
	v_lshl_add_u64 v[224:225], v[226:227], 0, s[12:13]
	s_addc_u32 s27, s27, 0
	s_add_i32 s30, s59, s38
	global_load_lds_dwordx4 v[224:225], off
	v_lshl_add_u64 v[224:225], s[26:27], 0, v[130:131]
	s_mov_b32 m0, s30
	s_nop 0
	global_load_lds_dwordx4 v[224:225], off
	v_lshl_add_u64 v[224:225], s[26:27], 0, v[134:135]
	s_add_i32 m0, s30, 0x2000
	s_nop 0
	global_load_lds_dwordx4 v[224:225], off
	v_lshl_add_u64 v[224:225], v[230:231], 0, s[12:13]
	s_mov_b32 m0, s47
	s_nop 0
	global_load_lds_dwordx4 v[224:225], off
	v_lshl_add_u64 v[224:225], v[232:233], 0, s[12:13]
	s_mov_b32 m0, s48
	s_nop 0
	global_load_lds_dwordx4 v[224:225], off
	s_waitcnt vmcnt(8) lgkmcnt(0)
	s_barrier
	s_setprio 1
	v_mfma_f32_16x16x32_bf16 v[60:63], v[148:151], v[188:191], v[60:63]
	v_mfma_f32_16x16x32_bf16 v[60:63], v[160:163], v[192:195], v[60:63]
	v_mfma_f32_16x16x32_bf16 v[56:59], v[168:171], v[192:195], v[56:59]
	v_mfma_f32_16x16x32_bf16 v[56:59], v[164:167], v[188:191], v[56:59]
	v_mfma_f32_16x16x32_bf16 v[52:55], v[172:175], v[188:191], v[52:55]
	v_mfma_f32_16x16x32_bf16 v[52:55], v[176:179], v[192:195], v[52:55]
	v_mfma_f32_16x16x32_bf16 v[48:51], v[184:187], v[192:195], v[48:51]
	v_mfma_f32_16x16x32_bf16 v[48:51], v[180:183], v[188:191], v[48:51]
	v_mfma_f32_16x16x32_bf16 v[32:35], v[180:183], v[196:199], v[32:35]
	v_mfma_f32_16x16x32_bf16 v[32:35], v[184:187], v[200:203], v[32:35]
	v_mfma_f32_16x16x32_bf16 v[36:39], v[176:179], v[200:203], v[36:39]
	v_mfma_f32_16x16x32_bf16 v[36:39], v[172:175], v[196:199], v[36:39]
	v_mfma_f32_16x16x32_bf16 v[40:43], v[164:167], v[196:199], v[40:43]
	v_mfma_f32_16x16x32_bf16 v[40:43], v[168:171], v[200:203], v[40:43]
	v_mfma_f32_16x16x32_bf16 v[44:47], v[160:163], v[200:203], v[44:47]
	v_mfma_f32_16x16x32_bf16 v[44:47], v[148:151], v[196:199], v[44:47]
	s_setprio 0
	s_setprio 1
	v_mfma_f32_16x16x32_bf16 v[28:31], v[148:151], v[208:211], v[28:31]
	v_mfma_f32_16x16x32_bf16 v[28:31], v[160:163], v[212:215], v[28:31]
	v_mfma_f32_16x16x32_bf16 v[24:27], v[168:171], v[212:215], v[24:27]
	v_mfma_f32_16x16x32_bf16 v[24:27], v[164:167], v[208:211], v[24:27]
	v_mfma_f32_16x16x32_bf16 v[20:23], v[172:175], v[208:211], v[20:23]
	v_mfma_f32_16x16x32_bf16 v[20:23], v[176:179], v[212:215], v[20:23]
	v_mfma_f32_16x16x32_bf16 v[16:19], v[184:187], v[212:215], v[16:19]
	v_mfma_f32_16x16x32_bf16 v[16:19], v[180:183], v[208:211], v[16:19]
	v_mfma_f32_16x16x32_bf16 v[0:3], v[180:183], v[216:219], v[0:3]
	v_mfma_f32_16x16x32_bf16 v[0:3], v[184:187], v[220:223], v[0:3]
	v_mfma_f32_16x16x32_bf16 v[4:7], v[176:179], v[220:223], v[4:7]
	v_mfma_f32_16x16x32_bf16 v[4:7], v[172:175], v[216:219], v[4:7]
	v_mfma_f32_16x16x32_bf16 v[8:11], v[164:167], v[216:219], v[8:11]
	v_mfma_f32_16x16x32_bf16 v[8:11], v[168:171], v[220:223], v[8:11]
	v_mfma_f32_16x16x32_bf16 v[12:15], v[160:163], v[220:223], v[12:15]
	v_mfma_f32_16x16x32_bf16 v[12:15], v[148:151], v[216:219], v[12:15]
	s_setprio 0
	s_barrier
	s_add_u32 s8, s8, 0x100
	s_addc_u32 s9, s9, 0
	s_add_u32 s33, s33, 0x100
	s_addc_u32 s34, s34, 0
	s_cmp_ge_i32 s35, s44
	s_mov_b32 s26, s35
	s_cbranch_scc0 .LBB0_541

; #define PG8_STAGE(bufoff, gbase, voff) do { _Pragma("unroll") for (int _i = 0; _i < 2; ++_i) \
;         __builtin_amdgcn_global_load_lds((const unsigned*)((const char*)(gbase) + (voff)[_i]), (LAS unsigned*)(lds + (bufoff) + ldsw + _i * 8192), 16, 0, 0); } while (0)
; #define PG8_LDA(dst, b, h) do { _Pragma("unroll") for (int m = 0; m < 4; ++m) _Pragma("unroll") for (int k = 0; k < 2; ++k) dst[m][k] = *(const LAS bf16x8*)(lds + PG8_SA(b, h) + aoff + m * 2048 + k * 1024); } while (0)
; #define PG8_LDB(dst, b, h) do { _Pragma("unroll") for (int n = 0; n < 2; ++n) _Pragma("unroll") for (int k = 0; k < 2; ++k) dst[n][k] = *(const LAS bf16x8*)(lds + PG8_SB(b, h) + boff + n * 2048 + k * 1024); } while (0)
; #define PG8_MMA(ai, bj, At, Bt) do { __builtin_amdgcn_s_setprio(1); _Pragma("unroll") for (int m = 0; m < 4; ++m) _Pragma("unroll") for (int n = 0; n < 2; ++n) _Pragma("unroll") for (int k = 0; k < 2; ++k) \
;         acc[ai][bj][m][n] = __builtin_amdgcn_mfma_f32_16x16x32_bf16(Bt[n][k], At[m][k], acc[ai][bj][m][n], 0, 0, 0); __builtin_amdgcn_s_setprio(0); } while (0)
; #define PG8_WAIT_V(n) asm volatile("s_waitcnt vmcnt(" #n ")" ::: "memory")
; #define PG8_WAIT_L(n) asm volatile("s_waitcnt lgkmcnt(" #n ")" ::: "memory")
; #define PG8_BAR __builtin_amdgcn_s_barrier()
; #define PG8_SCHED __builtin_amdgcn_sched_barrier(0)
; template <class Epi>
; __device__ __forceinline__ void gemm_phase(LAS unsigned char* lds, const Gemm g, const StaticOrder& S, const Epi& E) {
;     ...
;             PG8_LDB(B0, 0, 0); PG8_LDB(B1, 0, 1); PG8_SCHED; PG8_LDA(At, 0, 0); PG8_STAGE(PG8_SA(1, 1), a1 + hstepA, voffA);
;             PG8_WAIT_V(8); PG8_WAIT_L(0); PG8_BAR; PG8_MMA(0, 0, At, B0); PG8_MMA(0, 1, At, B1); PG8_BAR; PG8_SCHED;
;             PG8_LDA(At, 0, 1); PG8_STAGE(PG8_SB(0, 0), b2, voffB); PG8_STAGE(PG8_SB(0, 1), b2 + hstepB, voffB); PG8_STAGE(PG8_SA(0, 0), a2, voffA);
;             PG8_WAIT_V(8); PG8_WAIT_L(0); PG8_BAR; PG8_MMA(1, 0, At, B0); PG8_MMA(1, 1, At, B1); PG8_BAR; PG8_SCHED;
.LBB0_685:
	ds_read_b128 v[88:91], v85
	ds_read_b128 v[92:95], v85 offset:1024
	ds_read_b128 v[96:99], v85 offset:2048
	ds_read_b128 v[100:103], v85 offset:3072
	s_add_i32 s61, s34, 2
	s_add_u32 s8, s30, 0x100
	s_addc_u32 s9, s31, 0
	s_cmp_eq_u32 s53, s34
	s_cselect_b32 s34, s25, s59
	s_cselect_b32 s37, s27, s9
	s_cselect_b32 s36, s26, s8
	s_cselect_b32 s35, s17, s60
	v_lshl_add_u64 v[136:137], s[30:31], 0, v[76:77]
	s_add_i32 m0, s40, 0xc000
	ds_read_b128 v[104:107], v86
	ds_read_b128 v[108:111], v86 offset:1024
	ds_read_b128 v[112:115], v86 offset:2048
	ds_read_b128 v[116:119], v86 offset:3072
	ds_read_b128 v[120:123], v86 offset:4096
	ds_read_b128 v[124:127], v86 offset:5120
	ds_read_b128 v[128:131], v86 offset:6144
	ds_read_b128 v[132:135], v86 offset:7168
	global_load_lds_dwordx4 v[136:137], off
	v_lshl_add_u64 v[136:137], s[30:31], 0, v[78:79]
	s_add_i32 m0, s40, 0xe000
	s_nop 0
	global_load_lds_dwordx4 v[136:137], off
	s_waitcnt vmcnt(8) lgkmcnt(0)
	s_barrier
	s_setprio 1
	v_mfma_f32_16x16x32_bf16 v[60:63], v[88:91], v[104:107], v[60:63]
	v_mfma_f32_16x16x32_bf16 v[60:63], v[92:95], v[108:111], v[60:63]
	v_mfma_f32_16x16x32_bf16 v[56:59], v[100:103], v[108:111], v[56:59]
	v_mfma_f32_16x16x32_bf16 v[56:59], v[96:99], v[104:107], v[56:59]
	v_mfma_f32_16x16x32_bf16 v[48:51], v[96:99], v[112:115], v[48:51]
	v_mfma_f32_16x16x32_bf16 v[48:51], v[100:103], v[116:119], v[48:51]
	v_mfma_f32_16x16x32_bf16 v[52:55], v[92:95], v[116:119], v[52:55]
	v_mfma_f32_16x16x32_bf16 v[52:55], v[88:91], v[112:115], v[52:55]
	v_mfma_f32_16x16x32_bf16 v[44:47], v[88:91], v[120:123], v[44:47]
	v_mfma_f32_16x16x32_bf16 v[44:47], v[92:95], v[124:127], v[44:47]
	v_mfma_f32_16x16x32_bf16 v[40:43], v[100:103], v[124:127], v[40:43]
	v_mfma_f32_16x16x32_bf16 v[40:43], v[96:99], v[120:123], v[40:43]
	v_mfma_f32_16x16x32_bf16 v[32:35], v[96:99], v[128:131], v[32:35]
	v_mfma_f32_16x16x32_bf16 v[32:35], v[100:103], v[132:135], v[32:35]
	v_mfma_f32_16x16x32_bf16 v[36:39], v[92:95], v[132:135], v[36:39]
	v_mfma_f32_16x16x32_bf16 v[36:39], v[88:91], v[128:131], v[36:39]
	s_setprio 0
	s_setprio 1
	s_setprio 0
	s_barrier
	s_add_i32 s30, s56, s39
	v_lshl_add_u64 v[136:137], s[34:35], 0, v[66:67]
	s_mov_b32 m0, s30
	ds_read_b128 v[104:107], v86 offset:16384
	ds_read_b128 v[108:111], v86 offset:17408
	ds_read_b128 v[112:115], v86 offset:18432
	ds_read_b128 v[116:119], v86 offset:19456
	ds_read_b128 v[120:123], v86 offset:20480
	ds_read_b128 v[124:127], v86 offset:21504
	ds_read_b128 v[128:131], v86 offset:22528
	ds_read_b128 v[132:135], v86 offset:23552
	global_load_lds_dwordx4 v[136:137], off
	s_add_i32 m0, s30, 0x2000
	s_add_u32 s30, s34, 0x10000
	v_lshl_add_u64 v[138:139], s[34:35], 0, v[70:71]
	s_addc_u32 s31, s35, 0
	global_load_lds_dwordx4 v[138:139], off
	v_lshl_add_u64 v[140:141], s[30:31], 0, v[66:67]
	s_mov_b32 m0, s41
	v_lshl_add_u64 v[142:143], s[36:37], 0, v[68:69]
	global_load_lds_dwordx4 v[140:141], off
	v_lshl_add_u64 v[140:141], s[30:31], 0, v[70:71]
	s_mov_b32 m0, s42
	s_nop 0
	global_load_lds_dwordx4 v[140:141], off
	v_lshl_add_u64 v[140:141], s[36:37], 0, v[64:65]
	s_mov_b32 m0, s40
	s_nop 0
	global_load_lds_dwordx4 v[140:141], off
	s_mov_b32 m0, s43
	s_nop 0
	global_load_lds_dwordx4 v[142:143], off
	s_waitcnt vmcnt(8) lgkmcnt(0)
	s_barrier
	s_setprio 1
	v_mfma_f32_16x16x32_bf16 v[28:31], v[88:91], v[104:107], v[28:31]
	v_mfma_f32_16x16x32_bf16 v[28:31], v[92:95], v[108:111], v[28:31]
	v_mfma_f32_16x16x32_bf16 v[24:27], v[100:103], v[108:111], v[24:27]
	v_mfma_f32_16x16x32_bf16 v[24:27], v[96:99], v[104:107], v[24:27]
	v_mfma_f32_16x16x32_bf16 v[16:19], v[96:99], v[112:115], v[16:19]
	v_mfma_f32_16x16x32_bf16 v[16:19], v[100:103], v[116:119], v[16:19]
	v_mfma_f32_16x16x32_bf16 v[20:23], v[92:95], v[116:119], v[20:23]
	v_mfma_f32_16x16x32_bf16 v[20:23], v[88:91], v[112:115], v[20:23]
	v_mfma_f32_16x16x32_bf16 v[12:15], v[88:91], v[120:123], v[12:15]
	v_mfma_f32_16x16x32_bf16 v[12:15], v[92:95], v[124:127], v[12:15]
	v_mfma_f32_16x16x32_bf16 v[8:11], v[100:103], v[124:127], v[8:11]
	v_mfma_f32_16x16x32_bf16 v[8:11], v[96:99], v[120:123], v[8:11]
	v_mfma_f32_16x16x32_bf16 v[0:3], v[96:99], v[128:131], v[0:3]
	v_mfma_f32_16x16x32_bf16 v[0:3], v[100:103], v[132:135], v[0:3]
	v_mfma_f32_16x16x32_bf16 v[4:7], v[92:95], v[132:135], v[4:7]
	v_mfma_f32_16x16x32_bf16 v[4:7], v[88:91], v[128:131], v[4:7]
	s_setprio 0
	s_setprio 1
	s_setprio 0
	s_barrier
; #define PG8_STAGE(bufoff, gbase, voff) do { _Pragma("unroll") for (int _i = 0; _i < 2; ++_i) \
;         __builtin_amdgcn_global_load_lds((const unsigned*)((const char*)(gbase) + (voff)[_i]), (LAS unsigned*)(lds + (bufoff) + ldsw + _i * 8192), 16, 0, 0); } while (0)
; #define PG8_LDA(dst, b, h) do { _Pragma("unroll") for (int m = 0; m < 4; ++m) _Pragma("unroll") for (int k = 0; k < 2; ++k) dst[m][k] = *(const LAS bf16x8*)(lds + PG8_SA(b, h) + aoff + m * 2048 + k * 1024); } while (0)
; #define PG8_LDB(dst, b, h) do { _Pragma("unroll") for (int n = 0; n < 2; ++n) _Pragma("unroll") for (int k = 0; k < 2; ++k) dst[n][k] = *(const LAS bf16x8*)(lds + PG8_SB(b, h) + boff + n * 2048 + k * 1024); } while (0)
; #define PG8_MMA(ai, bj, At, Bt) do { __builtin_amdgcn_s_setprio(1); _Pragma("unroll") for (int m = 0; m < 4; ++m) _Pragma("unroll") for (int n = 0; n < 2; ++n) _Pragma("unroll") for (int k = 0; k < 2; ++k) \
;         acc[ai][bj][m][n] = __builtin_amdgcn_mfma_f32_16x16x32_bf16(Bt[n][k], At[m][k], acc[ai][bj][m][n], 0, 0, 0); __builtin_amdgcn_s_setprio(0); } while (0)
; #define PG8_WAIT_V(n) asm volatile("s_waitcnt vmcnt(" #n ")" ::: "memory")
; #define PG8_WAIT_L(n) asm volatile("s_waitcnt lgkmcnt(" #n ")" ::: "memory")
; #define PG8_BAR __builtin_amdgcn_s_barrier()
; #define PG8_SCHED __builtin_amdgcn_sched_barrier(0)
; template <class Epi>
; __device__ __forceinline__ void gemm_phase(LAS unsigned char* lds, const Gemm g, const StaticOrder& S, const Epi& E) {
;     ...
;             PG8_LDB(B0, 1, 0); PG8_LDB(B1, 1, 1); PG8_SCHED; PG8_LDA(At, 1, 0); PG8_STAGE(PG8_SA(0, 1), a2 + hstepA, voffA);
;             PG8_WAIT_V(8); PG8_WAIT_L(0); PG8_BAR; PG8_MMA(0, 0, At, B0); PG8_MMA(0, 1, At, B1); PG8_BAR; PG8_SCHED;
;             PG8_LDA(At, 1, 1); PG8_STAGE(PG8_SB(1, 0), b3, voffB); PG8_STAGE(PG8_SB(1, 1), b3 + hstepB, voffB); PG8_STAGE(PG8_SA(1, 0), a3, voffA);
;             PG8_WAIT_V(8); PG8_WAIT_L(0); PG8_BAR; PG8_MMA(1, 0, At, B0); PG8_MMA(1, 1, At, B1); PG8_BAR; PG8_SCHED;
	s_add_i32 s62, 0, 0x18000
	v_add_u32_e32 v87, s62, v84
	ds_read_b128 v[88:91], v87
	ds_read_b128 v[92:95], v87 offset:1024
	ds_read_b128 v[96:99], v87 offset:2048
	ds_read_b128 v[100:103], v87 offset:3072
	s_add_u32 s30, s36, 0x18000
	s_addc_u32 s31, s37, 0
	s_mov_b32 m0, s44
	v_lshl_add_u64 v[144:145], s[30:31], 0, v[64:65]
	ds_read_b128 v[104:107], v86 offset:32768
	ds_read_b128 v[108:111], v86 offset:33792
	ds_read_b128 v[112:115], v86 offset:34816
	ds_read_b128 v[116:119], v86 offset:35840
	ds_read_b128 v[120:123], v86 offset:36864
	ds_read_b128 v[124:127], v86 offset:37888
	ds_read_b128 v[128:131], v86 offset:38912
	ds_read_b128 v[132:135], v86 offset:39936
	global_load_lds_dwordx4 v[144:145], off
	v_lshl_add_u64 v[144:145], s[30:31], 0, v[68:69]
	s_mov_b32 m0, s45
	s_nop 0
	global_load_lds_dwordx4 v[144:145], off
	s_waitcnt vmcnt(8) lgkmcnt(0)
	s_barrier
	s_setprio 1
	v_mfma_f32_16x16x32_bf16 v[60:63], v[88:91], v[104:107], v[60:63]
	v_mfma_f32_16x16x32_bf16 v[60:63], v[92:95], v[108:111], v[60:63]
	v_mfma_f32_16x16x32_bf16 v[56:59], v[100:103], v[108:111], v[56:59]
	v_mfma_f32_16x16x32_bf16 v[56:59], v[96:99], v[104:107], v[56:59]
	v_mfma_f32_16x16x32_bf16 v[48:51], v[96:99], v[112:115], v[48:51]
	v_mfma_f32_16x16x32_bf16 v[48:51], v[100:103], v[116:119], v[48:51]
	v_mfma_f32_16x16x32_bf16 v[52:55], v[92:95], v[116:119], v[52:55]
	v_mfma_f32_16x16x32_bf16 v[52:55], v[88:91], v[112:115], v[52:55]
	v_mfma_f32_16x16x32_bf16 v[44:47], v[88:91], v[120:123], v[44:47]
	v_mfma_f32_16x16x32_bf16 v[44:47], v[92:95], v[124:127], v[44:47]
	v_mfma_f32_16x16x32_bf16 v[40:43], v[100:103], v[124:127], v[40:43]
	v_mfma_f32_16x16x32_bf16 v[40:43], v[96:99], v[120:123], v[40:43]
	v_mfma_f32_16x16x32_bf16 v[32:35], v[96:99], v[128:131], v[32:35]
	v_mfma_f32_16x16x32_bf16 v[32:35], v[100:103], v[132:135], v[32:35]
	v_mfma_f32_16x16x32_bf16 v[36:39], v[92:95], v[132:135], v[36:39]
	v_mfma_f32_16x16x32_bf16 v[36:39], v[88:91], v[128:131], v[36:39]
	s_setprio 0
	s_setprio 1
	s_setprio 0
	s_barrier
	s_add_i32 s30, s62, s39
	v_lshl_add_u64 v[136:137], v[136:137], 0, s[10:11]
	s_mov_b32 m0, s30
	ds_read_b128 v[104:107], v86 offset:49152
	ds_read_b128 v[108:111], v86 offset:50176
	ds_read_b128 v[112:115], v86 offset:51200
	ds_read_b128 v[116:119], v86 offset:52224
	ds_read_b128 v[120:123], v86 offset:53248
	ds_read_b128 v[124:127], v86 offset:54272
	ds_read_b128 v[128:131], v86 offset:55296
	ds_read_b128 v[132:135], v86 offset:56320
	global_load_lds_dwordx4 v[136:137], off
	s_add_i32 m0, s30, 0x2000
	s_add_u32 s30, s34, 0x10080
	v_lshl_add_u64 v[136:137], v[138:139], 0, s[10:11]
	s_addc_u32 s31, s35, 0
	global_load_lds_dwordx4 v[136:137], off
	v_lshl_add_u64 v[136:137], s[30:31], 0, v[66:67]
	s_mov_b32 m0, s49
	s_nop 0
	global_load_lds_dwordx4 v[136:137], off
	v_lshl_add_u64 v[136:137], s[30:31], 0, v[70:71]
	s_mov_b32 m0, s52
	s_nop 0
	global_load_lds_dwordx4 v[136:137], off
	v_lshl_add_u64 v[136:137], v[140:141], 0, s[10:11]
	s_mov_b32 m0, s47
	s_nop 0
	global_load_lds_dwordx4 v[136:137], off
	v_lshl_add_u64 v[136:137], v[142:143], 0, s[10:11]
	s_mov_b32 m0, s48
	s_nop 0
	global_load_lds_dwordx4 v[136:137], off
	s_waitcnt vmcnt(8) lgkmcnt(0)
	s_barrier
	s_setprio 1
	v_mfma_f32_16x16x32_bf16 v[28:31], v[88:91], v[104:107], v[28:31]
	v_mfma_f32_16x16x32_bf16 v[28:31], v[92:95], v[108:111], v[28:31]
	v_mfma_f32_16x16x32_bf16 v[24:27], v[100:103], v[108:111], v[24:27]
	v_mfma_f32_16x16x32_bf16 v[24:27], v[96:99], v[104:107], v[24:27]
	v_mfma_f32_16x16x32_bf16 v[16:19], v[96:99], v[112:115], v[16:19]
	v_mfma_f32_16x16x32_bf16 v[16:19], v[100:103], v[116:119], v[16:19]
	v_mfma_f32_16x16x32_bf16 v[20:23], v[92:95], v[116:119], v[20:23]
	v_mfma_f32_16x16x32_bf16 v[20:23], v[88:91], v[112:115], v[20:23]
	v_mfma_f32_16x16x32_bf16 v[12:15], v[88:91], v[120:123], v[12:15]
	v_mfma_f32_16x16x32_bf16 v[12:15], v[92:95], v[124:127], v[12:15]
	v_mfma_f32_16x16x32_bf16 v[8:11], v[100:103], v[124:127], v[8:11]
	v_mfma_f32_16x16x32_bf16 v[8:11], v[96:99], v[120:123], v[8:11]
	v_mfma_f32_16x16x32_bf16 v[0:3], v[96:99], v[128:131], v[0:3]
	v_mfma_f32_16x16x32_bf16 v[0:3], v[100:103], v[132:135], v[0:3]
	v_mfma_f32_16x16x32_bf16 v[4:7], v[92:95], v[132:135], v[4:7]
	v_mfma_f32_16x16x32_bf16 v[4:7], v[88:91], v[128:131], v[4:7]
	s_setprio 0
	s_setprio 1
	s_setprio 0
	s_barrier
	s_add_u32 s59, s59, 0x100
	s_addc_u32 s60, s60, 0
	s_cmp_ge_i32 s61, s46
	s_mov_b64 s[30:31], s[8:9]
	s_mov_b32 s34, s61
	s_cbranch_scc0 .LBB0_685

; #define PG8_STAGE(bufoff, gbase, voff) do { _Pragma("unroll") for (int _i = 0; _i < 2; ++_i) \
;         __builtin_amdgcn_global_load_lds((const unsigned*)((const char*)(gbase) + (voff)[_i]), (LAS unsigned*)(lds + (bufoff) + ldsw + _i * 8192), 16, 0, 0); } while (0)
; #define PG8_LDA(dst, b, h) do { _Pragma("unroll") for (int m = 0; m < 4; ++m) _Pragma("unroll") for (int k = 0; k < 2; ++k) dst[m][k] = *(const LAS bf16x8*)(lds + PG8_SA(b, h) + aoff + m * 2048 + k * 1024); } while (0)
; #define PG8_LDB(dst, b, h) do { _Pragma("unroll") for (int n = 0; n < 2; ++n) _Pragma("unroll") for (int k = 0; k < 2; ++k) dst[n][k] = *(const LAS bf16x8*)(lds + PG8_SB(b, h) + boff + n * 2048 + k * 1024); } while (0)
; #define PG8_MMA(ai, bj, At, Bt) do { __builtin_amdgcn_s_setprio(1); _Pragma("unroll") for (int m = 0; m < 4; ++m) _Pragma("unroll") for (int n = 0; n < 2; ++n) _Pragma("unroll") for (int k = 0; k < 2; ++k) \
;         acc[ai][bj][m][n] = __builtin_amdgcn_mfma_f32_16x16x32_bf16(Bt[n][k], At[m][k], acc[ai][bj][m][n], 0, 0, 0); __builtin_amdgcn_s_setprio(0); } while (0)
; #define PG8_WAIT_V(n) asm volatile("s_waitcnt vmcnt(" #n ")" ::: "memory")
; #define PG8_WAIT_L(n) asm volatile("s_waitcnt lgkmcnt(" #n ")" ::: "memory")
; #define PG8_BAR __builtin_amdgcn_s_barrier()
; #define PG8_SCHED __builtin_amdgcn_sched_barrier(0)
; template <class Epi>
; __device__ __forceinline__ void gemm_phase(LAS unsigned char* lds, const Gemm g, const StaticOrder& S, const Epi& E) {
;     ...
;             PG8_LDB(B0, 0, 0); PG8_LDB(B1, 0, 1); PG8_SCHED; PG8_LDA(At, 0, 0); PG8_STAGE(PG8_SA(1, 1), a1 + hstepA, voffA);
;             PG8_WAIT_V(8); PG8_WAIT_L(0); PG8_BAR; PG8_MMA(0, 0, At, B0); PG8_MMA(0, 1, At, B1); PG8_BAR; PG8_SCHED;
;             PG8_LDA(At, 0, 1); PG8_STAGE(PG8_SB(0, 0), b2, voffB); PG8_STAGE(PG8_SB(0, 1), b2 + hstepB, voffB); PG8_STAGE(PG8_SA(0, 0), a2, voffA);
;             PG8_WAIT_V(8); PG8_WAIT_L(0); PG8_BAR; PG8_MMA(1, 0, At, B0); PG8_MMA(1, 1, At, B1); PG8_BAR; PG8_SCHED;
.LBB0_834:
	ds_read_b128 v[156:159], v152
	ds_read_b128 v[160:163], v152 offset:1024
	ds_read_b128 v[164:167], v152 offset:2048
	ds_read_b128 v[168:171], v152 offset:3072
	ds_read_b128 v[172:175], v153
	ds_read_b128 v[176:179], v153 offset:1024
	ds_read_b128 v[180:183], v153 offset:2048
	ds_read_b128 v[184:187], v153 offset:3072
	s_add_i32 s49, s22, 2
	s_add_u32 s4, s0, 0x100
	s_addc_u32 s5, s1, 0
	s_cmp_eq_u32 s40, s22
	s_cselect_b32 s22, s20, s47
	s_cselect_b32 s25, s11, s5
	s_cselect_b32 s24, s10, s4
	s_cselect_b32 s23, s21, s48
	v_lshl_add_u64 v[224:225], s[0:1], 0, v[138:139]
	s_add_i32 m0, s29, 0xc000
	ds_read_b128 v[188:191], v154
	ds_read_b128 v[192:195], v154 offset:1024
	ds_read_b128 v[196:199], v154 offset:2048
	ds_read_b128 v[200:203], v154 offset:3072
	ds_read_b128 v[208:211], v154 offset:4096
	ds_read_b128 v[212:215], v154 offset:5120
	ds_read_b128 v[216:219], v154 offset:6144
	ds_read_b128 v[220:223], v154 offset:7168
	global_load_lds_dwordx4 v[224:225], off
	v_lshl_add_u64 v[224:225], s[0:1], 0, v[140:141]
	s_add_i32 m0, s29, 0xe000
	s_nop 0
	global_load_lds_dwordx4 v[224:225], off
	s_waitcnt vmcnt(8) lgkmcnt(0)
	s_barrier
	s_setprio 1
	v_mfma_f32_16x16x32_bf16 v[124:127], v[156:159], v[188:191], v[124:127]
	v_mfma_f32_16x16x32_bf16 v[124:127], v[160:163], v[192:195], v[124:127]
	v_mfma_f32_16x16x32_bf16 v[120:123], v[168:171], v[192:195], v[120:123]
	v_mfma_f32_16x16x32_bf16 v[120:123], v[164:167], v[188:191], v[120:123]
	v_mfma_f32_16x16x32_bf16 v[116:119], v[172:175], v[188:191], v[116:119]
	v_mfma_f32_16x16x32_bf16 v[116:119], v[176:179], v[192:195], v[116:119]
	v_mfma_f32_16x16x32_bf16 v[112:115], v[184:187], v[192:195], v[112:115]
	v_mfma_f32_16x16x32_bf16 v[112:115], v[180:183], v[188:191], v[112:115]
	v_mfma_f32_16x16x32_bf16 v[96:99], v[180:183], v[196:199], v[96:99]
	v_mfma_f32_16x16x32_bf16 v[96:99], v[184:187], v[200:203], v[96:99]
	v_mfma_f32_16x16x32_bf16 v[100:103], v[176:179], v[200:203], v[100:103]
	v_mfma_f32_16x16x32_bf16 v[100:103], v[172:175], v[196:199], v[100:103]
	v_mfma_f32_16x16x32_bf16 v[104:107], v[164:167], v[196:199], v[104:107]
	v_mfma_f32_16x16x32_bf16 v[104:107], v[168:171], v[200:203], v[104:107]
	v_mfma_f32_16x16x32_bf16 v[108:111], v[160:163], v[200:203], v[108:111]
	v_mfma_f32_16x16x32_bf16 v[108:111], v[156:159], v[196:199], v[108:111]
	s_setprio 0
	s_setprio 1
	v_mfma_f32_16x16x32_bf16 v[92:95], v[156:159], v[208:211], v[92:95]
	v_mfma_f32_16x16x32_bf16 v[92:95], v[160:163], v[212:215], v[92:95]
	v_mfma_f32_16x16x32_bf16 v[88:91], v[168:171], v[212:215], v[88:91]
	v_mfma_f32_16x16x32_bf16 v[88:91], v[164:167], v[208:211], v[88:91]
	v_mfma_f32_16x16x32_bf16 v[84:87], v[172:175], v[208:211], v[84:87]
	v_mfma_f32_16x16x32_bf16 v[84:87], v[176:179], v[212:215], v[84:87]
	v_mfma_f32_16x16x32_bf16 v[80:83], v[184:187], v[212:215], v[80:83]
	v_mfma_f32_16x16x32_bf16 v[80:83], v[180:183], v[208:211], v[80:83]
	v_mfma_f32_16x16x32_bf16 v[64:67], v[180:183], v[216:219], v[64:67]
	v_mfma_f32_16x16x32_bf16 v[64:67], v[184:187], v[220:223], v[64:67]
	v_mfma_f32_16x16x32_bf16 v[68:71], v[176:179], v[220:223], v[68:71]
	v_mfma_f32_16x16x32_bf16 v[68:71], v[172:175], v[216:219], v[68:71]
	v_mfma_f32_16x16x32_bf16 v[72:75], v[164:167], v[216:219], v[72:75]
	v_mfma_f32_16x16x32_bf16 v[72:75], v[168:171], v[220:223], v[72:75]
	v_mfma_f32_16x16x32_bf16 v[76:79], v[160:163], v[220:223], v[76:79]
	v_mfma_f32_16x16x32_bf16 v[76:79], v[156:159], v[216:219], v[76:79]
	s_setprio 0
	s_barrier
	s_add_i32 s0, s43, s28
	v_lshl_add_u64 v[224:225], s[22:23], 0, v[130:131]
	s_mov_b32 m0, s0
	ds_read_b128 v[188:191], v154 offset:16384
	ds_read_b128 v[192:195], v154 offset:17408
	ds_read_b128 v[196:199], v154 offset:18432
	ds_read_b128 v[200:203], v154 offset:19456
	ds_read_b128 v[208:211], v154 offset:20480
	ds_read_b128 v[212:215], v154 offset:21504
	ds_read_b128 v[216:219], v154 offset:22528
	ds_read_b128 v[220:223], v154 offset:23552
	global_load_lds_dwordx4 v[224:225], off
	s_add_i32 m0, s0, 0x2000
	s_add_u32 s0, s22, 0x18000
	v_lshl_add_u64 v[226:227], s[22:23], 0, v[134:135]
	s_addc_u32 s1, s23, 0
	s_add_i32 s50, s44, s28
	global_load_lds_dwordx4 v[226:227], off
	v_lshl_add_u64 v[230:231], s[0:1], 0, v[130:131]
	s_mov_b32 m0, s50
	v_lshl_add_u64 v[232:233], s[24:25], 0, v[132:133]
	global_load_lds_dwordx4 v[230:231], off
	v_lshl_add_u64 v[230:231], s[0:1], 0, v[134:135]
	s_add_i32 m0, s50, 0x2000
	s_nop 0
	global_load_lds_dwordx4 v[230:231], off
	v_lshl_add_u64 v[230:231], s[24:25], 0, v[128:129]
	s_mov_b32 m0, s29
	s_nop 0
	global_load_lds_dwordx4 v[230:231], off
	s_mov_b32 m0, s30
	s_nop 0
	global_load_lds_dwordx4 v[232:233], off
	s_waitcnt vmcnt(8) lgkmcnt(0)
	s_barrier
; #define PG8_STAGE(bufoff, gbase, voff) do { _Pragma("unroll") for (int _i = 0; _i < 2; ++_i) \
;         __builtin_amdgcn_global_load_lds((const unsigned*)((const char*)(gbase) + (voff)[_i]), (LAS unsigned*)(lds + (bufoff) + ldsw + _i * 8192), 16, 0, 0); } while (0)
; #define PG8_LDA(dst, b, h) do { _Pragma("unroll") for (int m = 0; m < 4; ++m) _Pragma("unroll") for (int k = 0; k < 2; ++k) dst[m][k] = *(const LAS bf16x8*)(lds + PG8_SA(b, h) + aoff + m * 2048 + k * 1024); } while (0)
; #define PG8_LDB(dst, b, h) do { _Pragma("unroll") for (int n = 0; n < 2; ++n) _Pragma("unroll") for (int k = 0; k < 2; ++k) dst[n][k] = *(const LAS bf16x8*)(lds + PG8_SB(b, h) + boff + n * 2048 + k * 1024); } while (0)
; #define PG8_MMA(ai, bj, At, Bt) do { __builtin_amdgcn_s_setprio(1); _Pragma("unroll") for (int m = 0; m < 4; ++m) _Pragma("unroll") for (int n = 0; n < 2; ++n) _Pragma("unroll") for (int k = 0; k < 2; ++k) \
;         acc[ai][bj][m][n] = __builtin_amdgcn_mfma_f32_16x16x32_bf16(Bt[n][k], At[m][k], acc[ai][bj][m][n], 0, 0, 0); __builtin_amdgcn_s_setprio(0); } while (0)
; #define PG8_WAIT_V(n) asm volatile("s_waitcnt vmcnt(" #n ")" ::: "memory")
; #define PG8_WAIT_L(n) asm volatile("s_waitcnt lgkmcnt(" #n ")" ::: "memory")
; #define PG8_BAR __builtin_amdgcn_s_barrier()
; #define PG8_SCHED __builtin_amdgcn_sched_barrier(0)
; template <class Epi>
; __device__ __forceinline__ void gemm_phase(LAS unsigned char* lds, const Gemm g, const StaticOrder& S, const Epi& E) {
;     ...
;             PG8_WAIT_V(8); PG8_WAIT_L(0); PG8_BAR; PG8_MMA(1, 0, At, B0); PG8_MMA(1, 1, At, B1); PG8_BAR; PG8_SCHED;
;             PG8_LDB(B0, 1, 0); PG8_LDB(B1, 1, 1); PG8_SCHED; PG8_LDA(At, 1, 0); PG8_STAGE(PG8_SA(0, 1), a2 + hstepA, voffA);
;             PG8_WAIT_V(8); PG8_WAIT_L(0); PG8_BAR; PG8_MMA(0, 0, At, B0); PG8_MMA(0, 1, At, B1); PG8_BAR; PG8_SCHED;
	s_setprio 1
	v_mfma_f32_16x16x32_bf16 v[60:63], v[156:159], v[188:191], v[60:63]
	v_mfma_f32_16x16x32_bf16 v[60:63], v[160:163], v[192:195], v[60:63]
	v_mfma_f32_16x16x32_bf16 v[56:59], v[168:171], v[192:195], v[56:59]
	v_mfma_f32_16x16x32_bf16 v[56:59], v[164:167], v[188:191], v[56:59]
	v_mfma_f32_16x16x32_bf16 v[52:55], v[172:175], v[188:191], v[52:55]
	v_mfma_f32_16x16x32_bf16 v[52:55], v[176:179], v[192:195], v[52:55]
	v_mfma_f32_16x16x32_bf16 v[48:51], v[184:187], v[192:195], v[48:51]
	v_mfma_f32_16x16x32_bf16 v[48:51], v[180:183], v[188:191], v[48:51]
	v_mfma_f32_16x16x32_bf16 v[32:35], v[180:183], v[196:199], v[32:35]
	v_mfma_f32_16x16x32_bf16 v[32:35], v[184:187], v[200:203], v[32:35]
	v_mfma_f32_16x16x32_bf16 v[36:39], v[176:179], v[200:203], v[36:39]
	v_mfma_f32_16x16x32_bf16 v[36:39], v[172:175], v[196:199], v[36:39]
	v_mfma_f32_16x16x32_bf16 v[40:43], v[164:167], v[196:199], v[40:43]
	v_mfma_f32_16x16x32_bf16 v[40:43], v[168:171], v[200:203], v[40:43]
	v_mfma_f32_16x16x32_bf16 v[44:47], v[160:163], v[200:203], v[44:47]
	v_mfma_f32_16x16x32_bf16 v[44:47], v[156:159], v[196:199], v[44:47]
	s_setprio 0
	s_setprio 1
	v_mfma_f32_16x16x32_bf16 v[28:31], v[156:159], v[208:211], v[28:31]
	v_mfma_f32_16x16x32_bf16 v[28:31], v[160:163], v[212:215], v[28:31]
	v_mfma_f32_16x16x32_bf16 v[24:27], v[168:171], v[212:215], v[24:27]
	v_mfma_f32_16x16x32_bf16 v[24:27], v[164:167], v[208:211], v[24:27]
	v_mfma_f32_16x16x32_bf16 v[20:23], v[172:175], v[208:211], v[20:23]
	v_mfma_f32_16x16x32_bf16 v[20:23], v[176:179], v[212:215], v[20:23]
	v_mfma_f32_16x16x32_bf16 v[16:19], v[184:187], v[212:215], v[16:19]
	v_mfma_f32_16x16x32_bf16 v[16:19], v[180:183], v[208:211], v[16:19]
	v_mfma_f32_16x16x32_bf16 v[0:3], v[180:183], v[216:219], v[0:3]
	v_mfma_f32_16x16x32_bf16 v[0:3], v[184:187], v[220:223], v[0:3]
	v_mfma_f32_16x16x32_bf16 v[4:7], v[176:179], v[220:223], v[4:7]
	v_mfma_f32_16x16x32_bf16 v[4:7], v[172:175], v[216:219], v[4:7]
	v_mfma_f32_16x16x32_bf16 v[8:11], v[164:167], v[216:219], v[8:11]
	v_mfma_f32_16x16x32_bf16 v[8:11], v[168:171], v[220:223], v[8:11]
	v_mfma_f32_16x16x32_bf16 v[12:15], v[160:163], v[220:223], v[12:15]
	v_mfma_f32_16x16x32_bf16 v[12:15], v[156:159], v[216:219], v[12:15]
	s_setprio 0
	s_barrier
	s_add_i32 s50, 0, 0x18000
	v_add_u32_e32 v136, s50, v149
	s_add_i32 s51, 0, 0x1c000
	ds_read_b128 v[156:159], v136
	ds_read_b128 v[160:163], v136 offset:1024
	ds_read_b128 v[164:167], v136 offset:2048
	ds_read_b128 v[168:171], v136 offset:3072
	v_add_u32_e32 v136, s51, v149
	ds_read_b128 v[172:175], v136
	ds_read_b128 v[176:179], v136 offset:1024
	ds_read_b128 v[180:183], v136 offset:2048
	ds_read_b128 v[184:187], v136 offset:3072
	s_add_u32 s0, s24, 0x18000
	s_addc_u32 s1, s25, 0
	s_mov_b32 m0, s31
	v_lshl_add_u64 v[234:235], s[0:1], 0, v[128:129]
	ds_read_b128 v[188:191], v154 offset:32768
	ds_read_b128 v[192:195], v154 offset:33792
	ds_read_b128 v[196:199], v154 offset:34816
	ds_read_b128 v[200:203], v154 offset:35840
	ds_read_b128 v[208:211], v154 offset:36864
	ds_read_b128 v[212:215], v154 offset:37888
	ds_read_b128 v[216:219], v154 offset:38912
	ds_read_b128 v[220:223], v154 offset:39936
	global_load_lds_dwordx4 v[234:235], off
	v_lshl_add_u64 v[234:235], s[0:1], 0, v[132:133]
	s_mov_b32 m0, s34
	s_nop 0
	global_load_lds_dwordx4 v[234:235], off
	s_waitcnt vmcnt(8) lgkmcnt(0)
	s_barrier
	s_setprio 1
	v_mfma_f32_16x16x32_bf16 v[124:127], v[156:159], v[188:191], v[124:127]
	v_mfma_f32_16x16x32_bf16 v[124:127], v[160:163], v[192:195], v[124:127]
	v_mfma_f32_16x16x32_bf16 v[120:123], v[168:171], v[192:195], v[120:123]
	v_mfma_f32_16x16x32_bf16 v[120:123], v[164:167], v[188:191], v[120:123]
	v_mfma_f32_16x16x32_bf16 v[116:119], v[172:175], v[188:191], v[116:119]
	v_mfma_f32_16x16x32_bf16 v[116:119], v[176:179], v[192:195], v[116:119]
	v_mfma_f32_16x16x32_bf16 v[112:115], v[184:187], v[192:195], v[112:115]
	v_mfma_f32_16x16x32_bf16 v[112:115], v[180:183], v[188:191], v[112:115]
	v_mfma_f32_16x16x32_bf16 v[96:99], v[180:183], v[196:199], v[96:99]
	v_mfma_f32_16x16x32_bf16 v[96:99], v[184:187], v[200:203], v[96:99]
	v_mfma_f32_16x16x32_bf16 v[100:103], v[176:179], v[200:203], v[100:103]
	v_mfma_f32_16x16x32_bf16 v[100:103], v[172:175], v[196:199], v[100:103]
	v_mfma_f32_16x16x32_bf16 v[104:107], v[164:167], v[196:199], v[104:107]
	v_mfma_f32_16x16x32_bf16 v[104:107], v[168:171], v[200:203], v[104:107]
	v_mfma_f32_16x16x32_bf16 v[108:111], v[160:163], v[200:203], v[108:111]
	v_mfma_f32_16x16x32_bf16 v[108:111], v[156:159], v[196:199], v[108:111]
	s_setprio 0
	s_setprio 1
	v_mfma_f32_16x16x32_bf16 v[92:95], v[156:159], v[208:211], v[92:95]
	v_mfma_f32_16x16x32_bf16 v[92:95], v[160:163], v[212:215], v[92:95]
	v_mfma_f32_16x16x32_bf16 v[88:91], v[168:171], v[212:215], v[88:91]
	v_mfma_f32_16x16x32_bf16 v[88:91], v[164:167], v[208:211], v[88:91]
	v_mfma_f32_16x16x32_bf16 v[84:87], v[172:175], v[208:211], v[84:87]
	v_mfma_f32_16x16x32_bf16 v[84:87], v[176:179], v[212:215], v[84:87]
	v_mfma_f32_16x16x32_bf16 v[80:83], v[184:187], v[212:215], v[80:83]
	v_mfma_f32_16x16x32_bf16 v[80:83], v[180:183], v[208:211], v[80:83]
	v_mfma_f32_16x16x32_bf16 v[64:67], v[180:183], v[216:219], v[64:67]
	v_mfma_f32_16x16x32_bf16 v[64:67], v[184:187], v[220:223], v[64:67]
	v_mfma_f32_16x16x32_bf16 v[68:71], v[176:179], v[220:223], v[68:71]
	v_mfma_f32_16x16x32_bf16 v[68:71], v[172:175], v[216:219], v[68:71]
	v_mfma_f32_16x16x32_bf16 v[72:75], v[164:167], v[216:219], v[72:75]
	v_mfma_f32_16x16x32_bf16 v[72:75], v[168:171], v[220:223], v[72:75]
	v_mfma_f32_16x16x32_bf16 v[76:79], v[160:163], v[220:223], v[76:79]
	v_mfma_f32_16x16x32_bf16 v[76:79], v[156:159], v[216:219], v[76:79]
	s_setprio 0
	s_barrier
; #define PG8_STAGE(bufoff, gbase, voff) do { _Pragma("unroll") for (int _i = 0; _i < 2; ++_i) \
;         __builtin_amdgcn_global_load_lds((const unsigned*)((const char*)(gbase) + (voff)[_i]), (LAS unsigned*)(lds + (bufoff) + ldsw + _i * 8192), 16, 0, 0); } while (0)
; #define PG8_LDA(dst, b, h) do { _Pragma("unroll") for (int m = 0; m < 4; ++m) _Pragma("unroll") for (int k = 0; k < 2; ++k) dst[m][k] = *(const LAS bf16x8*)(lds + PG8_SA(b, h) + aoff + m * 2048 + k * 1024); } while (0)
; #define PG8_MMA(ai, bj, At, Bt) do { __builtin_amdgcn_s_setprio(1); _Pragma("unroll") for (int m = 0; m < 4; ++m) _Pragma("unroll") for (int n = 0; n < 2; ++n) _Pragma("unroll") for (int k = 0; k < 2; ++k) \
;         acc[ai][bj][m][n] = __builtin_amdgcn_mfma_f32_16x16x32_bf16(Bt[n][k], At[m][k], acc[ai][bj][m][n], 0, 0, 0); __builtin_amdgcn_s_setprio(0); } while (0)
; #define PG8_WAIT_V(n) asm volatile("s_waitcnt vmcnt(" #n ")" ::: "memory")
; #define PG8_WAIT_L(n) asm volatile("s_waitcnt lgkmcnt(" #n ")" ::: "memory")
; #define PG8_BAR __builtin_amdgcn_s_barrier()
; #define PG8_SCHED __builtin_amdgcn_sched_barrier(0)
; template <class Epi>
; __device__ __forceinline__ void gemm_phase(LAS unsigned char* lds, const Gemm g, const StaticOrder& S, const Epi& E) {
;     ...
;             PG8_LDA(At, 1, 1); PG8_STAGE(PG8_SB(1, 0), b3, voffB); PG8_STAGE(PG8_SB(1, 1), b3 + hstepB, voffB); PG8_STAGE(PG8_SA(1, 0), a3, voffA);
;             PG8_WAIT_V(8); PG8_WAIT_L(0); PG8_BAR; PG8_MMA(1, 0, At, B0); PG8_MMA(1, 1, At, B1); PG8_BAR; PG8_SCHED;
	s_add_i32 s0, s50, s28
	v_lshl_add_u64 v[224:225], v[224:225], 0, s[14:15]
	s_mov_b32 m0, s0
	ds_read_b128 v[188:191], v154 offset:49152
	ds_read_b128 v[192:195], v154 offset:50176
	ds_read_b128 v[196:199], v154 offset:51200
	ds_read_b128 v[200:203], v154 offset:52224
	ds_read_b128 v[208:211], v154 offset:53248
	ds_read_b128 v[212:215], v154 offset:54272
	ds_read_b128 v[216:219], v154 offset:55296
	ds_read_b128 v[220:223], v154 offset:56320
	global_load_lds_dwordx4 v[224:225], off
	s_add_i32 m0, s0, 0x2000
	s_add_u32 s0, s22, 0x18080
	v_lshl_add_u64 v[224:225], v[226:227], 0, s[14:15]
	s_addc_u32 s1, s23, 0
	s_add_i32 s22, s51, s28
	global_load_lds_dwordx4 v[224:225], off
	v_lshl_add_u64 v[224:225], s[0:1], 0, v[130:131]
	s_mov_b32 m0, s22
	s_nop 0
	global_load_lds_dwordx4 v[224:225], off
	v_lshl_add_u64 v[224:225], s[0:1], 0, v[134:135]
	s_add_i32 m0, s22, 0x2000
	s_nop 0
	global_load_lds_dwordx4 v[224:225], off
	v_lshl_add_u64 v[224:225], v[230:231], 0, s[14:15]
	s_mov_b32 m0, s38
	s_nop 0
	global_load_lds_dwordx4 v[224:225], off
	v_lshl_add_u64 v[224:225], v[232:233], 0, s[14:15]
	s_mov_b32 m0, s39
	s_nop 0
	global_load_lds_dwordx4 v[224:225], off
	s_waitcnt vmcnt(8) lgkmcnt(0)
	s_barrier
	s_setprio 1
	v_mfma_f32_16x16x32_bf16 v[60:63], v[156:159], v[188:191], v[60:63]
	v_mfma_f32_16x16x32_bf16 v[60:63], v[160:163], v[192:195], v[60:63]
	v_mfma_f32_16x16x32_bf16 v[56:59], v[168:171], v[192:195], v[56:59]
	v_mfma_f32_16x16x32_bf16 v[56:59], v[164:167], v[188:191], v[56:59]
	v_mfma_f32_16x16x32_bf16 v[52:55], v[172:175], v[188:191], v[52:55]
	v_mfma_f32_16x16x32_bf16 v[52:55], v[176:179], v[192:195], v[52:55]
	v_mfma_f32_16x16x32_bf16 v[48:51], v[184:187], v[192:195], v[48:51]
	v_mfma_f32_16x16x32_bf16 v[48:51], v[180:183], v[188:191], v[48:51]
	v_mfma_f32_16x16x32_bf16 v[32:35], v[180:183], v[196:199], v[32:35]
	v_mfma_f32_16x16x32_bf16 v[32:35], v[184:187], v[200:203], v[32:35]
	v_mfma_f32_16x16x32_bf16 v[36:39], v[176:179], v[200:203], v[36:39]
	v_mfma_f32_16x16x32_bf16 v[36:39], v[172:175], v[196:199], v[36:39]
	v_mfma_f32_16x16x32_bf16 v[40:43], v[164:167], v[196:199], v[40:43]
	v_mfma_f32_16x16x32_bf16 v[40:43], v[168:171], v[200:203], v[40:43]
	v_mfma_f32_16x16x32_bf16 v[44:47], v[160:163], v[200:203], v[44:47]
	v_mfma_f32_16x16x32_bf16 v[44:47], v[156:159], v[196:199], v[44:47]
	s_setprio 0
	s_setprio 1
	v_mfma_f32_16x16x32_bf16 v[28:31], v[156:159], v[208:211], v[28:31]
	v_mfma_f32_16x16x32_bf16 v[28:31], v[160:163], v[212:215], v[28:31]
	v_mfma_f32_16x16x32_bf16 v[24:27], v[168:171], v[212:215], v[24:27]
	v_mfma_f32_16x16x32_bf16 v[24:27], v[164:167], v[208:211], v[24:27]
	v_mfma_f32_16x16x32_bf16 v[20:23], v[172:175], v[208:211], v[20:23]
	v_mfma_f32_16x16x32_bf16 v[20:23], v[176:179], v[212:215], v[20:23]
	v_mfma_f32_16x16x32_bf16 v[16:19], v[184:187], v[212:215], v[16:19]
	v_mfma_f32_16x16x32_bf16 v[16:19], v[180:183], v[208:211], v[16:19]
	v_mfma_f32_16x16x32_bf16 v[0:3], v[180:183], v[216:219], v[0:3]
	v_mfma_f32_16x16x32_bf16 v[0:3], v[184:187], v[220:223], v[0:3]
	v_mfma_f32_16x16x32_bf16 v[4:7], v[176:179], v[220:223], v[4:7]
	v_mfma_f32_16x16x32_bf16 v[4:7], v[172:175], v[216:219], v[4:7]
	v_mfma_f32_16x16x32_bf16 v[8:11], v[164:167], v[216:219], v[8:11]
	v_mfma_f32_16x16x32_bf16 v[8:11], v[168:171], v[220:223], v[8:11]
	v_mfma_f32_16x16x32_bf16 v[12:15], v[160:163], v[220:223], v[12:15]
	v_mfma_f32_16x16x32_bf16 v[12:15], v[156:159], v[216:219], v[12:15]
	s_setprio 0
	s_barrier
	s_add_u32 s47, s47, 0x100
	s_addc_u32 s48, s48, 0
	s_cmp_ge_i32 s49, s36
	s_mov_b64 s[0:1], s[4:5]
	s_mov_b32 s22, s49
	s_cbranch_scc0 .LBB0_834

; #define PG8_STAGE(bufoff, gbase, voff) do { _Pragma("unroll") for (int _i = 0; _i < 2; ++_i) \
;         __builtin_amdgcn_global_load_lds((const unsigned*)((const char*)(gbase) + (voff)[_i]), (LAS unsigned*)(lds + (bufoff) + ldsw + _i * 8192), 16, 0, 0); } while (0)
; #define PG8_LDA(dst, b, h) do { _Pragma("unroll") for (int m = 0; m < 4; ++m) _Pragma("unroll") for (int k = 0; k < 2; ++k) dst[m][k] = *(const LAS bf16x8*)(lds + PG8_SA(b, h) + aoff + m * 2048 + k * 1024); } while (0)
; #define PG8_LDB(dst, b, h) do { _Pragma("unroll") for (int n = 0; n < 2; ++n) _Pragma("unroll") for (int k = 0; k < 2; ++k) dst[n][k] = *(const LAS bf16x8*)(lds + PG8_SB(b, h) + boff + n * 2048 + k * 1024); } while (0)
; #define PG8_MMA(ai, bj, At, Bt) do { __builtin_amdgcn_s_setprio(1); _Pragma("unroll") for (int m = 0; m < 4; ++m) _Pragma("unroll") for (int n = 0; n < 2; ++n) _Pragma("unroll") for (int k = 0; k < 2; ++k) \
;         acc[ai][bj][m][n] = __builtin_amdgcn_mfma_f32_16x16x32_bf16(Bt[n][k], At[m][k], acc[ai][bj][m][n], 0, 0, 0); __builtin_amdgcn_s_setprio(0); } while (0)
; #define PG8_WAIT_V(n) asm volatile("s_waitcnt vmcnt(" #n ")" ::: "memory")
; #define PG8_WAIT_L(n) asm volatile("s_waitcnt lgkmcnt(" #n ")" ::: "memory")
; #define PG8_BAR __builtin_amdgcn_s_barrier()
; #define PG8_SCHED __builtin_amdgcn_sched_barrier(0)
; template <class Epi>
; __device__ __forceinline__ void gemm_phase(LAS unsigned char* lds, const Gemm g, const StaticOrder& S, const Epi& E) {
;     ...
;             PG8_LDB(B0, 0, 0); PG8_LDB(B1, 0, 1); PG8_SCHED; PG8_LDA(At, 0, 0); PG8_STAGE(PG8_SA(1, 1), a1 + hstepA, voffA);
;             PG8_WAIT_V(8); PG8_WAIT_L(0); PG8_BAR; PG8_MMA(0, 0, At, B0); PG8_MMA(0, 1, At, B1); PG8_BAR; PG8_SCHED;
;             PG8_LDA(At, 0, 1); PG8_STAGE(PG8_SB(0, 0), b2, voffB); PG8_STAGE(PG8_SB(0, 1), b2 + hstepB, voffB); PG8_STAGE(PG8_SA(0, 0), a2, voffA);
;             PG8_WAIT_V(8); PG8_WAIT_L(0); PG8_BAR; PG8_MMA(1, 0, At, B0); PG8_MMA(1, 1, At, B1); PG8_BAR; PG8_SCHED;
.LBB0_912:
	ds_read_b128 v[96:99], v230
	ds_read_b128 v[100:103], v230 offset:1024
	ds_read_b128 v[104:107], v230 offset:2048
	ds_read_b128 v[116:119], v230 offset:3072
	ds_read_b128 v[120:123], v231
	ds_read_b128 v[124:127], v231 offset:1024
	ds_read_b128 v[136:139], v231 offset:2048
	ds_read_b128 v[148:151], v231 offset:3072
	s_add_i32 s56, s24, 2
	s_add_u32 s25, s4, 0xfffc0080
	s_addc_u32 s26, s5, -1
	s_cmp_eq_u32 s44, s24
	s_cselect_b32 s24, s53, s54
	s_cselect_b32 s27, s17, s26
	s_cselect_b32 s26, s19, s25
	s_cselect_b32 s25, s33, s55
	v_lshl_add_u64 v[192:193], s[4:5], 0, v[220:221]
	s_add_i32 m0, s31, 0xc000
	ds_read_b128 v[160:163], v232
	ds_read_b128 v[164:167], v232 offset:1024
	ds_read_b128 v[168:171], v232 offset:2048
	ds_read_b128 v[172:175], v232 offset:3072
	ds_read_b128 v[176:179], v232 offset:4096
	ds_read_b128 v[180:183], v232 offset:5120
	ds_read_b128 v[184:187], v232 offset:6144
	ds_read_b128 v[188:191], v232 offset:7168
	global_load_lds_dwordx4 v[192:193], off
	v_lshl_add_u64 v[192:193], s[4:5], 0, v[222:223]
	s_add_i32 m0, s31, 0xe000
	s_nop 0
	global_load_lds_dwordx4 v[192:193], off
	s_waitcnt vmcnt(8) lgkmcnt(0)
	s_barrier
	s_setprio 1
	v_mfma_f32_16x16x32_bf16 v[156:159], v[96:99], v[160:163], v[156:159]
	v_mfma_f32_16x16x32_bf16 v[156:159], v[100:103], v[164:167], v[156:159]
	v_mfma_f32_16x16x32_bf16 v[152:155], v[116:119], v[164:167], v[152:155]
	v_mfma_f32_16x16x32_bf16 v[152:155], v[104:107], v[160:163], v[152:155]
	v_mfma_f32_16x16x32_bf16 v[144:147], v[120:123], v[160:163], v[144:147]
	v_mfma_f32_16x16x32_bf16 v[144:147], v[124:127], v[164:167], v[144:147]
	v_mfma_f32_16x16x32_bf16 v[140:143], v[148:151], v[164:167], v[140:143]
	v_mfma_f32_16x16x32_bf16 v[140:143], v[136:139], v[160:163], v[140:143]
	v_mfma_f32_16x16x32_bf16 v[108:111], v[136:139], v[168:171], v[108:111]
	v_mfma_f32_16x16x32_bf16 v[108:111], v[148:151], v[172:175], v[108:111]
	v_mfma_f32_16x16x32_bf16 v[112:115], v[124:127], v[172:175], v[112:115]
	v_mfma_f32_16x16x32_bf16 v[112:115], v[120:123], v[168:171], v[112:115]
	v_mfma_f32_16x16x32_bf16 v[128:131], v[104:107], v[168:171], v[128:131]
	v_mfma_f32_16x16x32_bf16 v[128:131], v[116:119], v[172:175], v[128:131]
	v_mfma_f32_16x16x32_bf16 v[132:135], v[100:103], v[172:175], v[132:135]
	v_mfma_f32_16x16x32_bf16 v[132:135], v[96:99], v[168:171], v[132:135]
	s_setprio 0
	s_setprio 1
	v_mfma_f32_16x16x32_bf16 v[92:95], v[96:99], v[176:179], v[92:95]
	v_mfma_f32_16x16x32_bf16 v[92:95], v[100:103], v[180:183], v[92:95]
	v_mfma_f32_16x16x32_bf16 v[88:91], v[116:119], v[180:183], v[88:91]
	v_mfma_f32_16x16x32_bf16 v[88:91], v[104:107], v[176:179], v[88:91]
	v_mfma_f32_16x16x32_bf16 v[84:87], v[120:123], v[176:179], v[84:87]
	v_mfma_f32_16x16x32_bf16 v[84:87], v[124:127], v[180:183], v[84:87]
	v_mfma_f32_16x16x32_bf16 v[80:83], v[148:151], v[180:183], v[80:83]
	v_mfma_f32_16x16x32_bf16 v[80:83], v[136:139], v[176:179], v[80:83]
	v_mfma_f32_16x16x32_bf16 v[64:67], v[136:139], v[184:187], v[64:67]
	v_mfma_f32_16x16x32_bf16 v[64:67], v[148:151], v[188:191], v[64:67]
	v_mfma_f32_16x16x32_bf16 v[68:71], v[124:127], v[188:191], v[68:71]
	v_mfma_f32_16x16x32_bf16 v[68:71], v[120:123], v[184:187], v[68:71]
	v_mfma_f32_16x16x32_bf16 v[72:75], v[104:107], v[184:187], v[72:75]
	v_mfma_f32_16x16x32_bf16 v[72:75], v[116:119], v[188:191], v[72:75]
	v_mfma_f32_16x16x32_bf16 v[76:79], v[100:103], v[188:191], v[76:79]
	v_mfma_f32_16x16x32_bf16 v[76:79], v[96:99], v[184:187], v[76:79]
	s_setprio 0
	s_barrier
	s_add_i32 s57, s47, s30
	v_lshl_add_u64 v[192:193], s[24:25], 0, v[210:211]
	s_mov_b32 m0, s57
	ds_read_b128 v[160:163], v232 offset:16384
	ds_read_b128 v[164:167], v232 offset:17408
	ds_read_b128 v[168:171], v232 offset:18432
	ds_read_b128 v[172:175], v232 offset:19456
	ds_read_b128 v[176:179], v232 offset:20480
	ds_read_b128 v[180:183], v232 offset:21504
	ds_read_b128 v[184:187], v232 offset:22528
	ds_read_b128 v[188:191], v232 offset:23552
	global_load_lds_dwordx4 v[192:193], off
	s_add_i32 m0, s57, 0x2000
	s_add_u32 s58, s24, 0x40000
	v_lshl_add_u64 v[194:195], s[24:25], 0, v[214:215]
	s_addc_u32 s59, s25, 0
	s_add_i32 s57, s48, s30
	global_load_lds_dwordx4 v[194:195], off
	v_lshl_add_u64 v[196:197], s[58:59], 0, v[210:211]
	s_mov_b32 m0, s57
	v_lshl_add_u64 v[198:199], s[26:27], 0, v[212:213]
	global_load_lds_dwordx4 v[196:197], off
	v_lshl_add_u64 v[196:197], s[58:59], 0, v[214:215]
	s_add_i32 m0, s57, 0x2000
	s_nop 0
	global_load_lds_dwordx4 v[196:197], off
	v_lshl_add_u64 v[196:197], s[26:27], 0, v[208:209]
	s_mov_b32 m0, s31
	s_nop 0
	global_load_lds_dwordx4 v[196:197], off
	s_mov_b32 m0, s34
	s_nop 0
	global_load_lds_dwordx4 v[198:199], off
	s_waitcnt vmcnt(8) lgkmcnt(0)
	s_barrier
; #define PG8_STAGE(bufoff, gbase, voff) do { _Pragma("unroll") for (int _i = 0; _i < 2; ++_i) \
;         __builtin_amdgcn_global_load_lds((const unsigned*)((const char*)(gbase) + (voff)[_i]), (LAS unsigned*)(lds + (bufoff) + ldsw + _i * 8192), 16, 0, 0); } while (0)
; #define PG8_LDA(dst, b, h) do { _Pragma("unroll") for (int m = 0; m < 4; ++m) _Pragma("unroll") for (int k = 0; k < 2; ++k) dst[m][k] = *(const LAS bf16x8*)(lds + PG8_SA(b, h) + aoff + m * 2048 + k * 1024); } while (0)
; #define PG8_LDB(dst, b, h) do { _Pragma("unroll") for (int n = 0; n < 2; ++n) _Pragma("unroll") for (int k = 0; k < 2; ++k) dst[n][k] = *(const LAS bf16x8*)(lds + PG8_SB(b, h) + boff + n * 2048 + k * 1024); } while (0)
; #define PG8_MMA(ai, bj, At, Bt) do { __builtin_amdgcn_s_setprio(1); _Pragma("unroll") for (int m = 0; m < 4; ++m) _Pragma("unroll") for (int n = 0; n < 2; ++n) _Pragma("unroll") for (int k = 0; k < 2; ++k) \
;         acc[ai][bj][m][n] = __builtin_amdgcn_mfma_f32_16x16x32_bf16(Bt[n][k], At[m][k], acc[ai][bj][m][n], 0, 0, 0); __builtin_amdgcn_s_setprio(0); } while (0)
; #define PG8_WAIT_V(n) asm volatile("s_waitcnt vmcnt(" #n ")" ::: "memory")
; #define PG8_WAIT_L(n) asm volatile("s_waitcnt lgkmcnt(" #n ")" ::: "memory")
; #define PG8_BAR __builtin_amdgcn_s_barrier()
; #define PG8_SCHED __builtin_amdgcn_sched_barrier(0)
; template <class Epi>
; __device__ __forceinline__ void gemm_phase(LAS unsigned char* lds, const Gemm g, const StaticOrder& S, const Epi& E) {
;     ...
;             PG8_WAIT_V(8); PG8_WAIT_L(0); PG8_BAR; PG8_MMA(1, 0, At, B0); PG8_MMA(1, 1, At, B1); PG8_BAR; PG8_SCHED;
;             PG8_LDB(B0, 1, 0); PG8_LDB(B1, 1, 1); PG8_SCHED; PG8_LDA(At, 1, 0); PG8_STAGE(PG8_SA(0, 1), a2 + hstepA, voffA);
;             PG8_WAIT_V(8); PG8_WAIT_L(0); PG8_BAR; PG8_MMA(0, 0, At, B0); PG8_MMA(0, 1, At, B1); PG8_BAR; PG8_SCHED;
	s_setprio 1
	v_mfma_f32_16x16x32_bf16 v[60:63], v[96:99], v[160:163], v[60:63]
	v_mfma_f32_16x16x32_bf16 v[60:63], v[100:103], v[164:167], v[60:63]
	v_mfma_f32_16x16x32_bf16 v[56:59], v[116:119], v[164:167], v[56:59]
	v_mfma_f32_16x16x32_bf16 v[56:59], v[104:107], v[160:163], v[56:59]
	v_mfma_f32_16x16x32_bf16 v[52:55], v[120:123], v[160:163], v[52:55]
	v_mfma_f32_16x16x32_bf16 v[52:55], v[124:127], v[164:167], v[52:55]
	v_mfma_f32_16x16x32_bf16 v[48:51], v[148:151], v[164:167], v[48:51]
	v_mfma_f32_16x16x32_bf16 v[48:51], v[136:139], v[160:163], v[48:51]
	v_mfma_f32_16x16x32_bf16 v[32:35], v[136:139], v[168:171], v[32:35]
	v_mfma_f32_16x16x32_bf16 v[32:35], v[148:151], v[172:175], v[32:35]
	v_mfma_f32_16x16x32_bf16 v[36:39], v[124:127], v[172:175], v[36:39]
	v_mfma_f32_16x16x32_bf16 v[36:39], v[120:123], v[168:171], v[36:39]
	v_mfma_f32_16x16x32_bf16 v[40:43], v[104:107], v[168:171], v[40:43]
	v_mfma_f32_16x16x32_bf16 v[40:43], v[116:119], v[172:175], v[40:43]
	v_mfma_f32_16x16x32_bf16 v[44:47], v[100:103], v[172:175], v[44:47]
	v_mfma_f32_16x16x32_bf16 v[44:47], v[96:99], v[168:171], v[44:47]
	s_setprio 0
	s_setprio 1
	v_mfma_f32_16x16x32_bf16 v[28:31], v[96:99], v[176:179], v[28:31]
	v_mfma_f32_16x16x32_bf16 v[28:31], v[100:103], v[180:183], v[28:31]
	v_mfma_f32_16x16x32_bf16 v[24:27], v[116:119], v[180:183], v[24:27]
	v_mfma_f32_16x16x32_bf16 v[24:27], v[104:107], v[176:179], v[24:27]
	v_mfma_f32_16x16x32_bf16 v[20:23], v[120:123], v[176:179], v[20:23]
	v_mfma_f32_16x16x32_bf16 v[20:23], v[124:127], v[180:183], v[20:23]
	v_mfma_f32_16x16x32_bf16 v[16:19], v[148:151], v[180:183], v[16:19]
	v_mfma_f32_16x16x32_bf16 v[16:19], v[136:139], v[176:179], v[16:19]
	v_mfma_f32_16x16x32_bf16 v[0:3], v[136:139], v[184:187], v[0:3]
	v_mfma_f32_16x16x32_bf16 v[0:3], v[148:151], v[188:191], v[0:3]
	v_mfma_f32_16x16x32_bf16 v[4:7], v[124:127], v[188:191], v[4:7]
	v_mfma_f32_16x16x32_bf16 v[4:7], v[120:123], v[184:187], v[4:7]
	v_mfma_f32_16x16x32_bf16 v[8:11], v[104:107], v[184:187], v[8:11]
	v_mfma_f32_16x16x32_bf16 v[8:11], v[116:119], v[188:191], v[8:11]
	v_mfma_f32_16x16x32_bf16 v[12:15], v[100:103], v[188:191], v[12:15]
	v_mfma_f32_16x16x32_bf16 v[12:15], v[96:99], v[184:187], v[12:15]
	s_setprio 0
	s_barrier
	s_add_i32 s57, 0, 0x18000
	s_add_i32 s58, 0, 0x1c000
	v_add_u32_e32 v116, s57, v229
	v_add_u32_e32 v148, s58, v229
	ds_read_b128 v[96:99], v116
	ds_read_b128 v[100:103], v116 offset:1024
	ds_read_b128 v[104:107], v116 offset:2048
	ds_read_b128 v[116:119], v116 offset:3072
	ds_read_b128 v[120:123], v148
	ds_read_b128 v[124:127], v148 offset:1024
	ds_read_b128 v[136:139], v148 offset:2048
	ds_read_b128 v[148:151], v148 offset:3072
	s_add_u32 s26, s26, 0x40000
	s_addc_u32 s27, s27, 0
	s_mov_b32 m0, s35
	v_lshl_add_u64 v[200:201], s[26:27], 0, v[208:209]
	ds_read_b128 v[160:163], v232 offset:32768
	ds_read_b128 v[164:167], v232 offset:33792
	ds_read_b128 v[168:171], v232 offset:34816
	ds_read_b128 v[172:175], v232 offset:35840
	ds_read_b128 v[176:179], v232 offset:36864
	ds_read_b128 v[180:183], v232 offset:37888
	ds_read_b128 v[184:187], v232 offset:38912
	ds_read_b128 v[188:191], v232 offset:39936
	global_load_lds_dwordx4 v[200:201], off
	v_lshl_add_u64 v[200:201], s[26:27], 0, v[212:213]
	s_mov_b32 m0, s36
	s_nop 0
	global_load_lds_dwordx4 v[200:201], off
	s_waitcnt vmcnt(8) lgkmcnt(0)
	s_barrier
	s_setprio 1
	v_mfma_f32_16x16x32_bf16 v[156:159], v[96:99], v[160:163], v[156:159]
	v_mfma_f32_16x16x32_bf16 v[156:159], v[100:103], v[164:167], v[156:159]
	v_mfma_f32_16x16x32_bf16 v[152:155], v[116:119], v[164:167], v[152:155]
	v_mfma_f32_16x16x32_bf16 v[152:155], v[104:107], v[160:163], v[152:155]
	v_mfma_f32_16x16x32_bf16 v[144:147], v[120:123], v[160:163], v[144:147]
	v_mfma_f32_16x16x32_bf16 v[144:147], v[124:127], v[164:167], v[144:147]
	v_mfma_f32_16x16x32_bf16 v[140:143], v[148:151], v[164:167], v[140:143]
	v_mfma_f32_16x16x32_bf16 v[140:143], v[136:139], v[160:163], v[140:143]
	v_mfma_f32_16x16x32_bf16 v[108:111], v[136:139], v[168:171], v[108:111]
	v_mfma_f32_16x16x32_bf16 v[108:111], v[148:151], v[172:175], v[108:111]
	v_mfma_f32_16x16x32_bf16 v[112:115], v[124:127], v[172:175], v[112:115]
	v_mfma_f32_16x16x32_bf16 v[112:115], v[120:123], v[168:171], v[112:115]
	v_mfma_f32_16x16x32_bf16 v[128:131], v[104:107], v[168:171], v[128:131]
	v_mfma_f32_16x16x32_bf16 v[128:131], v[116:119], v[172:175], v[128:131]
	v_mfma_f32_16x16x32_bf16 v[132:135], v[100:103], v[172:175], v[132:135]
	v_mfma_f32_16x16x32_bf16 v[132:135], v[96:99], v[168:171], v[132:135]
	s_setprio 0
	s_setprio 1
	v_mfma_f32_16x16x32_bf16 v[92:95], v[96:99], v[176:179], v[92:95]
	v_mfma_f32_16x16x32_bf16 v[92:95], v[100:103], v[180:183], v[92:95]
	v_mfma_f32_16x16x32_bf16 v[88:91], v[116:119], v[180:183], v[88:91]
	v_mfma_f32_16x16x32_bf16 v[88:91], v[104:107], v[176:179], v[88:91]
	v_mfma_f32_16x16x32_bf16 v[84:87], v[120:123], v[176:179], v[84:87]
	v_mfma_f32_16x16x32_bf16 v[84:87], v[124:127], v[180:183], v[84:87]
	v_mfma_f32_16x16x32_bf16 v[80:83], v[148:151], v[180:183], v[80:83]
	v_mfma_f32_16x16x32_bf16 v[80:83], v[136:139], v[176:179], v[80:83]
	v_mfma_f32_16x16x32_bf16 v[64:67], v[136:139], v[184:187], v[64:67]
	v_mfma_f32_16x16x32_bf16 v[64:67], v[148:151], v[188:191], v[64:67]
	v_mfma_f32_16x16x32_bf16 v[68:71], v[124:127], v[188:191], v[68:71]
	v_mfma_f32_16x16x32_bf16 v[68:71], v[120:123], v[184:187], v[68:71]
	v_mfma_f32_16x16x32_bf16 v[72:75], v[104:107], v[184:187], v[72:75]
	v_mfma_f32_16x16x32_bf16 v[72:75], v[116:119], v[188:191], v[72:75]
	v_mfma_f32_16x16x32_bf16 v[76:79], v[100:103], v[188:191], v[76:79]
	v_mfma_f32_16x16x32_bf16 v[76:79], v[96:99], v[184:187], v[76:79]
	s_setprio 0
	s_barrier
; #define PG8_STAGE(bufoff, gbase, voff) do { _Pragma("unroll") for (int _i = 0; _i < 2; ++_i) \
;         __builtin_amdgcn_global_load_lds((const unsigned*)((const char*)(gbase) + (voff)[_i]), (LAS unsigned*)(lds + (bufoff) + ldsw + _i * 8192), 16, 0, 0); } while (0)
; #define PG8_LDA(dst, b, h) do { _Pragma("unroll") for (int m = 0; m < 4; ++m) _Pragma("unroll") for (int k = 0; k < 2; ++k) dst[m][k] = *(const LAS bf16x8*)(lds + PG8_SA(b, h) + aoff + m * 2048 + k * 1024); } while (0)
; #define PG8_MMA(ai, bj, At, Bt) do { __builtin_amdgcn_s_setprio(1); _Pragma("unroll") for (int m = 0; m < 4; ++m) _Pragma("unroll") for (int n = 0; n < 2; ++n) _Pragma("unroll") for (int k = 0; k < 2; ++k) \
;         acc[ai][bj][m][n] = __builtin_amdgcn_mfma_f32_16x16x32_bf16(Bt[n][k], At[m][k], acc[ai][bj][m][n], 0, 0, 0); __builtin_amdgcn_s_setprio(0); } while (0)
; #define PG8_WAIT_V(n) asm volatile("s_waitcnt vmcnt(" #n ")" ::: "memory")
; #define PG8_WAIT_L(n) asm volatile("s_waitcnt lgkmcnt(" #n ")" ::: "memory")
; #define PG8_BAR __builtin_amdgcn_s_barrier()
; #define PG8_SCHED __builtin_amdgcn_sched_barrier(0)
; template <class Epi>
; __device__ __forceinline__ void gemm_phase(LAS unsigned char* lds, const Gemm g, const StaticOrder& S, const Epi& E) {
;     ...
;             PG8_LDA(At, 1, 1); PG8_STAGE(PG8_SB(1, 0), b3, voffB); PG8_STAGE(PG8_SB(1, 1), b3 + hstepB, voffB); PG8_STAGE(PG8_SA(1, 0), a3, voffA);
;             PG8_WAIT_V(8); PG8_WAIT_L(0); PG8_BAR; PG8_MMA(1, 0, At, B0); PG8_MMA(1, 1, At, B1); PG8_BAR; PG8_SCHED;
	s_add_i32 s26, s57, s30
	v_lshl_add_u64 v[192:193], v[192:193], 0, s[10:11]
	s_mov_b32 m0, s26
	ds_read_b128 v[160:163], v232 offset:49152
	ds_read_b128 v[164:167], v232 offset:50176
	ds_read_b128 v[168:171], v232 offset:51200
	ds_read_b128 v[172:175], v232 offset:52224
	ds_read_b128 v[176:179], v232 offset:53248
	ds_read_b128 v[180:183], v232 offset:54272
	ds_read_b128 v[184:187], v232 offset:55296
	ds_read_b128 v[188:191], v232 offset:56320
	global_load_lds_dwordx4 v[192:193], off
	s_add_i32 m0, s26, 0x2000
	s_add_u32 s24, s24, 0x40080
	v_lshl_add_u64 v[192:193], v[194:195], 0, s[10:11]
	s_addc_u32 s25, s25, 0
	s_add_i32 s26, s58, s30
	global_load_lds_dwordx4 v[192:193], off
	v_lshl_add_u64 v[192:193], s[24:25], 0, v[210:211]
	s_mov_b32 m0, s26
	s_nop 0
	global_load_lds_dwordx4 v[192:193], off
	v_lshl_add_u64 v[192:193], s[24:25], 0, v[214:215]
	s_add_i32 m0, s26, 0x2000
	s_nop 0
	global_load_lds_dwordx4 v[192:193], off
	v_lshl_add_u64 v[192:193], v[196:197], 0, s[10:11]
	s_mov_b32 m0, s40
	s_nop 0
	global_load_lds_dwordx4 v[192:193], off
	v_lshl_add_u64 v[192:193], v[198:199], 0, s[10:11]
	s_mov_b32 m0, s41
	s_nop 0
	global_load_lds_dwordx4 v[192:193], off
	s_waitcnt vmcnt(8) lgkmcnt(0)
	s_barrier
	s_setprio 1
	v_mfma_f32_16x16x32_bf16 v[60:63], v[96:99], v[160:163], v[60:63]
	v_mfma_f32_16x16x32_bf16 v[60:63], v[100:103], v[164:167], v[60:63]
	v_mfma_f32_16x16x32_bf16 v[56:59], v[116:119], v[164:167], v[56:59]
	v_mfma_f32_16x16x32_bf16 v[56:59], v[104:107], v[160:163], v[56:59]
	v_mfma_f32_16x16x32_bf16 v[52:55], v[120:123], v[160:163], v[52:55]
	v_mfma_f32_16x16x32_bf16 v[52:55], v[124:127], v[164:167], v[52:55]
	v_mfma_f32_16x16x32_bf16 v[48:51], v[148:151], v[164:167], v[48:51]
	v_mfma_f32_16x16x32_bf16 v[48:51], v[136:139], v[160:163], v[48:51]
	v_mfma_f32_16x16x32_bf16 v[32:35], v[136:139], v[168:171], v[32:35]
	v_mfma_f32_16x16x32_bf16 v[32:35], v[148:151], v[172:175], v[32:35]
	v_mfma_f32_16x16x32_bf16 v[36:39], v[124:127], v[172:175], v[36:39]
	v_mfma_f32_16x16x32_bf16 v[36:39], v[120:123], v[168:171], v[36:39]
	v_mfma_f32_16x16x32_bf16 v[40:43], v[104:107], v[168:171], v[40:43]
	v_mfma_f32_16x16x32_bf16 v[40:43], v[116:119], v[172:175], v[40:43]
	v_mfma_f32_16x16x32_bf16 v[44:47], v[100:103], v[172:175], v[44:47]
	v_mfma_f32_16x16x32_bf16 v[44:47], v[96:99], v[168:171], v[44:47]
	s_setprio 0
	s_setprio 1
	v_mfma_f32_16x16x32_bf16 v[28:31], v[96:99], v[176:179], v[28:31]
	v_mfma_f32_16x16x32_bf16 v[28:31], v[100:103], v[180:183], v[28:31]
	v_mfma_f32_16x16x32_bf16 v[24:27], v[116:119], v[180:183], v[24:27]
	v_mfma_f32_16x16x32_bf16 v[24:27], v[104:107], v[176:179], v[24:27]
	v_mfma_f32_16x16x32_bf16 v[20:23], v[120:123], v[176:179], v[20:23]
	v_mfma_f32_16x16x32_bf16 v[20:23], v[124:127], v[180:183], v[20:23]
	v_mfma_f32_16x16x32_bf16 v[16:19], v[148:151], v[180:183], v[16:19]
	v_mfma_f32_16x16x32_bf16 v[16:19], v[136:139], v[176:179], v[16:19]
	v_mfma_f32_16x16x32_bf16 v[0:3], v[136:139], v[184:187], v[0:3]
	v_mfma_f32_16x16x32_bf16 v[0:3], v[148:151], v[188:191], v[0:3]
	v_mfma_f32_16x16x32_bf16 v[4:7], v[124:127], v[188:191], v[4:7]
	v_mfma_f32_16x16x32_bf16 v[4:7], v[120:123], v[184:187], v[4:7]
	v_mfma_f32_16x16x32_bf16 v[8:11], v[104:107], v[184:187], v[8:11]
	v_mfma_f32_16x16x32_bf16 v[8:11], v[116:119], v[188:191], v[8:11]
	v_mfma_f32_16x16x32_bf16 v[12:15], v[100:103], v[188:191], v[12:15]
	v_mfma_f32_16x16x32_bf16 v[12:15], v[96:99], v[184:187], v[12:15]
	s_setprio 0
	s_barrier
	s_add_u32 s4, s4, 0x100
	s_addc_u32 s5, s5, 0
	s_add_u32 s54, s54, 0x100
	s_addc_u32 s55, s55, 0
	s_cmp_ge_i32 s56, s39
	s_mov_b32 s24, s56
	s_cbranch_scc0 .LBB0_912

; #define PG8_STAGE(bufoff, gbase, voff) do { _Pragma("unroll") for (int _i = 0; _i < 2; ++_i) \
;         __builtin_amdgcn_global_load_lds((const unsigned*)((const char*)(gbase) + (voff)[_i]), (LAS unsigned*)(lds + (bufoff) + ldsw + _i * 8192), 16, 0, 0); } while (0)
; #define PG8_LDA(dst, b, h) do { _Pragma("unroll") for (int m = 0; m < 4; ++m) _Pragma("unroll") for (int k = 0; k < 2; ++k) dst[m][k] = *(const LAS bf16x8*)(lds + PG8_SA(b, h) + aoff + m * 2048 + k * 1024); } while (0)
; #define PG8_LDB(dst, b, h) do { _Pragma("unroll") for (int n = 0; n < 2; ++n) _Pragma("unroll") for (int k = 0; k < 2; ++k) dst[n][k] = *(const LAS bf16x8*)(lds + PG8_SB(b, h) + boff + n * 2048 + k * 1024); } while (0)
; #define PG8_MMA(ai, bj, At, Bt) do { __builtin_amdgcn_s_setprio(1); _Pragma("unroll") for (int m = 0; m < 4; ++m) _Pragma("unroll") for (int n = 0; n < 2; ++n) _Pragma("unroll") for (int k = 0; k < 2; ++k) \
;         acc[ai][bj][m][n] = __builtin_amdgcn_mfma_f32_16x16x32_bf16(Bt[n][k], At[m][k], acc[ai][bj][m][n], 0, 0, 0); __builtin_amdgcn_s_setprio(0); } while (0)
; #define PG8_WAIT_V(n) asm volatile("s_waitcnt vmcnt(" #n ")" ::: "memory")
; #define PG8_WAIT_L(n) asm volatile("s_waitcnt lgkmcnt(" #n ")" ::: "memory")
; #define PG8_BAR __builtin_amdgcn_s_barrier()
; #define PG8_SCHED __builtin_amdgcn_sched_barrier(0)
; template <class Epi>
; __device__ __forceinline__ void gemm_phase(LAS unsigned char* lds, const Gemm g, const StaticOrder& S, const Epi& E) {
;     ...
;             PG8_LDB(B0, 0, 0); PG8_LDB(B1, 0, 1); PG8_SCHED; PG8_LDA(At, 0, 0); PG8_STAGE(PG8_SA(1, 1), a1 + hstepA, voffA);
;             PG8_WAIT_V(8); PG8_WAIT_L(0); PG8_BAR; PG8_MMA(0, 0, At, B0); PG8_MMA(0, 1, At, B1); PG8_BAR; PG8_SCHED;
;             PG8_LDA(At, 0, 1); PG8_STAGE(PG8_SB(0, 0), b2, voffB); PG8_STAGE(PG8_SB(0, 1), b2 + hstepB, voffB); PG8_STAGE(PG8_SA(0, 0), a2, voffA);
;             PG8_WAIT_V(8); PG8_WAIT_L(0); PG8_BAR; PG8_MMA(1, 0, At, B0); PG8_MMA(1, 1, At, B1); PG8_BAR; PG8_SCHED;
.LBB0_1046:
	ds_read_b128 v[128:131], v185
	ds_read_b128 v[132:135], v185 offset:1024
	ds_read_b128 v[136:139], v185 offset:2048
	ds_read_b128 v[140:143], v185 offset:3072
	ds_read_b128 v[144:147], v186
	ds_read_b128 v[148:151], v186 offset:1024
	ds_read_b128 v[152:155], v186 offset:2048
	ds_read_b128 v[156:159], v186 offset:3072
	s_add_i32 s73, s46, 2
	s_add_u32 s47, s12, 0xfff80080
	s_addc_u32 s48, s13, -1
	s_cmp_eq_u32 s62, s46
	s_cselect_b32 s46, s41, s71
	s_cselect_b32 s49, s1, s48
	s_cselect_b32 s48, s33, s47
	s_cselect_b32 s47, s39, s72
	v_lshl_add_u64 v[182:183], s[12:13], 0, v[174:175]
	s_add_i32 m0, s5, 0xc000
	ds_read_b128 v[190:193], v187
	ds_read_b128 v[194:197], v187 offset:1024
	ds_read_b128 v[198:201], v187 offset:2048
	ds_read_b128 v[208:211], v187 offset:3072
	ds_read_b128 v[212:215], v187 offset:4096
	ds_read_b128 v[216:219], v187 offset:5120
	ds_read_b128 v[220:223], v187 offset:6144
	ds_read_b128 v[224:227], v187 offset:7168
	global_load_lds_dwordx4 v[182:183], off
	v_lshl_add_u64 v[182:183], s[12:13], 0, v[176:177]
	s_add_i32 m0, s5, 0xe000
	s_nop 0
	global_load_lds_dwordx4 v[182:183], off
	s_waitcnt vmcnt(8) lgkmcnt(0)
	s_barrier
	s_setprio 1
	v_mfma_f32_16x16x32_bf16 v[120:123], v[128:131], v[190:193], v[120:123]
	v_mfma_f32_16x16x32_bf16 v[120:123], v[132:135], v[194:197], v[120:123]
	v_mfma_f32_16x16x32_bf16 v[124:127], v[140:143], v[194:197], v[124:127]
	v_mfma_f32_16x16x32_bf16 v[124:127], v[136:139], v[190:193], v[124:127]
	v_mfma_f32_16x16x32_bf16 v[116:119], v[144:147], v[190:193], v[116:119]
	v_mfma_f32_16x16x32_bf16 v[116:119], v[148:151], v[194:197], v[116:119]
	v_mfma_f32_16x16x32_bf16 v[112:115], v[156:159], v[194:197], v[112:115]
	v_mfma_f32_16x16x32_bf16 v[112:115], v[152:155], v[190:193], v[112:115]
	v_mfma_f32_16x16x32_bf16 v[96:99], v[152:155], v[198:201], v[96:99]
	v_mfma_f32_16x16x32_bf16 v[96:99], v[156:159], v[208:211], v[96:99]
	v_mfma_f32_16x16x32_bf16 v[100:103], v[148:151], v[208:211], v[100:103]
	v_mfma_f32_16x16x32_bf16 v[100:103], v[144:147], v[198:201], v[100:103]
	v_mfma_f32_16x16x32_bf16 v[104:107], v[136:139], v[198:201], v[104:107]
	v_mfma_f32_16x16x32_bf16 v[104:107], v[140:143], v[208:211], v[104:107]
	v_mfma_f32_16x16x32_bf16 v[108:111], v[132:135], v[208:211], v[108:111]
	v_mfma_f32_16x16x32_bf16 v[108:111], v[128:131], v[198:201], v[108:111]
	s_setprio 0
	s_setprio 1
	v_mfma_f32_16x16x32_bf16 v[92:95], v[128:131], v[212:215], v[92:95]
	v_mfma_f32_16x16x32_bf16 v[92:95], v[132:135], v[216:219], v[92:95]
	v_mfma_f32_16x16x32_bf16 v[88:91], v[140:143], v[216:219], v[88:91]
	v_mfma_f32_16x16x32_bf16 v[88:91], v[136:139], v[212:215], v[88:91]
	v_mfma_f32_16x16x32_bf16 v[84:87], v[144:147], v[212:215], v[84:87]
	v_mfma_f32_16x16x32_bf16 v[84:87], v[148:151], v[216:219], v[84:87]
	v_mfma_f32_16x16x32_bf16 v[80:83], v[156:159], v[216:219], v[80:83]
	v_mfma_f32_16x16x32_bf16 v[80:83], v[152:155], v[212:215], v[80:83]
	v_mfma_f32_16x16x32_bf16 v[64:67], v[152:155], v[220:223], v[64:67]
	v_mfma_f32_16x16x32_bf16 v[64:67], v[156:159], v[224:227], v[64:67]
	v_mfma_f32_16x16x32_bf16 v[68:71], v[148:151], v[224:227], v[68:71]
	v_mfma_f32_16x16x32_bf16 v[68:71], v[144:147], v[220:223], v[68:71]
	v_mfma_f32_16x16x32_bf16 v[72:75], v[136:139], v[220:223], v[72:75]
	v_mfma_f32_16x16x32_bf16 v[72:75], v[140:143], v[224:227], v[72:75]
	v_mfma_f32_16x16x32_bf16 v[76:79], v[132:135], v[224:227], v[76:79]
	v_mfma_f32_16x16x32_bf16 v[76:79], v[128:131], v[220:223], v[76:79]
	s_setprio 0
	s_barrier
	s_add_i32 s76, s65, s54
	v_lshl_add_u64 v[182:183], s[46:47], 0, v[162:163]
	s_mov_b32 m0, s76
	ds_read_b128 v[190:193], v187 offset:16384
	ds_read_b128 v[194:197], v187 offset:17408
	ds_read_b128 v[198:201], v187 offset:18432
	ds_read_b128 v[208:211], v187 offset:19456
	ds_read_b128 v[212:215], v187 offset:20480
	ds_read_b128 v[216:219], v187 offset:21504
	ds_read_b128 v[220:223], v187 offset:22528
	ds_read_b128 v[224:227], v187 offset:23552
	global_load_lds_dwordx4 v[182:183], off
	s_add_i32 m0, s76, 0x2000
	s_add_u32 s76, s46, 0x80000
	v_lshl_add_u64 v[202:203], s[46:47], 0, v[166:167]
	s_addc_u32 s77, s47, 0
	s_add_i32 s78, s66, s54
	global_load_lds_dwordx4 v[202:203], off
	v_lshl_add_u64 v[230:231], s[76:77], 0, v[162:163]
	s_mov_b32 m0, s78
	v_lshl_add_u64 v[232:233], s[48:49], 0, v[164:165]
	global_load_lds_dwordx4 v[230:231], off
	v_lshl_add_u64 v[230:231], s[76:77], 0, v[166:167]
	s_add_i32 m0, s78, 0x2000
	s_nop 0
	global_load_lds_dwordx4 v[230:231], off
	v_lshl_add_u64 v[230:231], s[48:49], 0, v[160:161]
	s_mov_b32 m0, s5
	s_nop 0
	global_load_lds_dwordx4 v[230:231], off
	s_mov_b32 m0, s55
	s_nop 0
	global_load_lds_dwordx4 v[232:233], off
	s_waitcnt vmcnt(8) lgkmcnt(0)
	s_barrier
; #define PG8_STAGE(bufoff, gbase, voff) do { _Pragma("unroll") for (int _i = 0; _i < 2; ++_i) \
;         __builtin_amdgcn_global_load_lds((const unsigned*)((const char*)(gbase) + (voff)[_i]), (LAS unsigned*)(lds + (bufoff) + ldsw + _i * 8192), 16, 0, 0); } while (0)
; #define PG8_LDA(dst, b, h) do { _Pragma("unroll") for (int m = 0; m < 4; ++m) _Pragma("unroll") for (int k = 0; k < 2; ++k) dst[m][k] = *(const LAS bf16x8*)(lds + PG8_SA(b, h) + aoff + m * 2048 + k * 1024); } while (0)
; #define PG8_LDB(dst, b, h) do { _Pragma("unroll") for (int n = 0; n < 2; ++n) _Pragma("unroll") for (int k = 0; k < 2; ++k) dst[n][k] = *(const LAS bf16x8*)(lds + PG8_SB(b, h) + boff + n * 2048 + k * 1024); } while (0)
; #define PG8_MMA(ai, bj, At, Bt) do { __builtin_amdgcn_s_setprio(1); _Pragma("unroll") for (int m = 0; m < 4; ++m) _Pragma("unroll") for (int n = 0; n < 2; ++n) _Pragma("unroll") for (int k = 0; k < 2; ++k) \
;         acc[ai][bj][m][n] = __builtin_amdgcn_mfma_f32_16x16x32_bf16(Bt[n][k], At[m][k], acc[ai][bj][m][n], 0, 0, 0); __builtin_amdgcn_s_setprio(0); } while (0)
; #define PG8_WAIT_V(n) asm volatile("s_waitcnt vmcnt(" #n ")" ::: "memory")
; #define PG8_WAIT_L(n) asm volatile("s_waitcnt lgkmcnt(" #n ")" ::: "memory")
; #define PG8_BAR __builtin_amdgcn_s_barrier()
; #define PG8_SCHED __builtin_amdgcn_sched_barrier(0)
; template <class Epi>
; __device__ __forceinline__ void gemm_phase(LAS unsigned char* lds, const Gemm g, const StaticOrder& S, const Epi& E) {
;     ...
;             PG8_WAIT_V(8); PG8_WAIT_L(0); PG8_BAR; PG8_MMA(1, 0, At, B0); PG8_MMA(1, 1, At, B1); PG8_BAR; PG8_SCHED;
;             PG8_LDB(B0, 1, 0); PG8_LDB(B1, 1, 1); PG8_SCHED; PG8_LDA(At, 1, 0); PG8_STAGE(PG8_SA(0, 1), a2 + hstepA, voffA);
;             PG8_WAIT_V(8); PG8_WAIT_L(0); PG8_BAR; PG8_MMA(0, 0, At, B0); PG8_MMA(0, 1, At, B1); PG8_BAR; PG8_SCHED;
	s_setprio 1
	v_mfma_f32_16x16x32_bf16 v[60:63], v[128:131], v[190:193], v[60:63]
	v_mfma_f32_16x16x32_bf16 v[60:63], v[132:135], v[194:197], v[60:63]
	v_mfma_f32_16x16x32_bf16 v[56:59], v[140:143], v[194:197], v[56:59]
	v_mfma_f32_16x16x32_bf16 v[56:59], v[136:139], v[190:193], v[56:59]
	v_mfma_f32_16x16x32_bf16 v[52:55], v[144:147], v[190:193], v[52:55]
	v_mfma_f32_16x16x32_bf16 v[52:55], v[148:151], v[194:197], v[52:55]
	v_mfma_f32_16x16x32_bf16 v[48:51], v[156:159], v[194:197], v[48:51]
	v_mfma_f32_16x16x32_bf16 v[48:51], v[152:155], v[190:193], v[48:51]
	v_mfma_f32_16x16x32_bf16 v[32:35], v[152:155], v[198:201], v[32:35]
	v_mfma_f32_16x16x32_bf16 v[32:35], v[156:159], v[208:211], v[32:35]
	v_mfma_f32_16x16x32_bf16 v[36:39], v[148:151], v[208:211], v[36:39]
	v_mfma_f32_16x16x32_bf16 v[36:39], v[144:147], v[198:201], v[36:39]
	v_mfma_f32_16x16x32_bf16 v[40:43], v[136:139], v[198:201], v[40:43]
	v_mfma_f32_16x16x32_bf16 v[40:43], v[140:143], v[208:211], v[40:43]
	v_mfma_f32_16x16x32_bf16 v[44:47], v[132:135], v[208:211], v[44:47]
	v_mfma_f32_16x16x32_bf16 v[44:47], v[128:131], v[198:201], v[44:47]
	s_setprio 0
	s_setprio 1
	v_mfma_f32_16x16x32_bf16 v[28:31], v[128:131], v[212:215], v[28:31]
	v_mfma_f32_16x16x32_bf16 v[28:31], v[132:135], v[216:219], v[28:31]
	v_mfma_f32_16x16x32_bf16 v[24:27], v[140:143], v[216:219], v[24:27]
	v_mfma_f32_16x16x32_bf16 v[24:27], v[136:139], v[212:215], v[24:27]
	v_mfma_f32_16x16x32_bf16 v[20:23], v[144:147], v[212:215], v[20:23]
	v_mfma_f32_16x16x32_bf16 v[20:23], v[148:151], v[216:219], v[20:23]
	v_mfma_f32_16x16x32_bf16 v[16:19], v[156:159], v[216:219], v[16:19]
	v_mfma_f32_16x16x32_bf16 v[16:19], v[152:155], v[212:215], v[16:19]
	v_mfma_f32_16x16x32_bf16 v[0:3], v[152:155], v[220:223], v[0:3]
	v_mfma_f32_16x16x32_bf16 v[0:3], v[156:159], v[224:227], v[0:3]
	v_mfma_f32_16x16x32_bf16 v[4:7], v[148:151], v[224:227], v[4:7]
	v_mfma_f32_16x16x32_bf16 v[4:7], v[144:147], v[220:223], v[4:7]
	v_mfma_f32_16x16x32_bf16 v[8:11], v[136:139], v[220:223], v[8:11]
	v_mfma_f32_16x16x32_bf16 v[8:11], v[140:143], v[224:227], v[8:11]
	v_mfma_f32_16x16x32_bf16 v[12:15], v[132:135], v[224:227], v[12:15]
	v_mfma_f32_16x16x32_bf16 v[12:15], v[128:131], v[220:223], v[12:15]
	s_setprio 0
	s_barrier
	s_add_i32 s76, 0, 0x18000
	s_add_i32 s77, 0, 0x1c000
	v_add_u32_e32 v140, s76, v184
	v_add_u32_e32 v156, s77, v184
	ds_read_b128 v[128:131], v140
	ds_read_b128 v[132:135], v140 offset:1024
	ds_read_b128 v[136:139], v140 offset:2048
	ds_read_b128 v[140:143], v140 offset:3072
	ds_read_b128 v[144:147], v156
	ds_read_b128 v[148:151], v156 offset:1024
	ds_read_b128 v[152:155], v156 offset:2048
	ds_read_b128 v[156:159], v156 offset:3072
	s_add_u32 s48, s48, 0x80000
	s_addc_u32 s49, s49, 0
	s_mov_b32 m0, s56
	v_lshl_add_u64 v[234:235], s[48:49], 0, v[160:161]
	ds_read_b128 v[190:193], v187 offset:32768
	ds_read_b128 v[194:197], v187 offset:33792
	ds_read_b128 v[198:201], v187 offset:34816
	ds_read_b128 v[208:211], v187 offset:35840
	ds_read_b128 v[212:215], v187 offset:36864
	ds_read_b128 v[216:219], v187 offset:37888
	ds_read_b128 v[220:223], v187 offset:38912
	ds_read_b128 v[224:227], v187 offset:39936
	global_load_lds_dwordx4 v[234:235], off
	v_lshl_add_u64 v[234:235], s[48:49], 0, v[164:165]
	s_mov_b32 m0, s57
	s_nop 0
	global_load_lds_dwordx4 v[234:235], off
	s_waitcnt vmcnt(8) lgkmcnt(0)
	s_barrier
	s_setprio 1
	v_mfma_f32_16x16x32_bf16 v[120:123], v[128:131], v[190:193], v[120:123]
	v_mfma_f32_16x16x32_bf16 v[120:123], v[132:135], v[194:197], v[120:123]
	v_mfma_f32_16x16x32_bf16 v[124:127], v[140:143], v[194:197], v[124:127]
	v_mfma_f32_16x16x32_bf16 v[124:127], v[136:139], v[190:193], v[124:127]
	v_mfma_f32_16x16x32_bf16 v[116:119], v[144:147], v[190:193], v[116:119]
	v_mfma_f32_16x16x32_bf16 v[116:119], v[148:151], v[194:197], v[116:119]
	v_mfma_f32_16x16x32_bf16 v[112:115], v[156:159], v[194:197], v[112:115]
	v_mfma_f32_16x16x32_bf16 v[112:115], v[152:155], v[190:193], v[112:115]
	v_mfma_f32_16x16x32_bf16 v[96:99], v[152:155], v[198:201], v[96:99]
	v_mfma_f32_16x16x32_bf16 v[96:99], v[156:159], v[208:211], v[96:99]
	v_mfma_f32_16x16x32_bf16 v[100:103], v[148:151], v[208:211], v[100:103]
	v_mfma_f32_16x16x32_bf16 v[100:103], v[144:147], v[198:201], v[100:103]
	v_mfma_f32_16x16x32_bf16 v[104:107], v[136:139], v[198:201], v[104:107]
	v_mfma_f32_16x16x32_bf16 v[104:107], v[140:143], v[208:211], v[104:107]
	v_mfma_f32_16x16x32_bf16 v[108:111], v[132:135], v[208:211], v[108:111]
	v_mfma_f32_16x16x32_bf16 v[108:111], v[128:131], v[198:201], v[108:111]
	s_setprio 0
	s_setprio 1
	v_mfma_f32_16x16x32_bf16 v[92:95], v[128:131], v[212:215], v[92:95]
	v_mfma_f32_16x16x32_bf16 v[92:95], v[132:135], v[216:219], v[92:95]
	v_mfma_f32_16x16x32_bf16 v[88:91], v[140:143], v[216:219], v[88:91]
	v_mfma_f32_16x16x32_bf16 v[88:91], v[136:139], v[212:215], v[88:91]
	v_mfma_f32_16x16x32_bf16 v[84:87], v[144:147], v[212:215], v[84:87]
	v_mfma_f32_16x16x32_bf16 v[84:87], v[148:151], v[216:219], v[84:87]
	v_mfma_f32_16x16x32_bf16 v[80:83], v[156:159], v[216:219], v[80:83]
	v_mfma_f32_16x16x32_bf16 v[80:83], v[152:155], v[212:215], v[80:83]
	v_mfma_f32_16x16x32_bf16 v[64:67], v[152:155], v[220:223], v[64:67]
	v_mfma_f32_16x16x32_bf16 v[64:67], v[156:159], v[224:227], v[64:67]
	v_mfma_f32_16x16x32_bf16 v[68:71], v[148:151], v[224:227], v[68:71]
	v_mfma_f32_16x16x32_bf16 v[68:71], v[144:147], v[220:223], v[68:71]
	v_mfma_f32_16x16x32_bf16 v[72:75], v[136:139], v[220:223], v[72:75]
	v_mfma_f32_16x16x32_bf16 v[72:75], v[140:143], v[224:227], v[72:75]
	v_mfma_f32_16x16x32_bf16 v[76:79], v[132:135], v[224:227], v[76:79]
	v_mfma_f32_16x16x32_bf16 v[76:79], v[128:131], v[220:223], v[76:79]
	s_setprio 0
	s_barrier
; #define PG8_STAGE(bufoff, gbase, voff) do { _Pragma("unroll") for (int _i = 0; _i < 2; ++_i) \
;         __builtin_amdgcn_global_load_lds((const unsigned*)((const char*)(gbase) + (voff)[_i]), (LAS unsigned*)(lds + (bufoff) + ldsw + _i * 8192), 16, 0, 0); } while (0)
; #define PG8_LDA(dst, b, h) do { _Pragma("unroll") for (int m = 0; m < 4; ++m) _Pragma("unroll") for (int k = 0; k < 2; ++k) dst[m][k] = *(const LAS bf16x8*)(lds + PG8_SA(b, h) + aoff + m * 2048 + k * 1024); } while (0)
; #define PG8_MMA(ai, bj, At, Bt) do { __builtin_amdgcn_s_setprio(1); _Pragma("unroll") for (int m = 0; m < 4; ++m) _Pragma("unroll") for (int n = 0; n < 2; ++n) _Pragma("unroll") for (int k = 0; k < 2; ++k) \
;         acc[ai][bj][m][n] = __builtin_amdgcn_mfma_f32_16x16x32_bf16(Bt[n][k], At[m][k], acc[ai][bj][m][n], 0, 0, 0); __builtin_amdgcn_s_setprio(0); } while (0)
; #define PG8_WAIT_V(n) asm volatile("s_waitcnt vmcnt(" #n ")" ::: "memory")
; #define PG8_WAIT_L(n) asm volatile("s_waitcnt lgkmcnt(" #n ")" ::: "memory")
; #define PG8_BAR __builtin_amdgcn_s_barrier()
; #define PG8_SCHED __builtin_amdgcn_sched_barrier(0)
; template <class Epi>
; __device__ __forceinline__ void gemm_phase(LAS unsigned char* lds, const Gemm g, const StaticOrder& S, const Epi& E) {
;     ...
;             PG8_LDA(At, 1, 1); PG8_STAGE(PG8_SB(1, 0), b3, voffB); PG8_STAGE(PG8_SB(1, 1), b3 + hstepB, voffB); PG8_STAGE(PG8_SA(1, 0), a3, voffA);
;             PG8_WAIT_V(8); PG8_WAIT_L(0); PG8_BAR; PG8_MMA(1, 0, At, B0); PG8_MMA(1, 1, At, B1); PG8_BAR; PG8_SCHED;
	s_add_i32 s48, s76, s54
	v_lshl_add_u64 v[182:183], v[182:183], 0, s[16:17]
	s_mov_b32 m0, s48
	ds_read_b128 v[190:193], v187 offset:49152
	ds_read_b128 v[194:197], v187 offset:50176
	ds_read_b128 v[198:201], v187 offset:51200
	ds_read_b128 v[208:211], v187 offset:52224
	ds_read_b128 v[212:215], v187 offset:53248
	ds_read_b128 v[216:219], v187 offset:54272
	ds_read_b128 v[220:223], v187 offset:55296
	ds_read_b128 v[224:227], v187 offset:56320
	global_load_lds_dwordx4 v[182:183], off
	s_add_i32 m0, s48, 0x2000
	s_add_u32 s46, s46, 0x80080
	v_lshl_add_u64 v[182:183], v[202:203], 0, s[16:17]
	s_addc_u32 s47, s47, 0
	s_add_i32 s48, s77, s54
	global_load_lds_dwordx4 v[182:183], off
	v_lshl_add_u64 v[182:183], s[46:47], 0, v[162:163]
	s_mov_b32 m0, s48
	s_nop 0
	global_load_lds_dwordx4 v[182:183], off
	v_lshl_add_u64 v[182:183], s[46:47], 0, v[166:167]
	s_add_i32 m0, s48, 0x2000
	s_nop 0
	global_load_lds_dwordx4 v[182:183], off
	v_lshl_add_u64 v[182:183], v[230:231], 0, s[16:17]
	s_mov_b32 m0, s60
	s_nop 0
	global_load_lds_dwordx4 v[182:183], off
	v_lshl_add_u64 v[182:183], v[232:233], 0, s[16:17]
	s_mov_b32 m0, s61
	s_nop 0
	global_load_lds_dwordx4 v[182:183], off
	s_waitcnt vmcnt(8) lgkmcnt(0)
	s_barrier
	s_setprio 1
	v_mfma_f32_16x16x32_bf16 v[60:63], v[128:131], v[190:193], v[60:63]
	v_mfma_f32_16x16x32_bf16 v[60:63], v[132:135], v[194:197], v[60:63]
	v_mfma_f32_16x16x32_bf16 v[56:59], v[140:143], v[194:197], v[56:59]
	v_mfma_f32_16x16x32_bf16 v[56:59], v[136:139], v[190:193], v[56:59]
	v_mfma_f32_16x16x32_bf16 v[52:55], v[144:147], v[190:193], v[52:55]
	v_mfma_f32_16x16x32_bf16 v[52:55], v[148:151], v[194:197], v[52:55]
	v_mfma_f32_16x16x32_bf16 v[48:51], v[156:159], v[194:197], v[48:51]
	v_mfma_f32_16x16x32_bf16 v[48:51], v[152:155], v[190:193], v[48:51]
	v_mfma_f32_16x16x32_bf16 v[32:35], v[152:155], v[198:201], v[32:35]
	v_mfma_f32_16x16x32_bf16 v[32:35], v[156:159], v[208:211], v[32:35]
	v_mfma_f32_16x16x32_bf16 v[36:39], v[148:151], v[208:211], v[36:39]
	v_mfma_f32_16x16x32_bf16 v[36:39], v[144:147], v[198:201], v[36:39]
	v_mfma_f32_16x16x32_bf16 v[40:43], v[136:139], v[198:201], v[40:43]
	v_mfma_f32_16x16x32_bf16 v[40:43], v[140:143], v[208:211], v[40:43]
	v_mfma_f32_16x16x32_bf16 v[44:47], v[132:135], v[208:211], v[44:47]
	v_mfma_f32_16x16x32_bf16 v[44:47], v[128:131], v[198:201], v[44:47]
	s_setprio 0
	s_setprio 1
	v_mfma_f32_16x16x32_bf16 v[28:31], v[128:131], v[212:215], v[28:31]
	v_mfma_f32_16x16x32_bf16 v[28:31], v[132:135], v[216:219], v[28:31]
	v_mfma_f32_16x16x32_bf16 v[24:27], v[140:143], v[216:219], v[24:27]
	v_mfma_f32_16x16x32_bf16 v[24:27], v[136:139], v[212:215], v[24:27]
	v_mfma_f32_16x16x32_bf16 v[20:23], v[144:147], v[212:215], v[20:23]
	v_mfma_f32_16x16x32_bf16 v[20:23], v[148:151], v[216:219], v[20:23]
	v_mfma_f32_16x16x32_bf16 v[16:19], v[156:159], v[216:219], v[16:19]
	v_mfma_f32_16x16x32_bf16 v[16:19], v[152:155], v[212:215], v[16:19]
	v_mfma_f32_16x16x32_bf16 v[0:3], v[152:155], v[220:223], v[0:3]
	v_mfma_f32_16x16x32_bf16 v[0:3], v[156:159], v[224:227], v[0:3]
	v_mfma_f32_16x16x32_bf16 v[4:7], v[148:151], v[224:227], v[4:7]
	v_mfma_f32_16x16x32_bf16 v[4:7], v[144:147], v[220:223], v[4:7]
	v_mfma_f32_16x16x32_bf16 v[8:11], v[136:139], v[220:223], v[8:11]
	v_mfma_f32_16x16x32_bf16 v[8:11], v[140:143], v[224:227], v[8:11]
	v_mfma_f32_16x16x32_bf16 v[12:15], v[132:135], v[224:227], v[12:15]
	v_mfma_f32_16x16x32_bf16 v[12:15], v[128:131], v[220:223], v[12:15]
	s_setprio 0
	s_barrier
	s_add_u32 s12, s12, 0x100
	s_addc_u32 s13, s13, 0
	s_add_u32 s71, s71, 0x100
	s_addc_u32 s72, s72, 0
	s_cmp_ge_i32 s73, s59
	s_mov_b32 s46, s73
	s_cbranch_scc0 .LBB0_1046

; #define PG8_STAGE(bufoff, gbase, voff) do { _Pragma("unroll") for (int _i = 0; _i < 2; ++_i) \
;         __builtin_amdgcn_global_load_lds((const unsigned*)((const char*)(gbase) + (voff)[_i]), (LAS unsigned*)(lds + (bufoff) + ldsw + _i * 8192), 16, 0, 0); } while (0)
; #define PG8_LDA(dst, b, h) do { _Pragma("unroll") for (int m = 0; m < 4; ++m) _Pragma("unroll") for (int k = 0; k < 2; ++k) dst[m][k] = *(const LAS bf16x8*)(lds + PG8_SA(b, h) + aoff + m * 2048 + k * 1024); } while (0)
; #define PG8_LDB(dst, b, h) do { _Pragma("unroll") for (int n = 0; n < 2; ++n) _Pragma("unroll") for (int k = 0; k < 2; ++k) dst[n][k] = *(const LAS bf16x8*)(lds + PG8_SB(b, h) + boff + n * 2048 + k * 1024); } while (0)
; #define PG8_MMA(ai, bj, At, Bt) do { __builtin_amdgcn_s_setprio(1); _Pragma("unroll") for (int m = 0; m < 4; ++m) _Pragma("unroll") for (int n = 0; n < 2; ++n) _Pragma("unroll") for (int k = 0; k < 2; ++k) \
;         acc[ai][bj][m][n] = __builtin_amdgcn_mfma_f32_16x16x32_bf16(Bt[n][k], At[m][k], acc[ai][bj][m][n], 0, 0, 0); __builtin_amdgcn_s_setprio(0); } while (0)
; #define PG8_WAIT_V(n) asm volatile("s_waitcnt vmcnt(" #n ")" ::: "memory")
; #define PG8_WAIT_L(n) asm volatile("s_waitcnt lgkmcnt(" #n ")" ::: "memory")
; #define PG8_BAR __builtin_amdgcn_s_barrier()
; #define PG8_SCHED __builtin_amdgcn_sched_barrier(0)
; template <class Epi>
; __device__ __forceinline__ void gemm_phase(LAS unsigned char* lds, const Gemm g, const StaticOrder& S, const Epi& E) {
;     ...
;             const bool last = (t == nt - 2);
;             const char* a1 = cA + (size_t)(t + 1) * kstep;
;             const char* a2 = last ? nA : cA + (size_t)(t + 2) * kstep; const char* b2 = last ? nB : cB + (size_t)(t + 2) * kstep;
;             const char* a3 = a2 + kstep; const char* b3 = b2 + kstep;
;             PG8_LDB(B0, 0, 0); PG8_LDB(B1, 0, 1); PG8_SCHED; PG8_LDA(At, 0, 0); PG8_STAGE(PG8_SA(1, 1), a1 + hstepA, voffA);
;             PG8_WAIT_V(8); PG8_WAIT_L(0); PG8_BAR; PG8_MMA(0, 0, At, B0); PG8_MMA(0, 1, At, B1); PG8_BAR; PG8_SCHED;
;             PG8_LDA(At, 0, 1); PG8_STAGE(PG8_SB(0, 0), b2, voffB); PG8_STAGE(PG8_SB(0, 1), b2 + hstepB, voffB); PG8_STAGE(PG8_SA(0, 0), a2, voffA);
;             PG8_WAIT_V(8); PG8_WAIT_L(0); PG8_BAR; PG8_MMA(1, 0, At, B0); PG8_MMA(1, 1, At, B1); PG8_BAR; PG8_SCHED;
.LBB0_1131:
	ds_read_b128 v[164:167], v182
	ds_read_b128 v[168:171], v182 offset:1024
	ds_read_b128 v[172:175], v182 offset:2048
	ds_read_b128 v[176:179], v182 offset:3072
	ds_read_b128 v[186:189], v183
	ds_read_b128 v[190:193], v183 offset:1024
	ds_read_b128 v[194:197], v183 offset:2048
	ds_read_b128 v[198:201], v183 offset:3072
	s_add_i32 s22, s12, 2
	s_add_u32 s13, s10, 0xfff80080
	s_addc_u32 s14, s11, -1
	s_cmp_eq_u32 s58, s12
	s_cselect_b32 s12, s19, s20
	s_cselect_b32 s15, s16, s14
	s_cselect_b32 s14, s17, s13
	s_cselect_b32 s13, s18, s21
	v_lshl_add_u64 v[202:203], s[10:11], 0, v[140:141]
	s_add_i32 m0, s33, 0xc000
	ds_read_b128 v[208:211], v184
	ds_read_b128 v[212:215], v184 offset:1024
	ds_read_b128 v[216:219], v184 offset:2048
	ds_read_b128 v[220:223], v184 offset:3072
	ds_read_b128 v[224:227], v184 offset:4096
	ds_read_b128 v[230:233], v184 offset:5120
	ds_read_b128 v[234:237], v184 offset:6144
	ds_read_b128 v[238:241], v184 offset:7168
	global_load_lds_dwordx4 v[202:203], off
	v_lshl_add_u64 v[202:203], s[10:11], 0, v[142:143]
	s_add_i32 m0, s33, 0xe000
	s_nop 0
	global_load_lds_dwordx4 v[202:203], off
	s_waitcnt vmcnt(8) lgkmcnt(0)
	s_barrier
	s_setprio 1
	v_mfma_f32_16x16x32_bf16 v[120:123], v[164:167], v[208:211], v[120:123]
	v_mfma_f32_16x16x32_bf16 v[120:123], v[168:171], v[212:215], v[120:123]
	v_mfma_f32_16x16x32_bf16 v[116:119], v[176:179], v[212:215], v[116:119]
	v_mfma_f32_16x16x32_bf16 v[116:119], v[172:175], v[208:211], v[116:119]
	v_mfma_f32_16x16x32_bf16 v[124:127], v[186:189], v[208:211], v[124:127]
	v_mfma_f32_16x16x32_bf16 v[124:127], v[190:193], v[212:215], v[124:127]
	v_mfma_f32_16x16x32_bf16 v[112:115], v[198:201], v[212:215], v[112:115]
	v_mfma_f32_16x16x32_bf16 v[112:115], v[194:197], v[208:211], v[112:115]
	v_mfma_f32_16x16x32_bf16 v[96:99], v[194:197], v[216:219], v[96:99]
	v_mfma_f32_16x16x32_bf16 v[96:99], v[198:201], v[220:223], v[96:99]
	v_mfma_f32_16x16x32_bf16 v[104:107], v[190:193], v[220:223], v[104:107]
	v_mfma_f32_16x16x32_bf16 v[104:107], v[186:189], v[216:219], v[104:107]
	v_mfma_f32_16x16x32_bf16 v[100:103], v[172:175], v[216:219], v[100:103]
	v_mfma_f32_16x16x32_bf16 v[100:103], v[176:179], v[220:223], v[100:103]
	v_mfma_f32_16x16x32_bf16 v[108:111], v[168:171], v[220:223], v[108:111]
	v_mfma_f32_16x16x32_bf16 v[108:111], v[164:167], v[216:219], v[108:111]
	s_setprio 0
	s_setprio 1
	v_mfma_f32_16x16x32_bf16 v[92:95], v[164:167], v[224:227], v[92:95]
	v_mfma_f32_16x16x32_bf16 v[92:95], v[168:171], v[230:233], v[92:95]
	v_mfma_f32_16x16x32_bf16 v[84:87], v[176:179], v[230:233], v[84:87]
	v_mfma_f32_16x16x32_bf16 v[84:87], v[172:175], v[224:227], v[84:87]
	v_mfma_f32_16x16x32_bf16 v[88:91], v[186:189], v[224:227], v[88:91]
	v_mfma_f32_16x16x32_bf16 v[88:91], v[190:193], v[230:233], v[88:91]
	v_mfma_f32_16x16x32_bf16 v[80:83], v[198:201], v[230:233], v[80:83]
	v_mfma_f32_16x16x32_bf16 v[80:83], v[194:197], v[224:227], v[80:83]
	v_mfma_f32_16x16x32_bf16 v[64:67], v[194:197], v[234:237], v[64:67]
	v_mfma_f32_16x16x32_bf16 v[64:67], v[198:201], v[238:241], v[64:67]
	v_mfma_f32_16x16x32_bf16 v[72:75], v[190:193], v[238:241], v[72:75]
	v_mfma_f32_16x16x32_bf16 v[72:75], v[186:189], v[234:237], v[72:75]
	v_mfma_f32_16x16x32_bf16 v[68:71], v[172:175], v[234:237], v[68:71]
	v_mfma_f32_16x16x32_bf16 v[68:71], v[176:179], v[238:241], v[68:71]
	v_mfma_f32_16x16x32_bf16 v[76:79], v[168:171], v[238:241], v[76:79]
	v_mfma_f32_16x16x32_bf16 v[76:79], v[164:167], v[234:237], v[76:79]
	s_setprio 0
	s_barrier
	s_add_i32 s23, s62, s37
	v_lshl_add_u64 v[202:203], s[12:13], 0, v[132:133]
	s_mov_b32 m0, s23
	ds_read_b128 v[208:211], v184 offset:16384
	ds_read_b128 v[212:215], v184 offset:17408
	ds_read_b128 v[216:219], v184 offset:18432
	ds_read_b128 v[220:223], v184 offset:19456
	ds_read_b128 v[224:227], v184 offset:20480
	ds_read_b128 v[230:233], v184 offset:21504
	ds_read_b128 v[234:237], v184 offset:22528
	ds_read_b128 v[238:241], v184 offset:23552
	global_load_lds_dwordx4 v[202:203], off
	s_add_i32 m0, s23, 0x2000
	s_add_u32 s50, s12, 0x80000
	v_lshl_add_u64 v[242:243], s[12:13], 0, v[128:129]
	s_addc_u32 s51, s13, 0
	s_add_i32 s23, s63, s37
	global_load_lds_dwordx4 v[242:243], off
	v_lshl_add_u64 v[244:245], s[50:51], 0, v[132:133]
	s_mov_b32 m0, s23
	v_lshl_add_u64 v[246:247], s[14:15], 0, v[130:131]
	global_load_lds_dwordx4 v[244:245], off
	v_lshl_add_u64 v[244:245], s[50:51], 0, v[128:129]
	s_add_i32 m0, s23, 0x2000
	s_nop 0
	global_load_lds_dwordx4 v[244:245], off
	v_lshl_add_u64 v[244:245], s[14:15], 0, v[134:135]
	s_mov_b32 m0, s33
	s_nop 0
	global_load_lds_dwordx4 v[244:245], off
	s_mov_b32 m0, s52
	s_nop 0
	global_load_lds_dwordx4 v[246:247], off
	s_waitcnt vmcnt(8) lgkmcnt(0)
	s_barrier
; #define PG8_STAGE(bufoff, gbase, voff) do { _Pragma("unroll") for (int _i = 0; _i < 2; ++_i) \
;         __builtin_amdgcn_global_load_lds((const unsigned*)((const char*)(gbase) + (voff)[_i]), (LAS unsigned*)(lds + (bufoff) + ldsw + _i * 8192), 16, 0, 0); } while (0)
; #define PG8_LDA(dst, b, h) do { _Pragma("unroll") for (int m = 0; m < 4; ++m) _Pragma("unroll") for (int k = 0; k < 2; ++k) dst[m][k] = *(const LAS bf16x8*)(lds + PG8_SA(b, h) + aoff + m * 2048 + k * 1024); } while (0)
; #define PG8_LDB(dst, b, h) do { _Pragma("unroll") for (int n = 0; n < 2; ++n) _Pragma("unroll") for (int k = 0; k < 2; ++k) dst[n][k] = *(const LAS bf16x8*)(lds + PG8_SB(b, h) + boff + n * 2048 + k * 1024); } while (0)
; #define PG8_MMA(ai, bj, At, Bt) do { __builtin_amdgcn_s_setprio(1); _Pragma("unroll") for (int m = 0; m < 4; ++m) _Pragma("unroll") for (int n = 0; n < 2; ++n) _Pragma("unroll") for (int k = 0; k < 2; ++k) \
;         acc[ai][bj][m][n] = __builtin_amdgcn_mfma_f32_16x16x32_bf16(Bt[n][k], At[m][k], acc[ai][bj][m][n], 0, 0, 0); __builtin_amdgcn_s_setprio(0); } while (0)
; #define PG8_WAIT_V(n) asm volatile("s_waitcnt vmcnt(" #n ")" ::: "memory")
; #define PG8_WAIT_L(n) asm volatile("s_waitcnt lgkmcnt(" #n ")" ::: "memory")
; #define PG8_BAR __builtin_amdgcn_s_barrier()
; #define PG8_SCHED __builtin_amdgcn_sched_barrier(0)
; template <class Epi>
; __device__ __forceinline__ void gemm_phase(LAS unsigned char* lds, const Gemm g, const StaticOrder& S, const Epi& E) {
;     ...
;             PG8_WAIT_V(8); PG8_WAIT_L(0); PG8_BAR; PG8_MMA(1, 0, At, B0); PG8_MMA(1, 1, At, B1); PG8_BAR; PG8_SCHED;
;             PG8_LDB(B0, 1, 0); PG8_LDB(B1, 1, 1); PG8_SCHED; PG8_LDA(At, 1, 0); PG8_STAGE(PG8_SA(0, 1), a2 + hstepA, voffA);
;             PG8_WAIT_V(8); PG8_WAIT_L(0); PG8_BAR; PG8_MMA(0, 0, At, B0); PG8_MMA(0, 1, At, B1); PG8_BAR; PG8_SCHED;
	s_setprio 1
	v_mfma_f32_16x16x32_bf16 v[60:63], v[164:167], v[208:211], v[60:63]
	v_mfma_f32_16x16x32_bf16 v[60:63], v[168:171], v[212:215], v[60:63]
	v_mfma_f32_16x16x32_bf16 v[52:55], v[176:179], v[212:215], v[52:55]
	v_mfma_f32_16x16x32_bf16 v[52:55], v[172:175], v[208:211], v[52:55]
	v_mfma_f32_16x16x32_bf16 v[56:59], v[186:189], v[208:211], v[56:59]
	v_mfma_f32_16x16x32_bf16 v[56:59], v[190:193], v[212:215], v[56:59]
	v_mfma_f32_16x16x32_bf16 v[48:51], v[198:201], v[212:215], v[48:51]
	v_mfma_f32_16x16x32_bf16 v[48:51], v[194:197], v[208:211], v[48:51]
	v_mfma_f32_16x16x32_bf16 v[32:35], v[194:197], v[216:219], v[32:35]
	v_mfma_f32_16x16x32_bf16 v[32:35], v[198:201], v[220:223], v[32:35]
	v_mfma_f32_16x16x32_bf16 v[40:43], v[190:193], v[220:223], v[40:43]
	v_mfma_f32_16x16x32_bf16 v[40:43], v[186:189], v[216:219], v[40:43]
	v_mfma_f32_16x16x32_bf16 v[36:39], v[172:175], v[216:219], v[36:39]
	v_mfma_f32_16x16x32_bf16 v[36:39], v[176:179], v[220:223], v[36:39]
	v_mfma_f32_16x16x32_bf16 v[44:47], v[168:171], v[220:223], v[44:47]
	v_mfma_f32_16x16x32_bf16 v[44:47], v[164:167], v[216:219], v[44:47]
	s_setprio 0
	s_setprio 1
	v_mfma_f32_16x16x32_bf16 v[28:31], v[164:167], v[224:227], v[28:31]
	v_mfma_f32_16x16x32_bf16 v[28:31], v[168:171], v[230:233], v[28:31]
	v_mfma_f32_16x16x32_bf16 v[20:23], v[176:179], v[230:233], v[20:23]
	v_mfma_f32_16x16x32_bf16 v[20:23], v[172:175], v[224:227], v[20:23]
	v_mfma_f32_16x16x32_bf16 v[24:27], v[186:189], v[224:227], v[24:27]
	v_mfma_f32_16x16x32_bf16 v[24:27], v[190:193], v[230:233], v[24:27]
	v_mfma_f32_16x16x32_bf16 v[16:19], v[198:201], v[230:233], v[16:19]
	v_mfma_f32_16x16x32_bf16 v[16:19], v[194:197], v[224:227], v[16:19]
	v_mfma_f32_16x16x32_bf16 v[0:3], v[194:197], v[234:237], v[0:3]
	v_mfma_f32_16x16x32_bf16 v[0:3], v[198:201], v[238:241], v[0:3]
	v_mfma_f32_16x16x32_bf16 v[8:11], v[190:193], v[238:241], v[8:11]
	v_mfma_f32_16x16x32_bf16 v[8:11], v[186:189], v[234:237], v[8:11]
	v_mfma_f32_16x16x32_bf16 v[4:7], v[172:175], v[234:237], v[4:7]
	v_mfma_f32_16x16x32_bf16 v[4:7], v[176:179], v[238:241], v[4:7]
	v_mfma_f32_16x16x32_bf16 v[12:15], v[168:171], v[238:241], v[12:15]
	v_mfma_f32_16x16x32_bf16 v[12:15], v[164:167], v[234:237], v[12:15]
	s_setprio 0
	s_barrier
	s_add_i32 s23, 0, 0x18000
	s_add_i32 s25, 0, 0x1c000
	v_add_u32_e32 v176, s23, v180
	v_add_u32_e32 v185, s25, v180
	ds_read_b128 v[164:167], v176
	ds_read_b128 v[168:171], v176 offset:1024
	ds_read_b128 v[172:175], v176 offset:2048
	ds_read_b128 v[176:179], v176 offset:3072
	ds_read_b128 v[186:189], v185
	ds_read_b128 v[190:193], v185 offset:1024
	ds_read_b128 v[194:197], v185 offset:2048
	ds_read_b128 v[198:201], v185 offset:3072
	s_add_u32 s14, s14, 0x80000
	s_addc_u32 s15, s15, 0
	s_mov_b32 m0, s53
	v_lshl_add_u64 v[248:249], s[14:15], 0, v[134:135]
	ds_read_b128 v[208:211], v184 offset:32768
	ds_read_b128 v[212:215], v184 offset:33792
	ds_read_b128 v[216:219], v184 offset:34816
	ds_read_b128 v[220:223], v184 offset:35840
	ds_read_b128 v[224:227], v184 offset:36864
	ds_read_b128 v[230:233], v184 offset:37888
	ds_read_b128 v[234:237], v184 offset:38912
	ds_read_b128 v[238:241], v184 offset:39936
	global_load_lds_dwordx4 v[248:249], off
	v_lshl_add_u64 v[248:249], s[14:15], 0, v[130:131]
	s_mov_b32 m0, s54
	s_nop 0
	global_load_lds_dwordx4 v[248:249], off
	s_waitcnt vmcnt(8) lgkmcnt(0)
	s_barrier
	s_setprio 1
	v_mfma_f32_16x16x32_bf16 v[120:123], v[164:167], v[208:211], v[120:123]
	v_mfma_f32_16x16x32_bf16 v[120:123], v[168:171], v[212:215], v[120:123]
	v_mfma_f32_16x16x32_bf16 v[116:119], v[176:179], v[212:215], v[116:119]
	v_mfma_f32_16x16x32_bf16 v[116:119], v[172:175], v[208:211], v[116:119]
	v_mfma_f32_16x16x32_bf16 v[124:127], v[186:189], v[208:211], v[124:127]
	v_mfma_f32_16x16x32_bf16 v[124:127], v[190:193], v[212:215], v[124:127]
	v_mfma_f32_16x16x32_bf16 v[112:115], v[198:201], v[212:215], v[112:115]
	v_mfma_f32_16x16x32_bf16 v[112:115], v[194:197], v[208:211], v[112:115]
	v_mfma_f32_16x16x32_bf16 v[96:99], v[194:197], v[216:219], v[96:99]
	v_mfma_f32_16x16x32_bf16 v[96:99], v[198:201], v[220:223], v[96:99]
	v_mfma_f32_16x16x32_bf16 v[104:107], v[190:193], v[220:223], v[104:107]
	v_mfma_f32_16x16x32_bf16 v[104:107], v[186:189], v[216:219], v[104:107]
	v_mfma_f32_16x16x32_bf16 v[100:103], v[172:175], v[216:219], v[100:103]
	v_mfma_f32_16x16x32_bf16 v[100:103], v[176:179], v[220:223], v[100:103]
	v_mfma_f32_16x16x32_bf16 v[108:111], v[168:171], v[220:223], v[108:111]
	v_mfma_f32_16x16x32_bf16 v[108:111], v[164:167], v[216:219], v[108:111]
	s_setprio 0
	s_setprio 1
	v_mfma_f32_16x16x32_bf16 v[92:95], v[164:167], v[224:227], v[92:95]
	v_mfma_f32_16x16x32_bf16 v[92:95], v[168:171], v[230:233], v[92:95]
	v_mfma_f32_16x16x32_bf16 v[84:87], v[176:179], v[230:233], v[84:87]
	v_mfma_f32_16x16x32_bf16 v[84:87], v[172:175], v[224:227], v[84:87]
	v_mfma_f32_16x16x32_bf16 v[88:91], v[186:189], v[224:227], v[88:91]
	v_mfma_f32_16x16x32_bf16 v[88:91], v[190:193], v[230:233], v[88:91]
	v_mfma_f32_16x16x32_bf16 v[80:83], v[198:201], v[230:233], v[80:83]
	v_mfma_f32_16x16x32_bf16 v[80:83], v[194:197], v[224:227], v[80:83]
	v_mfma_f32_16x16x32_bf16 v[64:67], v[194:197], v[234:237], v[64:67]
	v_mfma_f32_16x16x32_bf16 v[64:67], v[198:201], v[238:241], v[64:67]
	v_mfma_f32_16x16x32_bf16 v[72:75], v[190:193], v[238:241], v[72:75]
	v_mfma_f32_16x16x32_bf16 v[72:75], v[186:189], v[234:237], v[72:75]
	v_mfma_f32_16x16x32_bf16 v[68:71], v[172:175], v[234:237], v[68:71]
	v_mfma_f32_16x16x32_bf16 v[68:71], v[176:179], v[238:241], v[68:71]
	v_mfma_f32_16x16x32_bf16 v[76:79], v[168:171], v[238:241], v[76:79]
	v_mfma_f32_16x16x32_bf16 v[76:79], v[164:167], v[234:237], v[76:79]
	s_setprio 0
	s_barrier
; #define PG8_STAGE(bufoff, gbase, voff) do { _Pragma("unroll") for (int _i = 0; _i < 2; ++_i) \
;         __builtin_amdgcn_global_load_lds((const unsigned*)((const char*)(gbase) + (voff)[_i]), (LAS unsigned*)(lds + (bufoff) + ldsw + _i * 8192), 16, 0, 0); } while (0)
; #define PG8_LDA(dst, b, h) do { _Pragma("unroll") for (int m = 0; m < 4; ++m) _Pragma("unroll") for (int k = 0; k < 2; ++k) dst[m][k] = *(const LAS bf16x8*)(lds + PG8_SA(b, h) + aoff + m * 2048 + k * 1024); } while (0)
; #define PG8_MMA(ai, bj, At, Bt) do { __builtin_amdgcn_s_setprio(1); _Pragma("unroll") for (int m = 0; m < 4; ++m) _Pragma("unroll") for (int n = 0; n < 2; ++n) _Pragma("unroll") for (int k = 0; k < 2; ++k) \
;         acc[ai][bj][m][n] = __builtin_amdgcn_mfma_f32_16x16x32_bf16(Bt[n][k], At[m][k], acc[ai][bj][m][n], 0, 0, 0); __builtin_amdgcn_s_setprio(0); } while (0)
; #define PG8_WAIT_V(n) asm volatile("s_waitcnt vmcnt(" #n ")" ::: "memory")
; #define PG8_WAIT_L(n) asm volatile("s_waitcnt lgkmcnt(" #n ")" ::: "memory")
; #define PG8_BAR __builtin_amdgcn_s_barrier()
; #define PG8_SCHED __builtin_amdgcn_sched_barrier(0)
; template <class Epi>
; __device__ __forceinline__ void gemm_phase(LAS unsigned char* lds, const Gemm g, const StaticOrder& S, const Epi& E) {
;     ...
;             PG8_LDA(At, 1, 1); PG8_STAGE(PG8_SB(1, 0), b3, voffB); PG8_STAGE(PG8_SB(1, 1), b3 + hstepB, voffB); PG8_STAGE(PG8_SA(1, 0), a3, voffA);
;             PG8_WAIT_V(8); PG8_WAIT_L(0); PG8_BAR; PG8_MMA(1, 0, At, B0); PG8_MMA(1, 1, At, B1); PG8_BAR; PG8_SCHED;
;         }
	s_add_i32 s14, s23, s37
	v_lshl_add_u64 v[202:203], v[202:203], 0, s[4:5]
	s_mov_b32 m0, s14
	ds_read_b128 v[208:211], v184 offset:49152
	ds_read_b128 v[212:215], v184 offset:50176
	ds_read_b128 v[216:219], v184 offset:51200
	ds_read_b128 v[220:223], v184 offset:52224
	ds_read_b128 v[224:227], v184 offset:53248
	ds_read_b128 v[230:233], v184 offset:54272
	ds_read_b128 v[234:237], v184 offset:55296
	ds_read_b128 v[238:241], v184 offset:56320
	global_load_lds_dwordx4 v[202:203], off
	s_add_i32 m0, s14, 0x2000
	s_add_u32 s12, s12, 0x80080
	v_lshl_add_u64 v[202:203], v[242:243], 0, s[4:5]
	s_addc_u32 s13, s13, 0
	s_add_i32 s14, s25, s37
	global_load_lds_dwordx4 v[202:203], off
	v_lshl_add_u64 v[202:203], s[12:13], 0, v[132:133]
	s_mov_b32 m0, s14
	s_nop 0
	global_load_lds_dwordx4 v[202:203], off
	v_lshl_add_u64 v[202:203], s[12:13], 0, v[128:129]
	s_add_i32 m0, s14, 0x2000
	s_nop 0
	global_load_lds_dwordx4 v[202:203], off
	v_lshl_add_u64 v[202:203], v[244:245], 0, s[4:5]
	s_mov_b32 m0, s56
	s_nop 0
	global_load_lds_dwordx4 v[202:203], off
	v_lshl_add_u64 v[202:203], v[246:247], 0, s[4:5]
	s_mov_b32 m0, s57
	s_nop 0
	global_load_lds_dwordx4 v[202:203], off
	s_waitcnt vmcnt(8) lgkmcnt(0)
	s_barrier
	s_setprio 1
	v_mfma_f32_16x16x32_bf16 v[60:63], v[164:167], v[208:211], v[60:63]
	v_mfma_f32_16x16x32_bf16 v[60:63], v[168:171], v[212:215], v[60:63]
	v_mfma_f32_16x16x32_bf16 v[52:55], v[176:179], v[212:215], v[52:55]
	v_mfma_f32_16x16x32_bf16 v[52:55], v[172:175], v[208:211], v[52:55]
	v_mfma_f32_16x16x32_bf16 v[56:59], v[186:189], v[208:211], v[56:59]
	v_mfma_f32_16x16x32_bf16 v[56:59], v[190:193], v[212:215], v[56:59]
	v_mfma_f32_16x16x32_bf16 v[48:51], v[198:201], v[212:215], v[48:51]
	v_mfma_f32_16x16x32_bf16 v[48:51], v[194:197], v[208:211], v[48:51]
	v_mfma_f32_16x16x32_bf16 v[32:35], v[194:197], v[216:219], v[32:35]
	v_mfma_f32_16x16x32_bf16 v[32:35], v[198:201], v[220:223], v[32:35]
	v_mfma_f32_16x16x32_bf16 v[40:43], v[190:193], v[220:223], v[40:43]
	v_mfma_f32_16x16x32_bf16 v[40:43], v[186:189], v[216:219], v[40:43]
	v_mfma_f32_16x16x32_bf16 v[36:39], v[172:175], v[216:219], v[36:39]
	v_mfma_f32_16x16x32_bf16 v[36:39], v[176:179], v[220:223], v[36:39]
	v_mfma_f32_16x16x32_bf16 v[44:47], v[168:171], v[220:223], v[44:47]
	v_mfma_f32_16x16x32_bf16 v[44:47], v[164:167], v[216:219], v[44:47]
	s_setprio 0
	s_setprio 1
	v_mfma_f32_16x16x32_bf16 v[28:31], v[164:167], v[224:227], v[28:31]
	v_mfma_f32_16x16x32_bf16 v[28:31], v[168:171], v[230:233], v[28:31]
	v_mfma_f32_16x16x32_bf16 v[20:23], v[176:179], v[230:233], v[20:23]
	v_mfma_f32_16x16x32_bf16 v[20:23], v[172:175], v[224:227], v[20:23]
	v_mfma_f32_16x16x32_bf16 v[24:27], v[186:189], v[224:227], v[24:27]
	v_mfma_f32_16x16x32_bf16 v[24:27], v[190:193], v[230:233], v[24:27]
	v_mfma_f32_16x16x32_bf16 v[16:19], v[198:201], v[230:233], v[16:19]
	v_mfma_f32_16x16x32_bf16 v[16:19], v[194:197], v[224:227], v[16:19]
	v_mfma_f32_16x16x32_bf16 v[0:3], v[194:197], v[234:237], v[0:3]
	v_mfma_f32_16x16x32_bf16 v[0:3], v[198:201], v[238:241], v[0:3]
	v_mfma_f32_16x16x32_bf16 v[8:11], v[190:193], v[238:241], v[8:11]
	v_mfma_f32_16x16x32_bf16 v[8:11], v[186:189], v[234:237], v[8:11]
	v_mfma_f32_16x16x32_bf16 v[4:7], v[172:175], v[234:237], v[4:7]
	v_mfma_f32_16x16x32_bf16 v[4:7], v[176:179], v[238:241], v[4:7]
	v_mfma_f32_16x16x32_bf16 v[12:15], v[168:171], v[238:241], v[12:15]
	v_mfma_f32_16x16x32_bf16 v[12:15], v[164:167], v[234:237], v[12:15]
	s_setprio 0
	s_barrier
	s_add_u32 s10, s10, 0x100
	s_addc_u32 s11, s11, 0
	s_add_u32 s20, s20, 0x100
	s_addc_u32 s21, s21, 0
	s_cmp_ge_i32 s22, s55
	s_mov_b32 s12, s22
	s_cbranch_scc0 .LBB0_1131

; #define PG8_STAGE(bufoff, gbase, voff) do { _Pragma("unroll") for (int _i = 0; _i < 2; ++_i) \
;         __builtin_amdgcn_global_load_lds((const unsigned*)((const char*)(gbase) + (voff)[_i]), (LAS unsigned*)(lds + (bufoff) + ldsw + _i * 8192), 16, 0, 0); } while (0)
; #define PG8_LDA(dst, b, h) do { _Pragma("unroll") for (int m = 0; m < 4; ++m) _Pragma("unroll") for (int k = 0; k < 2; ++k) dst[m][k] = *(const LAS bf16x8*)(lds + PG8_SA(b, h) + aoff + m * 2048 + k * 1024); } while (0)
; #define PG8_LDB(dst, b, h) do { _Pragma("unroll") for (int n = 0; n < 2; ++n) _Pragma("unroll") for (int k = 0; k < 2; ++k) dst[n][k] = *(const LAS bf16x8*)(lds + PG8_SB(b, h) + boff + n * 2048 + k * 1024); } while (0)
; #define PG8_MMA(ai, bj, At, Bt) do { __builtin_amdgcn_s_setprio(1); _Pragma("unroll") for (int m = 0; m < 4; ++m) _Pragma("unroll") for (int n = 0; n < 2; ++n) _Pragma("unroll") for (int k = 0; k < 2; ++k) \
;         acc[ai][bj][m][n] = __builtin_amdgcn_mfma_f32_16x16x32_bf16(Bt[n][k], At[m][k], acc[ai][bj][m][n], 0, 0, 0); __builtin_amdgcn_s_setprio(0); } while (0)
; #define PG8_WAIT_V(n) asm volatile("s_waitcnt vmcnt(" #n ")" ::: "memory")
; #define PG8_WAIT_L(n) asm volatile("s_waitcnt lgkmcnt(" #n ")" ::: "memory")
; #define PG8_BAR __builtin_amdgcn_s_barrier()
; #define PG8_SCHED __builtin_amdgcn_sched_barrier(0)
; template <class Epi>
; __device__ __forceinline__ void gemm_phase(LAS unsigned char* lds, const Gemm g, const StaticOrder& S, const Epi& E) {
;     ...
;             const bool last = (t == nt - 2);
;             const char* a1 = cA + (size_t)(t + 1) * kstep;
;             const char* a2 = last ? nA : cA + (size_t)(t + 2) * kstep; const char* b2 = last ? nB : cB + (size_t)(t + 2) * kstep;
;             const char* a3 = a2 + kstep; const char* b3 = b2 + kstep;
;             PG8_LDB(B0, 0, 0); PG8_LDB(B1, 0, 1); PG8_SCHED; PG8_LDA(At, 0, 0); PG8_STAGE(PG8_SA(1, 1), a1 + hstepA, voffA);
;             PG8_WAIT_V(8); PG8_WAIT_L(0); PG8_BAR; PG8_MMA(0, 0, At, B0); PG8_MMA(0, 1, At, B1); PG8_BAR; PG8_SCHED;
;             PG8_LDA(At, 0, 1); PG8_STAGE(PG8_SB(0, 0), b2, voffB); PG8_STAGE(PG8_SB(0, 1), b2 + hstepB, voffB); PG8_STAGE(PG8_SA(0, 0), a2, voffA);
;             PG8_WAIT_V(8); PG8_WAIT_L(0); PG8_BAR; PG8_MMA(1, 0, At, B0); PG8_MMA(1, 1, At, B1); PG8_BAR; PG8_SCHED;
.LBB0_1161:
	ds_read_b128 v[152:155], v149
	ds_read_b128 v[156:159], v149 offset:1024
	ds_read_b128 v[160:163], v149 offset:2048
	ds_read_b128 v[164:167], v149 offset:3072
	ds_read_b128 v[168:171], v150
	ds_read_b128 v[172:175], v150 offset:1024
	ds_read_b128 v[176:179], v150 offset:2048
	ds_read_b128 v[180:183], v150 offset:3072
	s_add_i32 s83, s46, 2
	s_add_u32 s47, s44, 0xffff0080
	s_addc_u32 s48, s45, -1
	s_cmp_eq_u32 s65, s46
	s_cselect_b32 s46, s78, s79
	s_cselect_b32 s49, s35, s48
	s_cselect_b32 s48, s37, s47
	s_cselect_b32 s47, s39, s82
	v_lshl_add_u64 v[220:221], s[44:45], 0, v[140:141]
	s_add_i32 m0, s56, 0xc000
	ds_read_b128 v[184:187], v151
	ds_read_b128 v[188:191], v151 offset:1024
	ds_read_b128 v[192:195], v151 offset:2048
	ds_read_b128 v[196:199], v151 offset:3072
	ds_read_b128 v[200:203], v151 offset:4096
	ds_read_b128 v[208:211], v151 offset:5120
	ds_read_b128 v[212:215], v151 offset:6144
	ds_read_b128 v[216:219], v151 offset:7168
	global_load_lds_dwordx4 v[220:221], off
	v_lshl_add_u64 v[220:221], s[44:45], 0, v[142:143]
	s_add_i32 m0, s56, 0xe000
	s_nop 0
	global_load_lds_dwordx4 v[220:221], off
	s_waitcnt vmcnt(8) lgkmcnt(0)
	s_barrier
	s_setprio 1
	v_mfma_f32_16x16x32_bf16 v[120:123], v[152:155], v[184:187], v[120:123]
	v_mfma_f32_16x16x32_bf16 v[120:123], v[156:159], v[188:191], v[120:123]
	v_mfma_f32_16x16x32_bf16 v[124:127], v[164:167], v[188:191], v[124:127]
	v_mfma_f32_16x16x32_bf16 v[124:127], v[160:163], v[184:187], v[124:127]
	v_mfma_f32_16x16x32_bf16 v[116:119], v[168:171], v[184:187], v[116:119]
	v_mfma_f32_16x16x32_bf16 v[116:119], v[172:175], v[188:191], v[116:119]
	v_mfma_f32_16x16x32_bf16 v[112:115], v[180:183], v[188:191], v[112:115]
	v_mfma_f32_16x16x32_bf16 v[112:115], v[176:179], v[184:187], v[112:115]
	v_mfma_f32_16x16x32_bf16 v[96:99], v[176:179], v[192:195], v[96:99]
	v_mfma_f32_16x16x32_bf16 v[96:99], v[180:183], v[196:199], v[96:99]
	v_mfma_f32_16x16x32_bf16 v[100:103], v[172:175], v[196:199], v[100:103]
	v_mfma_f32_16x16x32_bf16 v[100:103], v[168:171], v[192:195], v[100:103]
	v_mfma_f32_16x16x32_bf16 v[104:107], v[160:163], v[192:195], v[104:107]
	v_mfma_f32_16x16x32_bf16 v[104:107], v[164:167], v[196:199], v[104:107]
	v_mfma_f32_16x16x32_bf16 v[108:111], v[156:159], v[196:199], v[108:111]
	v_mfma_f32_16x16x32_bf16 v[108:111], v[152:155], v[192:195], v[108:111]
	s_setprio 0
	s_setprio 1
	v_mfma_f32_16x16x32_bf16 v[92:95], v[152:155], v[200:203], v[92:95]
	v_mfma_f32_16x16x32_bf16 v[92:95], v[156:159], v[208:211], v[92:95]
	v_mfma_f32_16x16x32_bf16 v[88:91], v[164:167], v[208:211], v[88:91]
	v_mfma_f32_16x16x32_bf16 v[88:91], v[160:163], v[200:203], v[88:91]
	v_mfma_f32_16x16x32_bf16 v[84:87], v[168:171], v[200:203], v[84:87]
	v_mfma_f32_16x16x32_bf16 v[84:87], v[172:175], v[208:211], v[84:87]
	v_mfma_f32_16x16x32_bf16 v[80:83], v[180:183], v[208:211], v[80:83]
	v_mfma_f32_16x16x32_bf16 v[80:83], v[176:179], v[200:203], v[80:83]
	v_mfma_f32_16x16x32_bf16 v[64:67], v[176:179], v[212:215], v[64:67]
	v_mfma_f32_16x16x32_bf16 v[64:67], v[180:183], v[216:219], v[64:67]
	v_mfma_f32_16x16x32_bf16 v[68:71], v[172:175], v[216:219], v[68:71]
	v_mfma_f32_16x16x32_bf16 v[68:71], v[168:171], v[212:215], v[68:71]
	v_mfma_f32_16x16x32_bf16 v[72:75], v[160:163], v[212:215], v[72:75]
	v_mfma_f32_16x16x32_bf16 v[72:75], v[164:167], v[216:219], v[72:75]
	v_mfma_f32_16x16x32_bf16 v[76:79], v[156:159], v[216:219], v[76:79]
	v_mfma_f32_16x16x32_bf16 v[76:79], v[152:155], v[212:215], v[76:79]
	s_setprio 0
	s_barrier
	s_add_i32 s84, s67, s51
	v_lshl_add_u64 v[220:221], s[46:47], 0, v[130:131]
	s_mov_b32 m0, s84
	ds_read_b128 v[184:187], v151 offset:16384
	ds_read_b128 v[188:191], v151 offset:17408
	ds_read_b128 v[192:195], v151 offset:18432
	ds_read_b128 v[196:199], v151 offset:19456
	ds_read_b128 v[200:203], v151 offset:20480
	ds_read_b128 v[208:211], v151 offset:21504
	ds_read_b128 v[212:215], v151 offset:22528
	ds_read_b128 v[216:219], v151 offset:23552
	global_load_lds_dwordx4 v[220:221], off
	s_add_i32 m0, s84, 0x2000
	s_add_u32 s84, s46, 0x10000
	v_lshl_add_u64 v[222:223], s[46:47], 0, v[134:135]
	s_addc_u32 s85, s47, 0
	s_add_i32 s86, s68, s51
	global_load_lds_dwordx4 v[222:223], off
	v_lshl_add_u64 v[224:225], s[84:85], 0, v[130:131]
	s_mov_b32 m0, s86
	v_lshl_add_u64 v[226:227], s[48:49], 0, v[132:133]
	global_load_lds_dwordx4 v[224:225], off
	v_lshl_add_u64 v[224:225], s[84:85], 0, v[134:135]
	s_add_i32 m0, s86, 0x2000
	s_nop 0
	global_load_lds_dwordx4 v[224:225], off
	v_lshl_add_u64 v[224:225], s[48:49], 0, v[128:129]
	s_mov_b32 m0, s56
	s_nop 0
	global_load_lds_dwordx4 v[224:225], off
	s_mov_b32 m0, s57
	s_nop 0
	global_load_lds_dwordx4 v[226:227], off
	s_waitcnt vmcnt(8) lgkmcnt(0)
	s_barrier
; #define PG8_STAGE(bufoff, gbase, voff) do { _Pragma("unroll") for (int _i = 0; _i < 2; ++_i) \
;         __builtin_amdgcn_global_load_lds((const unsigned*)((const char*)(gbase) + (voff)[_i]), (LAS unsigned*)(lds + (bufoff) + ldsw + _i * 8192), 16, 0, 0); } while (0)
; #define PG8_LDA(dst, b, h) do { _Pragma("unroll") for (int m = 0; m < 4; ++m) _Pragma("unroll") for (int k = 0; k < 2; ++k) dst[m][k] = *(const LAS bf16x8*)(lds + PG8_SA(b, h) + aoff + m * 2048 + k * 1024); } while (0)
; #define PG8_LDB(dst, b, h) do { _Pragma("unroll") for (int n = 0; n < 2; ++n) _Pragma("unroll") for (int k = 0; k < 2; ++k) dst[n][k] = *(const LAS bf16x8*)(lds + PG8_SB(b, h) + boff + n * 2048 + k * 1024); } while (0)
; #define PG8_MMA(ai, bj, At, Bt) do { __builtin_amdgcn_s_setprio(1); _Pragma("unroll") for (int m = 0; m < 4; ++m) _Pragma("unroll") for (int n = 0; n < 2; ++n) _Pragma("unroll") for (int k = 0; k < 2; ++k) \
;         acc[ai][bj][m][n] = __builtin_amdgcn_mfma_f32_16x16x32_bf16(Bt[n][k], At[m][k], acc[ai][bj][m][n], 0, 0, 0); __builtin_amdgcn_s_setprio(0); } while (0)
; #define PG8_WAIT_V(n) asm volatile("s_waitcnt vmcnt(" #n ")" ::: "memory")
; #define PG8_WAIT_L(n) asm volatile("s_waitcnt lgkmcnt(" #n ")" ::: "memory")
; #define PG8_BAR __builtin_amdgcn_s_barrier()
; #define PG8_SCHED __builtin_amdgcn_sched_barrier(0)
; template <class Epi>
; __device__ __forceinline__ void gemm_phase(LAS unsigned char* lds, const Gemm g, const StaticOrder& S, const Epi& E) {
;     ...
;             PG8_WAIT_V(8); PG8_WAIT_L(0); PG8_BAR; PG8_MMA(1, 0, At, B0); PG8_MMA(1, 1, At, B1); PG8_BAR; PG8_SCHED;
;             PG8_LDB(B0, 1, 0); PG8_LDB(B1, 1, 1); PG8_SCHED; PG8_LDA(At, 1, 0); PG8_STAGE(PG8_SA(0, 1), a2 + hstepA, voffA);
;             PG8_WAIT_V(8); PG8_WAIT_L(0); PG8_BAR; PG8_MMA(0, 0, At, B0); PG8_MMA(0, 1, At, B1); PG8_BAR; PG8_SCHED;
	s_setprio 1
	v_mfma_f32_16x16x32_bf16 v[60:63], v[152:155], v[184:187], v[60:63]
	v_mfma_f32_16x16x32_bf16 v[60:63], v[156:159], v[188:191], v[60:63]
	v_mfma_f32_16x16x32_bf16 v[56:59], v[164:167], v[188:191], v[56:59]
	v_mfma_f32_16x16x32_bf16 v[56:59], v[160:163], v[184:187], v[56:59]
	v_mfma_f32_16x16x32_bf16 v[52:55], v[168:171], v[184:187], v[52:55]
	v_mfma_f32_16x16x32_bf16 v[52:55], v[172:175], v[188:191], v[52:55]
	v_mfma_f32_16x16x32_bf16 v[48:51], v[180:183], v[188:191], v[48:51]
	v_mfma_f32_16x16x32_bf16 v[48:51], v[176:179], v[184:187], v[48:51]
	v_mfma_f32_16x16x32_bf16 v[32:35], v[176:179], v[192:195], v[32:35]
	v_mfma_f32_16x16x32_bf16 v[32:35], v[180:183], v[196:199], v[32:35]
	v_mfma_f32_16x16x32_bf16 v[36:39], v[172:175], v[196:199], v[36:39]
	v_mfma_f32_16x16x32_bf16 v[36:39], v[168:171], v[192:195], v[36:39]
	v_mfma_f32_16x16x32_bf16 v[40:43], v[160:163], v[192:195], v[40:43]
	v_mfma_f32_16x16x32_bf16 v[40:43], v[164:167], v[196:199], v[40:43]
	v_mfma_f32_16x16x32_bf16 v[44:47], v[156:159], v[196:199], v[44:47]
	v_mfma_f32_16x16x32_bf16 v[44:47], v[152:155], v[192:195], v[44:47]
	s_setprio 0
	s_setprio 1
	v_mfma_f32_16x16x32_bf16 v[28:31], v[152:155], v[200:203], v[28:31]
	v_mfma_f32_16x16x32_bf16 v[28:31], v[156:159], v[208:211], v[28:31]
	v_mfma_f32_16x16x32_bf16 v[24:27], v[164:167], v[208:211], v[24:27]
	v_mfma_f32_16x16x32_bf16 v[24:27], v[160:163], v[200:203], v[24:27]
	v_mfma_f32_16x16x32_bf16 v[20:23], v[168:171], v[200:203], v[20:23]
	v_mfma_f32_16x16x32_bf16 v[20:23], v[172:175], v[208:211], v[20:23]
	v_mfma_f32_16x16x32_bf16 v[16:19], v[180:183], v[208:211], v[16:19]
	v_mfma_f32_16x16x32_bf16 v[16:19], v[176:179], v[200:203], v[16:19]
	v_mfma_f32_16x16x32_bf16 v[0:3], v[176:179], v[212:215], v[0:3]
	v_mfma_f32_16x16x32_bf16 v[0:3], v[180:183], v[216:219], v[0:3]
	v_mfma_f32_16x16x32_bf16 v[4:7], v[172:175], v[216:219], v[4:7]
	v_mfma_f32_16x16x32_bf16 v[4:7], v[168:171], v[212:215], v[4:7]
	v_mfma_f32_16x16x32_bf16 v[8:11], v[160:163], v[212:215], v[8:11]
	v_mfma_f32_16x16x32_bf16 v[8:11], v[164:167], v[216:219], v[8:11]
	v_mfma_f32_16x16x32_bf16 v[12:15], v[156:159], v[216:219], v[12:15]
	v_mfma_f32_16x16x32_bf16 v[12:15], v[152:155], v[212:215], v[12:15]
	s_setprio 0
	s_barrier
	s_add_i32 s84, 0, 0x18000
	s_add_i32 s85, 0, 0x1c000
	v_add_u32_e32 v164, s84, v148
	v_add_u32_e32 v180, s85, v148
	ds_read_b128 v[152:155], v164
	ds_read_b128 v[156:159], v164 offset:1024
	ds_read_b128 v[160:163], v164 offset:2048
	ds_read_b128 v[164:167], v164 offset:3072
	ds_read_b128 v[168:171], v180
	ds_read_b128 v[172:175], v180 offset:1024
	ds_read_b128 v[176:179], v180 offset:2048
	ds_read_b128 v[180:183], v180 offset:3072
	s_add_u32 s48, s48, 0x10000
	s_addc_u32 s49, s49, 0
	s_mov_b32 m0, s58
	v_lshl_add_u64 v[230:231], s[48:49], 0, v[128:129]
	ds_read_b128 v[184:187], v151 offset:32768
	ds_read_b128 v[188:191], v151 offset:33792
	ds_read_b128 v[192:195], v151 offset:34816
	ds_read_b128 v[196:199], v151 offset:35840
	ds_read_b128 v[200:203], v151 offset:36864
	ds_read_b128 v[208:211], v151 offset:37888
	ds_read_b128 v[212:215], v151 offset:38912
	ds_read_b128 v[216:219], v151 offset:39936
	global_load_lds_dwordx4 v[230:231], off
	v_lshl_add_u64 v[230:231], s[48:49], 0, v[132:133]
	s_mov_b32 m0, s59
	s_nop 0
	global_load_lds_dwordx4 v[230:231], off
	s_waitcnt vmcnt(8) lgkmcnt(0)
	s_barrier
	s_setprio 1
	v_mfma_f32_16x16x32_bf16 v[120:123], v[152:155], v[184:187], v[120:123]
	v_mfma_f32_16x16x32_bf16 v[120:123], v[156:159], v[188:191], v[120:123]
	v_mfma_f32_16x16x32_bf16 v[124:127], v[164:167], v[188:191], v[124:127]
	v_mfma_f32_16x16x32_bf16 v[124:127], v[160:163], v[184:187], v[124:127]
	v_mfma_f32_16x16x32_bf16 v[116:119], v[168:171], v[184:187], v[116:119]
	v_mfma_f32_16x16x32_bf16 v[116:119], v[172:175], v[188:191], v[116:119]
	v_mfma_f32_16x16x32_bf16 v[112:115], v[180:183], v[188:191], v[112:115]
	v_mfma_f32_16x16x32_bf16 v[112:115], v[176:179], v[184:187], v[112:115]
	v_mfma_f32_16x16x32_bf16 v[96:99], v[176:179], v[192:195], v[96:99]
	v_mfma_f32_16x16x32_bf16 v[96:99], v[180:183], v[196:199], v[96:99]
	v_mfma_f32_16x16x32_bf16 v[100:103], v[172:175], v[196:199], v[100:103]
	v_mfma_f32_16x16x32_bf16 v[100:103], v[168:171], v[192:195], v[100:103]
	v_mfma_f32_16x16x32_bf16 v[104:107], v[160:163], v[192:195], v[104:107]
	v_mfma_f32_16x16x32_bf16 v[104:107], v[164:167], v[196:199], v[104:107]
	v_mfma_f32_16x16x32_bf16 v[108:111], v[156:159], v[196:199], v[108:111]
	v_mfma_f32_16x16x32_bf16 v[108:111], v[152:155], v[192:195], v[108:111]
	s_setprio 0
	s_setprio 1
	v_mfma_f32_16x16x32_bf16 v[92:95], v[152:155], v[200:203], v[92:95]
	v_mfma_f32_16x16x32_bf16 v[92:95], v[156:159], v[208:211], v[92:95]
	v_mfma_f32_16x16x32_bf16 v[88:91], v[164:167], v[208:211], v[88:91]
	v_mfma_f32_16x16x32_bf16 v[88:91], v[160:163], v[200:203], v[88:91]
	v_mfma_f32_16x16x32_bf16 v[84:87], v[168:171], v[200:203], v[84:87]
	v_mfma_f32_16x16x32_bf16 v[84:87], v[172:175], v[208:211], v[84:87]
	v_mfma_f32_16x16x32_bf16 v[80:83], v[180:183], v[208:211], v[80:83]
	v_mfma_f32_16x16x32_bf16 v[80:83], v[176:179], v[200:203], v[80:83]
	v_mfma_f32_16x16x32_bf16 v[64:67], v[176:179], v[212:215], v[64:67]
	v_mfma_f32_16x16x32_bf16 v[64:67], v[180:183], v[216:219], v[64:67]
	v_mfma_f32_16x16x32_bf16 v[68:71], v[172:175], v[216:219], v[68:71]
	v_mfma_f32_16x16x32_bf16 v[68:71], v[168:171], v[212:215], v[68:71]
	v_mfma_f32_16x16x32_bf16 v[72:75], v[160:163], v[212:215], v[72:75]
	v_mfma_f32_16x16x32_bf16 v[72:75], v[164:167], v[216:219], v[72:75]
	v_mfma_f32_16x16x32_bf16 v[76:79], v[156:159], v[216:219], v[76:79]
	v_mfma_f32_16x16x32_bf16 v[76:79], v[152:155], v[212:215], v[76:79]
	s_setprio 0
	s_barrier
; #define PG8_STAGE(bufoff, gbase, voff) do { _Pragma("unroll") for (int _i = 0; _i < 2; ++_i) \
;         __builtin_amdgcn_global_load_lds((const unsigned*)((const char*)(gbase) + (voff)[_i]), (LAS unsigned*)(lds + (bufoff) + ldsw + _i * 8192), 16, 0, 0); } while (0)
; #define PG8_LDA(dst, b, h) do { _Pragma("unroll") for (int m = 0; m < 4; ++m) _Pragma("unroll") for (int k = 0; k < 2; ++k) dst[m][k] = *(const LAS bf16x8*)(lds + PG8_SA(b, h) + aoff + m * 2048 + k * 1024); } while (0)
; #define PG8_MMA(ai, bj, At, Bt) do { __builtin_amdgcn_s_setprio(1); _Pragma("unroll") for (int m = 0; m < 4; ++m) _Pragma("unroll") for (int n = 0; n < 2; ++n) _Pragma("unroll") for (int k = 0; k < 2; ++k) \
;         acc[ai][bj][m][n] = __builtin_amdgcn_mfma_f32_16x16x32_bf16(Bt[n][k], At[m][k], acc[ai][bj][m][n], 0, 0, 0); __builtin_amdgcn_s_setprio(0); } while (0)
; #define PG8_WAIT_V(n) asm volatile("s_waitcnt vmcnt(" #n ")" ::: "memory")
; #define PG8_WAIT_L(n) asm volatile("s_waitcnt lgkmcnt(" #n ")" ::: "memory")
; #define PG8_BAR __builtin_amdgcn_s_barrier()
; #define PG8_SCHED __builtin_amdgcn_sched_barrier(0)
; template <class Epi>
; __device__ __forceinline__ void gemm_phase(LAS unsigned char* lds, const Gemm g, const StaticOrder& S, const Epi& E) {
;     ...
;             PG8_LDA(At, 1, 1); PG8_STAGE(PG8_SB(1, 0), b3, voffB); PG8_STAGE(PG8_SB(1, 1), b3 + hstepB, voffB); PG8_STAGE(PG8_SA(1, 0), a3, voffA);
;             PG8_WAIT_V(8); PG8_WAIT_L(0); PG8_BAR; PG8_MMA(1, 0, At, B0); PG8_MMA(1, 1, At, B1); PG8_BAR; PG8_SCHED;
;         }
	s_add_i32 s48, s84, s51
	v_lshl_add_u64 v[220:221], v[220:221], 0, s[12:13]
	s_mov_b32 m0, s48
	ds_read_b128 v[184:187], v151 offset:49152
	ds_read_b128 v[188:191], v151 offset:50176
	ds_read_b128 v[192:195], v151 offset:51200
	ds_read_b128 v[196:199], v151 offset:52224
	ds_read_b128 v[200:203], v151 offset:53248
	ds_read_b128 v[208:211], v151 offset:54272
	ds_read_b128 v[212:215], v151 offset:55296
	ds_read_b128 v[216:219], v151 offset:56320
	global_load_lds_dwordx4 v[220:221], off
	s_add_i32 m0, s48, 0x2000
	s_add_u32 s46, s46, 0x10080
	v_lshl_add_u64 v[220:221], v[222:223], 0, s[12:13]
	s_addc_u32 s47, s47, 0
	s_add_i32 s48, s85, s51
	global_load_lds_dwordx4 v[220:221], off
	v_lshl_add_u64 v[220:221], s[46:47], 0, v[130:131]
	s_mov_b32 m0, s48
	s_nop 0
	global_load_lds_dwordx4 v[220:221], off
	v_lshl_add_u64 v[220:221], s[46:47], 0, v[134:135]
	s_add_i32 m0, s48, 0x2000
	s_nop 0
	global_load_lds_dwordx4 v[220:221], off
	v_lshl_add_u64 v[220:221], v[224:225], 0, s[12:13]
	s_mov_b32 m0, s63
	s_nop 0
	global_load_lds_dwordx4 v[220:221], off
	v_lshl_add_u64 v[220:221], v[226:227], 0, s[12:13]
	s_mov_b32 m0, s64
	s_nop 0
	global_load_lds_dwordx4 v[220:221], off
	s_waitcnt vmcnt(8) lgkmcnt(0)
	s_barrier
	s_setprio 1
	v_mfma_f32_16x16x32_bf16 v[60:63], v[152:155], v[184:187], v[60:63]
	v_mfma_f32_16x16x32_bf16 v[60:63], v[156:159], v[188:191], v[60:63]
	v_mfma_f32_16x16x32_bf16 v[56:59], v[164:167], v[188:191], v[56:59]
	v_mfma_f32_16x16x32_bf16 v[56:59], v[160:163], v[184:187], v[56:59]
	v_mfma_f32_16x16x32_bf16 v[52:55], v[168:171], v[184:187], v[52:55]
	v_mfma_f32_16x16x32_bf16 v[52:55], v[172:175], v[188:191], v[52:55]
	v_mfma_f32_16x16x32_bf16 v[48:51], v[180:183], v[188:191], v[48:51]
	v_mfma_f32_16x16x32_bf16 v[48:51], v[176:179], v[184:187], v[48:51]
	v_mfma_f32_16x16x32_bf16 v[32:35], v[176:179], v[192:195], v[32:35]
	v_mfma_f32_16x16x32_bf16 v[32:35], v[180:183], v[196:199], v[32:35]
	v_mfma_f32_16x16x32_bf16 v[36:39], v[172:175], v[196:199], v[36:39]
	v_mfma_f32_16x16x32_bf16 v[36:39], v[168:171], v[192:195], v[36:39]
	v_mfma_f32_16x16x32_bf16 v[40:43], v[160:163], v[192:195], v[40:43]
	v_mfma_f32_16x16x32_bf16 v[40:43], v[164:167], v[196:199], v[40:43]
	v_mfma_f32_16x16x32_bf16 v[44:47], v[156:159], v[196:199], v[44:47]
	v_mfma_f32_16x16x32_bf16 v[44:47], v[152:155], v[192:195], v[44:47]
	s_setprio 0
	s_setprio 1
	v_mfma_f32_16x16x32_bf16 v[28:31], v[152:155], v[200:203], v[28:31]
	v_mfma_f32_16x16x32_bf16 v[28:31], v[156:159], v[208:211], v[28:31]
	v_mfma_f32_16x16x32_bf16 v[24:27], v[164:167], v[208:211], v[24:27]
	v_mfma_f32_16x16x32_bf16 v[24:27], v[160:163], v[200:203], v[24:27]
	v_mfma_f32_16x16x32_bf16 v[20:23], v[168:171], v[200:203], v[20:23]
	v_mfma_f32_16x16x32_bf16 v[20:23], v[172:175], v[208:211], v[20:23]
	v_mfma_f32_16x16x32_bf16 v[16:19], v[180:183], v[208:211], v[16:19]
	v_mfma_f32_16x16x32_bf16 v[16:19], v[176:179], v[200:203], v[16:19]
	v_mfma_f32_16x16x32_bf16 v[0:3], v[176:179], v[212:215], v[0:3]
	v_mfma_f32_16x16x32_bf16 v[0:3], v[180:183], v[216:219], v[0:3]
	v_mfma_f32_16x16x32_bf16 v[4:7], v[172:175], v[216:219], v[4:7]
	v_mfma_f32_16x16x32_bf16 v[4:7], v[168:171], v[212:215], v[4:7]
	v_mfma_f32_16x16x32_bf16 v[8:11], v[160:163], v[212:215], v[8:11]
	v_mfma_f32_16x16x32_bf16 v[8:11], v[164:167], v[216:219], v[8:11]
	v_mfma_f32_16x16x32_bf16 v[12:15], v[156:159], v[216:219], v[12:15]
	v_mfma_f32_16x16x32_bf16 v[12:15], v[152:155], v[212:215], v[12:15]
	s_setprio 0
	s_barrier
	s_add_u32 s44, s44, 0x100
	s_addc_u32 s45, s45, 0
	s_add_u32 s79, s79, 0x100
	s_addc_u32 s82, s82, 0
	s_cmp_ge_i32 s83, s61
	s_mov_b32 s46, s83
	s_cbranch_scc0 .LBB0_1161

; #define PG8_STAGE(bufoff, gbase, voff) do { _Pragma("unroll") for (int _i = 0; _i < 2; ++_i) \
;         __builtin_amdgcn_global_load_lds((const unsigned*)((const char*)(gbase) + (voff)[_i]), (LAS unsigned*)(lds + (bufoff) + ldsw + _i * 8192), 16, 0, 0); } while (0)
; #define PG8_LDA(dst, b, h) do { _Pragma("unroll") for (int m = 0; m < 4; ++m) _Pragma("unroll") for (int k = 0; k < 2; ++k) dst[m][k] = *(const LAS bf16x8*)(lds + PG8_SA(b, h) + aoff + m * 2048 + k * 1024); } while (0)
; #define PG8_LDB(dst, b, h) do { _Pragma("unroll") for (int n = 0; n < 2; ++n) _Pragma("unroll") for (int k = 0; k < 2; ++k) dst[n][k] = *(const LAS bf16x8*)(lds + PG8_SB(b, h) + boff + n * 2048 + k * 1024); } while (0)
; #define PG8_MMA(ai, bj, At, Bt) do { __builtin_amdgcn_s_setprio(1); _Pragma("unroll") for (int m = 0; m < 4; ++m) _Pragma("unroll") for (int n = 0; n < 2; ++n) _Pragma("unroll") for (int k = 0; k < 2; ++k) \
;         acc[ai][bj][m][n] = __builtin_amdgcn_mfma_f32_16x16x32_bf16(Bt[n][k], At[m][k], acc[ai][bj][m][n], 0, 0, 0); __builtin_amdgcn_s_setprio(0); } while (0)
; #define PG8_WAIT_V(n) asm volatile("s_waitcnt vmcnt(" #n ")" ::: "memory")
; #define PG8_WAIT_L(n) asm volatile("s_waitcnt lgkmcnt(" #n ")" ::: "memory")
; #define PG8_BAR __builtin_amdgcn_s_barrier()
; #define PG8_SCHED __builtin_amdgcn_sched_barrier(0)
; template <class Epi>
; __device__ __forceinline__ void gemm_phase(LAS unsigned char* lds, const Gemm g, const StaticOrder& S, const Epi& E) {
;     ...
;             const bool last = (t == nt - 2);
;             const char* a1 = cA + (size_t)(t + 1) * kstep;
;             const char* a2 = last ? nA : cA + (size_t)(t + 2) * kstep; const char* b2 = last ? nB : cB + (size_t)(t + 2) * kstep;
;             const char* a3 = a2 + kstep; const char* b3 = b2 + kstep;
;             PG8_LDB(B0, 0, 0); PG8_LDB(B1, 0, 1); PG8_SCHED; PG8_LDA(At, 0, 0); PG8_STAGE(PG8_SA(1, 1), a1 + hstepA, voffA);
;             PG8_WAIT_V(8); PG8_WAIT_L(0); PG8_BAR; PG8_MMA(0, 0, At, B0); PG8_MMA(0, 1, At, B1); PG8_BAR; PG8_SCHED;
;             PG8_LDA(At, 0, 1); PG8_STAGE(PG8_SB(0, 0), b2, voffB); PG8_STAGE(PG8_SB(0, 1), b2 + hstepB, voffB); PG8_STAGE(PG8_SA(0, 0), a2, voffA);
;             PG8_WAIT_V(8); PG8_WAIT_L(0); PG8_BAR; PG8_MMA(1, 0, At, B0); PG8_MMA(1, 1, At, B1); PG8_BAR; PG8_SCHED;
.LBB0_1244:
	ds_read_b128 v[150:153], v187
	ds_read_b128 v[154:157], v187 offset:1024
	ds_read_b128 v[158:161], v187 offset:2048
	ds_read_b128 v[162:165], v187 offset:3072
	ds_read_b128 v[166:169], v188
	ds_read_b128 v[170:173], v188 offset:1024
	ds_read_b128 v[174:177], v188 offset:2048
	ds_read_b128 v[178:181], v188 offset:3072
	s_add_i32 s84, s52, 2
	s_add_u32 s12, s4, 0x100
	s_addc_u32 s13, s5, 0
	s_cmp_eq_u32 s67, s52
	s_cselect_b32 s52, s50, s1
	s_cselect_b32 s55, s49, s13
	s_cselect_b32 s54, s48, s12
	s_cselect_b32 s53, s51, s77
	v_lshl_add_u64 v[224:225], s[4:5], 0, v[142:143]
	s_add_i32 m0, s59, 0xc000
	ds_read_b128 v[182:185], v189
	ds_read_b128 v[192:195], v189 offset:1024
	ds_read_b128 v[196:199], v189 offset:2048
	ds_read_b128 v[200:203], v189 offset:3072
	ds_read_b128 v[208:211], v189 offset:4096
	ds_read_b128 v[212:215], v189 offset:5120
	ds_read_b128 v[216:219], v189 offset:6144
	ds_read_b128 v[220:223], v189 offset:7168
	global_load_lds_dwordx4 v[224:225], off
	v_lshl_add_u64 v[224:225], s[4:5], 0, v[144:145]
	s_add_i32 m0, s59, 0xe000
	s_nop 0
	global_load_lds_dwordx4 v[224:225], off
	s_waitcnt vmcnt(8) lgkmcnt(0)
	s_barrier
	s_setprio 1
	v_mfma_f32_16x16x32_bf16 v[124:127], v[150:153], v[182:185], v[124:127]
	v_mfma_f32_16x16x32_bf16 v[124:127], v[154:157], v[192:195], v[124:127]
	v_mfma_f32_16x16x32_bf16 v[120:123], v[162:165], v[192:195], v[120:123]
	v_mfma_f32_16x16x32_bf16 v[120:123], v[158:161], v[182:185], v[120:123]
	v_mfma_f32_16x16x32_bf16 v[108:111], v[166:169], v[182:185], v[108:111]
	v_mfma_f32_16x16x32_bf16 v[108:111], v[170:173], v[192:195], v[108:111]
	v_mfma_f32_16x16x32_bf16 v[100:103], v[178:181], v[192:195], v[100:103]
	v_mfma_f32_16x16x32_bf16 v[100:103], v[174:177], v[182:185], v[100:103]
	v_mfma_f32_16x16x32_bf16 v[84:87], v[174:177], v[196:199], v[84:87]
	v_mfma_f32_16x16x32_bf16 v[84:87], v[178:181], v[200:203], v[84:87]
	v_mfma_f32_16x16x32_bf16 v[92:95], v[170:173], v[200:203], v[92:95]
	v_mfma_f32_16x16x32_bf16 v[92:95], v[166:169], v[196:199], v[92:95]
	v_mfma_f32_16x16x32_bf16 v[112:115], v[158:161], v[196:199], v[112:115]
	v_mfma_f32_16x16x32_bf16 v[112:115], v[162:165], v[200:203], v[112:115]
	v_mfma_f32_16x16x32_bf16 v[116:119], v[154:157], v[200:203], v[116:119]
	v_mfma_f32_16x16x32_bf16 v[116:119], v[150:153], v[196:199], v[116:119]
	s_setprio 0
	s_setprio 1
	v_mfma_f32_16x16x32_bf16 v[104:107], v[150:153], v[208:211], v[104:107]
	v_mfma_f32_16x16x32_bf16 v[104:107], v[154:157], v[212:215], v[104:107]
	v_mfma_f32_16x16x32_bf16 v[96:99], v[162:165], v[212:215], v[96:99]
	v_mfma_f32_16x16x32_bf16 v[96:99], v[158:161], v[208:211], v[96:99]
	v_mfma_f32_16x16x32_bf16 v[76:79], v[166:169], v[208:211], v[76:79]
	v_mfma_f32_16x16x32_bf16 v[76:79], v[170:173], v[212:215], v[76:79]
	v_mfma_f32_16x16x32_bf16 v[72:75], v[178:181], v[212:215], v[72:75]
	v_mfma_f32_16x16x32_bf16 v[72:75], v[174:177], v[208:211], v[72:75]
	v_mfma_f32_16x16x32_bf16 v[64:67], v[174:177], v[216:219], v[64:67]
	v_mfma_f32_16x16x32_bf16 v[64:67], v[178:181], v[220:223], v[64:67]
	v_mfma_f32_16x16x32_bf16 v[68:71], v[170:173], v[220:223], v[68:71]
	v_mfma_f32_16x16x32_bf16 v[68:71], v[166:169], v[216:219], v[68:71]
	v_mfma_f32_16x16x32_bf16 v[80:83], v[158:161], v[216:219], v[80:83]
	v_mfma_f32_16x16x32_bf16 v[80:83], v[162:165], v[220:223], v[80:83]
	v_mfma_f32_16x16x32_bf16 v[88:91], v[154:157], v[220:223], v[88:91]
	v_mfma_f32_16x16x32_bf16 v[88:91], v[150:153], v[216:219], v[88:91]
	s_setprio 0
	s_barrier
	s_add_i32 s4, s70, s58
	v_lshl_add_u64 v[224:225], s[52:53], 0, v[130:131]
	s_mov_b32 m0, s4
	ds_read_b128 v[182:185], v189 offset:16384
	ds_read_b128 v[192:195], v189 offset:17408
	ds_read_b128 v[196:199], v189 offset:18432
	ds_read_b128 v[200:203], v189 offset:19456
	ds_read_b128 v[208:211], v189 offset:20480
	ds_read_b128 v[212:215], v189 offset:21504
	ds_read_b128 v[216:219], v189 offset:22528
	ds_read_b128 v[220:223], v189 offset:23552
	global_load_lds_dwordx4 v[224:225], off
	s_add_i32 m0, s4, 0x2000
	s_add_u32 s4, s52, 0x158000
	v_lshl_add_u64 v[226:227], s[52:53], 0, v[134:135]
	s_addc_u32 s5, s53, 0
	s_add_i32 s85, s71, s58
	global_load_lds_dwordx4 v[226:227], off
	v_lshl_add_u64 v[230:231], s[4:5], 0, v[130:131]
	s_mov_b32 m0, s85
	v_lshl_add_u64 v[232:233], s[54:55], 0, v[132:133]
	global_load_lds_dwordx4 v[230:231], off
	v_lshl_add_u64 v[230:231], s[4:5], 0, v[134:135]
	s_add_i32 m0, s85, 0x2000
	s_nop 0
	global_load_lds_dwordx4 v[230:231], off
	v_lshl_add_u64 v[230:231], s[54:55], 0, v[128:129]
	s_mov_b32 m0, s59
	s_nop 0
	global_load_lds_dwordx4 v[230:231], off
	s_mov_b32 m0, s60
	s_nop 0
	global_load_lds_dwordx4 v[232:233], off
	s_waitcnt vmcnt(8) lgkmcnt(0)
	s_barrier
; #define PG8_STAGE(bufoff, gbase, voff) do { _Pragma("unroll") for (int _i = 0; _i < 2; ++_i) \
;         __builtin_amdgcn_global_load_lds((const unsigned*)((const char*)(gbase) + (voff)[_i]), (LAS unsigned*)(lds + (bufoff) + ldsw + _i * 8192), 16, 0, 0); } while (0)
; #define PG8_LDA(dst, b, h) do { _Pragma("unroll") for (int m = 0; m < 4; ++m) _Pragma("unroll") for (int k = 0; k < 2; ++k) dst[m][k] = *(const LAS bf16x8*)(lds + PG8_SA(b, h) + aoff + m * 2048 + k * 1024); } while (0)
; #define PG8_LDB(dst, b, h) do { _Pragma("unroll") for (int n = 0; n < 2; ++n) _Pragma("unroll") for (int k = 0; k < 2; ++k) dst[n][k] = *(const LAS bf16x8*)(lds + PG8_SB(b, h) + boff + n * 2048 + k * 1024); } while (0)
; #define PG8_MMA(ai, bj, At, Bt) do { __builtin_amdgcn_s_setprio(1); _Pragma("unroll") for (int m = 0; m < 4; ++m) _Pragma("unroll") for (int n = 0; n < 2; ++n) _Pragma("unroll") for (int k = 0; k < 2; ++k) \
;         acc[ai][bj][m][n] = __builtin_amdgcn_mfma_f32_16x16x32_bf16(Bt[n][k], At[m][k], acc[ai][bj][m][n], 0, 0, 0); __builtin_amdgcn_s_setprio(0); } while (0)
; #define PG8_WAIT_V(n) asm volatile("s_waitcnt vmcnt(" #n ")" ::: "memory")
; #define PG8_WAIT_L(n) asm volatile("s_waitcnt lgkmcnt(" #n ")" ::: "memory")
; #define PG8_BAR __builtin_amdgcn_s_barrier()
; #define PG8_SCHED __builtin_amdgcn_sched_barrier(0)
; template <class Epi>
; __device__ __forceinline__ void gemm_phase(LAS unsigned char* lds, const Gemm g, const StaticOrder& S, const Epi& E) {
;     ...
;             PG8_WAIT_V(8); PG8_WAIT_L(0); PG8_BAR; PG8_MMA(1, 0, At, B0); PG8_MMA(1, 1, At, B1); PG8_BAR; PG8_SCHED;
;             PG8_LDB(B0, 1, 0); PG8_LDB(B1, 1, 1); PG8_SCHED; PG8_LDA(At, 1, 0); PG8_STAGE(PG8_SA(0, 1), a2 + hstepA, voffA);
;             PG8_WAIT_V(8); PG8_WAIT_L(0); PG8_BAR; PG8_MMA(0, 0, At, B0); PG8_MMA(0, 1, At, B1); PG8_BAR; PG8_SCHED;
	s_setprio 1
	v_mfma_f32_16x16x32_bf16 v[60:63], v[150:153], v[182:185], v[60:63]
	v_mfma_f32_16x16x32_bf16 v[60:63], v[154:157], v[192:195], v[60:63]
	v_mfma_f32_16x16x32_bf16 v[56:59], v[162:165], v[192:195], v[56:59]
	v_mfma_f32_16x16x32_bf16 v[56:59], v[158:161], v[182:185], v[56:59]
	v_mfma_f32_16x16x32_bf16 v[44:47], v[166:169], v[182:185], v[44:47]
	v_mfma_f32_16x16x32_bf16 v[44:47], v[170:173], v[192:195], v[44:47]
	v_mfma_f32_16x16x32_bf16 v[36:39], v[178:181], v[192:195], v[36:39]
	v_mfma_f32_16x16x32_bf16 v[36:39], v[174:177], v[182:185], v[36:39]
	v_mfma_f32_16x16x32_bf16 v[20:23], v[174:177], v[196:199], v[20:23]
	v_mfma_f32_16x16x32_bf16 v[20:23], v[178:181], v[200:203], v[20:23]
	v_mfma_f32_16x16x32_bf16 v[28:31], v[170:173], v[200:203], v[28:31]
	v_mfma_f32_16x16x32_bf16 v[28:31], v[166:169], v[196:199], v[28:31]
	v_mfma_f32_16x16x32_bf16 v[48:51], v[158:161], v[196:199], v[48:51]
	v_mfma_f32_16x16x32_bf16 v[48:51], v[162:165], v[200:203], v[48:51]
	v_mfma_f32_16x16x32_bf16 v[52:55], v[154:157], v[200:203], v[52:55]
	v_mfma_f32_16x16x32_bf16 v[52:55], v[150:153], v[196:199], v[52:55]
	s_setprio 0
	s_setprio 1
	v_mfma_f32_16x16x32_bf16 v[40:43], v[150:153], v[208:211], v[40:43]
	v_mfma_f32_16x16x32_bf16 v[40:43], v[154:157], v[212:215], v[40:43]
	v_mfma_f32_16x16x32_bf16 v[32:35], v[162:165], v[212:215], v[32:35]
	v_mfma_f32_16x16x32_bf16 v[32:35], v[158:161], v[208:211], v[32:35]
	v_mfma_f32_16x16x32_bf16 v[12:15], v[166:169], v[208:211], v[12:15]
	v_mfma_f32_16x16x32_bf16 v[12:15], v[170:173], v[212:215], v[12:15]
	v_mfma_f32_16x16x32_bf16 v[8:11], v[178:181], v[212:215], v[8:11]
	v_mfma_f32_16x16x32_bf16 v[8:11], v[174:177], v[208:211], v[8:11]
	v_mfma_f32_16x16x32_bf16 v[0:3], v[174:177], v[216:219], v[0:3]
	v_mfma_f32_16x16x32_bf16 v[0:3], v[178:181], v[220:223], v[0:3]
	v_mfma_f32_16x16x32_bf16 v[4:7], v[170:173], v[220:223], v[4:7]
	v_mfma_f32_16x16x32_bf16 v[4:7], v[166:169], v[216:219], v[4:7]
	v_mfma_f32_16x16x32_bf16 v[16:19], v[158:161], v[216:219], v[16:19]
	v_mfma_f32_16x16x32_bf16 v[16:19], v[162:165], v[220:223], v[16:19]
	v_mfma_f32_16x16x32_bf16 v[24:27], v[154:157], v[220:223], v[24:27]
	v_mfma_f32_16x16x32_bf16 v[24:27], v[150:153], v[216:219], v[24:27]
	s_setprio 0
	s_barrier
	s_add_i32 s85, 0, 0x18000
	s_add_i32 s86, 0, 0x1c000
	v_add_u32_e32 v162, s85, v186
	v_add_u32_e32 v178, s86, v186
	ds_read_b128 v[150:153], v162
	ds_read_b128 v[154:157], v162 offset:1024
	ds_read_b128 v[158:161], v162 offset:2048
	ds_read_b128 v[162:165], v162 offset:3072
	ds_read_b128 v[166:169], v178
	ds_read_b128 v[170:173], v178 offset:1024
	ds_read_b128 v[174:177], v178 offset:2048
	ds_read_b128 v[178:181], v178 offset:3072
	s_add_u32 s4, s54, 0x158000
	s_addc_u32 s5, s55, 0
	s_mov_b32 m0, s61
	v_lshl_add_u64 v[234:235], s[4:5], 0, v[128:129]
	ds_read_b128 v[182:185], v189 offset:32768
	ds_read_b128 v[192:195], v189 offset:33792
	ds_read_b128 v[196:199], v189 offset:34816
	ds_read_b128 v[200:203], v189 offset:35840
	ds_read_b128 v[208:211], v189 offset:36864
	ds_read_b128 v[212:215], v189 offset:37888
	ds_read_b128 v[216:219], v189 offset:38912
	ds_read_b128 v[220:223], v189 offset:39936
	global_load_lds_dwordx4 v[234:235], off
	v_lshl_add_u64 v[234:235], s[4:5], 0, v[132:133]
	s_mov_b32 m0, s62
	s_nop 0
	global_load_lds_dwordx4 v[234:235], off
	s_waitcnt vmcnt(8) lgkmcnt(0)
	s_barrier
	s_setprio 1
	v_mfma_f32_16x16x32_bf16 v[124:127], v[150:153], v[182:185], v[124:127]
	v_mfma_f32_16x16x32_bf16 v[124:127], v[154:157], v[192:195], v[124:127]
	v_mfma_f32_16x16x32_bf16 v[120:123], v[162:165], v[192:195], v[120:123]
	v_mfma_f32_16x16x32_bf16 v[120:123], v[158:161], v[182:185], v[120:123]
	v_mfma_f32_16x16x32_bf16 v[108:111], v[166:169], v[182:185], v[108:111]
	v_mfma_f32_16x16x32_bf16 v[108:111], v[170:173], v[192:195], v[108:111]
	v_mfma_f32_16x16x32_bf16 v[100:103], v[178:181], v[192:195], v[100:103]
	v_mfma_f32_16x16x32_bf16 v[100:103], v[174:177], v[182:185], v[100:103]
	v_mfma_f32_16x16x32_bf16 v[84:87], v[174:177], v[196:199], v[84:87]
	v_mfma_f32_16x16x32_bf16 v[84:87], v[178:181], v[200:203], v[84:87]
	v_mfma_f32_16x16x32_bf16 v[92:95], v[170:173], v[200:203], v[92:95]
	v_mfma_f32_16x16x32_bf16 v[92:95], v[166:169], v[196:199], v[92:95]
	v_mfma_f32_16x16x32_bf16 v[112:115], v[158:161], v[196:199], v[112:115]
	v_mfma_f32_16x16x32_bf16 v[112:115], v[162:165], v[200:203], v[112:115]
	v_mfma_f32_16x16x32_bf16 v[116:119], v[154:157], v[200:203], v[116:119]
	v_mfma_f32_16x16x32_bf16 v[116:119], v[150:153], v[196:199], v[116:119]
	s_setprio 0
	s_setprio 1
	v_mfma_f32_16x16x32_bf16 v[104:107], v[150:153], v[208:211], v[104:107]
	v_mfma_f32_16x16x32_bf16 v[104:107], v[154:157], v[212:215], v[104:107]
	v_mfma_f32_16x16x32_bf16 v[96:99], v[162:165], v[212:215], v[96:99]
	v_mfma_f32_16x16x32_bf16 v[96:99], v[158:161], v[208:211], v[96:99]
	v_mfma_f32_16x16x32_bf16 v[76:79], v[166:169], v[208:211], v[76:79]
	v_mfma_f32_16x16x32_bf16 v[76:79], v[170:173], v[212:215], v[76:79]
	v_mfma_f32_16x16x32_bf16 v[72:75], v[178:181], v[212:215], v[72:75]
	v_mfma_f32_16x16x32_bf16 v[72:75], v[174:177], v[208:211], v[72:75]
	v_mfma_f32_16x16x32_bf16 v[64:67], v[174:177], v[216:219], v[64:67]
	v_mfma_f32_16x16x32_bf16 v[64:67], v[178:181], v[220:223], v[64:67]
	v_mfma_f32_16x16x32_bf16 v[68:71], v[170:173], v[220:223], v[68:71]
	v_mfma_f32_16x16x32_bf16 v[68:71], v[166:169], v[216:219], v[68:71]
	v_mfma_f32_16x16x32_bf16 v[80:83], v[158:161], v[216:219], v[80:83]
	v_mfma_f32_16x16x32_bf16 v[80:83], v[162:165], v[220:223], v[80:83]
	v_mfma_f32_16x16x32_bf16 v[88:91], v[154:157], v[220:223], v[88:91]
	v_mfma_f32_16x16x32_bf16 v[88:91], v[150:153], v[216:219], v[88:91]
	s_setprio 0
	s_barrier
; #define PG8_STAGE(bufoff, gbase, voff) do { _Pragma("unroll") for (int _i = 0; _i < 2; ++_i) \
;         __builtin_amdgcn_global_load_lds((const unsigned*)((const char*)(gbase) + (voff)[_i]), (LAS unsigned*)(lds + (bufoff) + ldsw + _i * 8192), 16, 0, 0); } while (0)
; #define PG8_LDA(dst, b, h) do { _Pragma("unroll") for (int m = 0; m < 4; ++m) _Pragma("unroll") for (int k = 0; k < 2; ++k) dst[m][k] = *(const LAS bf16x8*)(lds + PG8_SA(b, h) + aoff + m * 2048 + k * 1024); } while (0)
; #define PG8_MMA(ai, bj, At, Bt) do { __builtin_amdgcn_s_setprio(1); _Pragma("unroll") for (int m = 0; m < 4; ++m) _Pragma("unroll") for (int n = 0; n < 2; ++n) _Pragma("unroll") for (int k = 0; k < 2; ++k) \
;         acc[ai][bj][m][n] = __builtin_amdgcn_mfma_f32_16x16x32_bf16(Bt[n][k], At[m][k], acc[ai][bj][m][n], 0, 0, 0); __builtin_amdgcn_s_setprio(0); } while (0)
; #define PG8_WAIT_V(n) asm volatile("s_waitcnt vmcnt(" #n ")" ::: "memory")
; #define PG8_WAIT_L(n) asm volatile("s_waitcnt lgkmcnt(" #n ")" ::: "memory")
; #define PG8_BAR __builtin_amdgcn_s_barrier()
; #define PG8_SCHED __builtin_amdgcn_sched_barrier(0)
; template <class Epi>
; __device__ __forceinline__ void gemm_phase(LAS unsigned char* lds, const Gemm g, const StaticOrder& S, const Epi& E) {
;     ...
;             PG8_LDA(At, 1, 1); PG8_STAGE(PG8_SB(1, 0), b3, voffB); PG8_STAGE(PG8_SB(1, 1), b3 + hstepB, voffB); PG8_STAGE(PG8_SA(1, 0), a3, voffA);
;             PG8_WAIT_V(8); PG8_WAIT_L(0); PG8_BAR; PG8_MMA(1, 0, At, B0); PG8_MMA(1, 1, At, B1); PG8_BAR; PG8_SCHED;
;         }
	s_add_i32 s4, s85, s58
	v_lshl_add_u64 v[224:225], v[224:225], 0, s[16:17]
	s_mov_b32 m0, s4
	ds_read_b128 v[182:185], v189 offset:49152
	ds_read_b128 v[192:195], v189 offset:50176
	ds_read_b128 v[196:199], v189 offset:51200
	ds_read_b128 v[200:203], v189 offset:52224
	ds_read_b128 v[208:211], v189 offset:53248
	ds_read_b128 v[212:215], v189 offset:54272
	ds_read_b128 v[216:219], v189 offset:55296
	ds_read_b128 v[220:223], v189 offset:56320
	global_load_lds_dwordx4 v[224:225], off
	s_add_i32 m0, s4, 0x2000
	s_add_u32 s4, s52, 0x158080
	v_lshl_add_u64 v[224:225], v[226:227], 0, s[16:17]
	s_addc_u32 s5, s53, 0
	s_add_i32 s52, s86, s58
	global_load_lds_dwordx4 v[224:225], off
	v_lshl_add_u64 v[224:225], s[4:5], 0, v[130:131]
	s_mov_b32 m0, s52
	s_nop 0
	global_load_lds_dwordx4 v[224:225], off
	v_lshl_add_u64 v[224:225], s[4:5], 0, v[134:135]
	s_add_i32 m0, s52, 0x2000
	s_nop 0
	global_load_lds_dwordx4 v[224:225], off
	v_lshl_add_u64 v[224:225], v[230:231], 0, s[16:17]
	s_mov_b32 m0, s65
	s_nop 0
	global_load_lds_dwordx4 v[224:225], off
	v_lshl_add_u64 v[224:225], v[232:233], 0, s[16:17]
	s_mov_b32 m0, s66
	s_nop 0
	global_load_lds_dwordx4 v[224:225], off
	s_waitcnt vmcnt(8) lgkmcnt(0)
	s_barrier
	s_setprio 1
	v_mfma_f32_16x16x32_bf16 v[60:63], v[150:153], v[182:185], v[60:63]
	v_mfma_f32_16x16x32_bf16 v[60:63], v[154:157], v[192:195], v[60:63]
	v_mfma_f32_16x16x32_bf16 v[56:59], v[162:165], v[192:195], v[56:59]
	v_mfma_f32_16x16x32_bf16 v[56:59], v[158:161], v[182:185], v[56:59]
	v_mfma_f32_16x16x32_bf16 v[44:47], v[166:169], v[182:185], v[44:47]
	v_mfma_f32_16x16x32_bf16 v[44:47], v[170:173], v[192:195], v[44:47]
	v_mfma_f32_16x16x32_bf16 v[36:39], v[178:181], v[192:195], v[36:39]
	v_mfma_f32_16x16x32_bf16 v[36:39], v[174:177], v[182:185], v[36:39]
	v_mfma_f32_16x16x32_bf16 v[20:23], v[174:177], v[196:199], v[20:23]
	v_mfma_f32_16x16x32_bf16 v[20:23], v[178:181], v[200:203], v[20:23]
	v_mfma_f32_16x16x32_bf16 v[28:31], v[170:173], v[200:203], v[28:31]
	v_mfma_f32_16x16x32_bf16 v[28:31], v[166:169], v[196:199], v[28:31]
	v_mfma_f32_16x16x32_bf16 v[48:51], v[158:161], v[196:199], v[48:51]
	v_mfma_f32_16x16x32_bf16 v[48:51], v[162:165], v[200:203], v[48:51]
	v_mfma_f32_16x16x32_bf16 v[52:55], v[154:157], v[200:203], v[52:55]
	v_mfma_f32_16x16x32_bf16 v[52:55], v[150:153], v[196:199], v[52:55]
	s_setprio 0
	s_setprio 1
	v_mfma_f32_16x16x32_bf16 v[40:43], v[150:153], v[208:211], v[40:43]
	v_mfma_f32_16x16x32_bf16 v[40:43], v[154:157], v[212:215], v[40:43]
	v_mfma_f32_16x16x32_bf16 v[32:35], v[162:165], v[212:215], v[32:35]
	v_mfma_f32_16x16x32_bf16 v[32:35], v[158:161], v[208:211], v[32:35]
	v_mfma_f32_16x16x32_bf16 v[12:15], v[166:169], v[208:211], v[12:15]
	v_mfma_f32_16x16x32_bf16 v[12:15], v[170:173], v[212:215], v[12:15]
	v_mfma_f32_16x16x32_bf16 v[8:11], v[178:181], v[212:215], v[8:11]
	v_mfma_f32_16x16x32_bf16 v[8:11], v[174:177], v[208:211], v[8:11]
	v_mfma_f32_16x16x32_bf16 v[0:3], v[174:177], v[216:219], v[0:3]
	v_mfma_f32_16x16x32_bf16 v[0:3], v[178:181], v[220:223], v[0:3]
	v_mfma_f32_16x16x32_bf16 v[4:7], v[170:173], v[220:223], v[4:7]
	v_mfma_f32_16x16x32_bf16 v[4:7], v[166:169], v[216:219], v[4:7]
	v_mfma_f32_16x16x32_bf16 v[16:19], v[158:161], v[216:219], v[16:19]
	v_mfma_f32_16x16x32_bf16 v[16:19], v[162:165], v[220:223], v[16:19]
	v_mfma_f32_16x16x32_bf16 v[24:27], v[154:157], v[220:223], v[24:27]
	v_mfma_f32_16x16x32_bf16 v[24:27], v[150:153], v[216:219], v[24:27]
	s_setprio 0
	s_barrier
	s_add_u32 s1, s1, 0x100
	s_addc_u32 s77, s77, 0
	s_cmp_ge_i32 s84, s64
	s_mov_b64 s[4:5], s[12:13]
	s_mov_b32 s52, s84
	s_cbranch_scc0 .LBB0_1244
	v_pk_mul_f32 v[170:171], v[126:127], 0.5 op_sel_hi:[1,0]
	v_pk_mul_f32 v[172:173], v[124:125], 0.5 op_sel_hi:[1,0]
	v_pk_mul_f32 v[174:175], v[122:123], 0.5 op_sel_hi:[1,0]
	v_pk_mul_f32 v[176:177], v[120:121], 0.5 op_sel_hi:[1,0]
	v_pk_mul_f32 v[178:179], v[110:111], 0.5 op_sel_hi:[1,0]
	v_pk_mul_f32 v[180:181], v[108:109], 0.5 op_sel_hi:[1,0]
	v_pk_mul_f32 v[182:183], v[102:103], 0.5 op_sel_hi:[1,0]
	v_pk_mul_f32 v[184:185], v[100:101], 0.5 op_sel_hi:[1,0]
	v_pk_mul_f32 v[160:161], v[118:119], 0.5 op_sel_hi:[1,0]
	v_pk_mul_f32 v[158:159], v[116:117], 0.5 op_sel_hi:[1,0]
	v_pk_mul_f32 v[156:157], v[114:115], 0.5 op_sel_hi:[1,0]
	v_pk_mul_f32 v[154:155], v[112:113], 0.5 op_sel_hi:[1,0]
	v_pk_mul_f32 v[168:169], v[94:95], 0.5 op_sel_hi:[1,0]
	v_pk_mul_f32 v[166:167], v[92:93], 0.5 op_sel_hi:[1,0]
	v_pk_mul_f32 v[164:165], v[86:87], 0.5 op_sel_hi:[1,0]
	v_pk_mul_f32 v[162:163], v[84:85], 0.5 op_sel_hi:[1,0]
	v_pk_mul_f32 v[116:117], v[106:107], 0.5 op_sel_hi:[1,0]
	v_pk_mul_f32 v[118:119], v[104:105], 0.5 op_sel_hi:[1,0]
	v_pk_mul_f32 v[120:121], v[98:99], 0.5 op_sel_hi:[1,0]
	v_pk_mul_f32 v[122:123], v[96:97], 0.5 op_sel_hi:[1,0]
	v_pk_mul_f32 v[124:125], v[78:79], 0.5 op_sel_hi:[1,0]
	v_pk_mul_f32 v[126:127], v[76:77], 0.5 op_sel_hi:[1,0]
	v_pk_mul_f32 v[150:151], v[74:75], 0.5 op_sel_hi:[1,0]
	v_pk_mul_f32 v[152:153], v[72:73], 0.5 op_sel_hi:[1,0]
	v_pk_mul_f32 v[104:105], v[90:91], 0.5 op_sel_hi:[1,0]
	v_pk_mul_f32 v[102:103], v[88:89], 0.5 op_sel_hi:[1,0]
	v_pk_mul_f32 v[100:101], v[82:83], 0.5 op_sel_hi:[1,0]
	v_pk_mul_f32 v[98:99], v[80:81], 0.5 op_sel_hi:[1,0]
	v_pk_mul_f32 v[112:113], v[70:71], 0.5 op_sel_hi:[1,0]
	v_pk_mul_f32 v[110:111], v[68:69], 0.5 op_sel_hi:[1,0]
	v_pk_mul_f32 v[108:109], v[66:67], 0.5 op_sel_hi:[1,0]
	v_pk_mul_f32 v[106:107], v[64:65], 0.5 op_sel_hi:[1,0]
	v_pk_mul_f32 v[80:81], v[62:63], 0.5 op_sel_hi:[1,0]
	v_pk_mul_f32 v[82:83], v[60:61], 0.5 op_sel_hi:[1,0]
	v_pk_mul_f32 v[84:85], v[58:59], 0.5 op_sel_hi:[1,0]
	v_pk_mul_f32 v[86:87], v[56:57], 0.5 op_sel_hi:[1,0]
	v_pk_mul_f32 v[88:89], v[46:47], 0.5 op_sel_hi:[1,0]
	v_pk_mul_f32 v[90:91], v[44:45], 0.5 op_sel_hi:[1,0]
	v_pk_mul_f32 v[92:93], v[38:39], 0.5 op_sel_hi:[1,0]
	v_pk_mul_f32 v[94:95], v[36:37], 0.5 op_sel_hi:[1,0]
	v_pk_mul_f32 v[70:71], v[54:55], 0.5 op_sel_hi:[1,0]
	v_pk_mul_f32 v[68:69], v[52:53], 0.5 op_sel_hi:[1,0]
	v_pk_mul_f32 v[66:67], v[50:51], 0.5 op_sel_hi:[1,0]
	v_pk_mul_f32 v[64:65], v[48:49], 0.5 op_sel_hi:[1,0]
	v_pk_mul_f32 v[78:79], v[30:31], 0.5 op_sel_hi:[1,0]
	v_pk_mul_f32 v[76:77], v[28:29], 0.5 op_sel_hi:[1,0]
	v_pk_mul_f32 v[74:75], v[22:23], 0.5 op_sel_hi:[1,0]
	v_pk_mul_f32 v[72:73], v[20:21], 0.5 op_sel_hi:[1,0]
	v_pk_mul_f32 v[54:55], v[42:43], 0.5 op_sel_hi:[1,0]
	v_pk_mul_f32 v[52:53], v[40:41], 0.5 op_sel_hi:[1,0]
	v_pk_mul_f32 v[50:51], v[34:35], 0.5 op_sel_hi:[1,0]
	v_pk_mul_f32 v[48:49], v[32:33], 0.5 op_sel_hi:[1,0]
	v_pk_mul_f32 v[62:63], v[14:15], 0.5 op_sel_hi:[1,0]
	v_pk_mul_f32 v[60:61], v[12:13], 0.5 op_sel_hi:[1,0]
	v_pk_mul_f32 v[58:59], v[10:11], 0.5 op_sel_hi:[1,0]
	v_pk_mul_f32 v[56:57], v[8:9], 0.5 op_sel_hi:[1,0]
	v_pk_mul_f32 v[38:39], v[26:27], 0.5 op_sel_hi:[1,0]
	v_pk_mul_f32 v[36:37], v[24:25], 0.5 op_sel_hi:[1,0]
	v_pk_mul_f32 v[34:35], v[18:19], 0.5 op_sel_hi:[1,0]
	v_pk_mul_f32 v[32:33], v[16:17], 0.5 op_sel_hi:[1,0]
	v_pk_mul_f32 v[46:47], v[6:7], 0.5 op_sel_hi:[1,0]
	v_pk_mul_f32 v[44:45], v[4:5], 0.5 op_sel_hi:[1,0]
	v_pk_mul_f32 v[42:43], v[2:3], 0.5 op_sel_hi:[1,0]
	v_pk_mul_f32 v[40:41], v[0:1], 0.5 op_sel_hi:[1,0]

; #define PG8_STAGE(bufoff, gbase, voff) do { _Pragma("unroll") for (int _i = 0; _i < 2; ++_i) \
;         __builtin_amdgcn_global_load_lds((const unsigned*)((const char*)(gbase) + (voff)[_i]), (LAS unsigned*)(lds + (bufoff) + ldsw + _i * 8192), 16, 0, 0); } while (0)
; #define PG8_LDA(dst, b, h) do { _Pragma("unroll") for (int m = 0; m < 4; ++m) _Pragma("unroll") for (int k = 0; k < 2; ++k) dst[m][k] = *(const LAS bf16x8*)(lds + PG8_SA(b, h) + aoff + m * 2048 + k * 1024); } while (0)
; #define PG8_LDB(dst, b, h) do { _Pragma("unroll") for (int n = 0; n < 2; ++n) _Pragma("unroll") for (int k = 0; k < 2; ++k) dst[n][k] = *(const LAS bf16x8*)(lds + PG8_SB(b, h) + boff + n * 2048 + k * 1024); } while (0)
; #define PG8_MMA(ai, bj, At, Bt) do { __builtin_amdgcn_s_setprio(1); _Pragma("unroll") for (int m = 0; m < 4; ++m) _Pragma("unroll") for (int n = 0; n < 2; ++n) _Pragma("unroll") for (int k = 0; k < 2; ++k) \
;         acc[ai][bj][m][n] = __builtin_amdgcn_mfma_f32_16x16x32_bf16(Bt[n][k], At[m][k], acc[ai][bj][m][n], 0, 0, 0); __builtin_amdgcn_s_setprio(0); } while (0)
; #define PG8_WAIT_V(n) asm volatile("s_waitcnt vmcnt(" #n ")" ::: "memory")
; #define PG8_WAIT_L(n) asm volatile("s_waitcnt lgkmcnt(" #n ")" ::: "memory")
; #define PG8_BAR __builtin_amdgcn_s_barrier()
; #define PG8_SCHED __builtin_amdgcn_sched_barrier(0)
; template <class Epi>
; __device__ __forceinline__ void gemm_phase(LAS unsigned char* lds, const Gemm g, const StaticOrder& S, const Epi& E) {
;     ...
;             const bool last = (t == nt - 2);
;             const char* a1 = cA + (size_t)(t + 1) * kstep;
;             const char* a2 = last ? nA : cA + (size_t)(t + 2) * kstep; const char* b2 = last ? nB : cB + (size_t)(t + 2) * kstep;
;             const char* a3 = a2 + kstep; const char* b3 = b2 + kstep;
;             PG8_LDB(B0, 0, 0); PG8_LDB(B1, 0, 1); PG8_SCHED; PG8_LDA(At, 0, 0); PG8_STAGE(PG8_SA(1, 1), a1 + hstepA, voffA);
;             PG8_WAIT_V(8); PG8_WAIT_L(0); PG8_BAR; PG8_MMA(0, 0, At, B0); PG8_MMA(0, 1, At, B1); PG8_BAR; PG8_SCHED;
;             PG8_LDA(At, 0, 1); PG8_STAGE(PG8_SB(0, 0), b2, voffB); PG8_STAGE(PG8_SB(0, 1), b2 + hstepB, voffB); PG8_STAGE(PG8_SA(0, 0), a2, voffA);
;             PG8_WAIT_V(8); PG8_WAIT_L(0); PG8_BAR; PG8_MMA(1, 0, At, B0); PG8_MMA(1, 1, At, B1); PG8_BAR; PG8_SCHED;
.LBB0_1338:
	ds_read_b128 v[128:131], v173
	ds_read_b128 v[132:135], v173 offset:1024
	ds_read_b128 v[136:139], v173 offset:2048
	ds_read_b128 v[140:143], v173 offset:3072
	ds_read_b128 v[144:147], v175
	ds_read_b128 v[148:151], v175 offset:1024
	ds_read_b128 v[176:179], v175 offset:2048
	ds_read_b128 v[184:187], v175 offset:3072
	s_add_i32 s20, s10, 2
	s_add_u32 s11, s8, 0xfff80080
	s_addc_u32 s12, s9, -1
	s_cmp_eq_u32 s56, s10
	s_cselect_b32 s10, s17, s18
	s_cselect_b32 s13, s1, s12
	s_cselect_b32 s12, s15, s11
	s_cselect_b32 s11, s16, s19
	v_lshl_add_u64 v[224:225], s[8:9], 0, v[164:165]
	s_add_i32 m0, s47, 0xc000
	ds_read_b128 v[188:191], v181
	ds_read_b128 v[192:195], v181 offset:1024
	ds_read_b128 v[196:199], v181 offset:2048
	ds_read_b128 v[200:203], v181 offset:3072
	ds_read_b128 v[208:211], v181 offset:4096
	ds_read_b128 v[212:215], v181 offset:5120
	ds_read_b128 v[216:219], v181 offset:6144
	ds_read_b128 v[220:223], v181 offset:7168
	global_load_lds_dwordx4 v[224:225], off
	v_lshl_add_u64 v[224:225], s[8:9], 0, v[166:167]
	s_add_i32 m0, s47, 0xe000
	s_nop 0
	global_load_lds_dwordx4 v[224:225], off
	s_waitcnt vmcnt(8) lgkmcnt(0)
	s_barrier
	s_setprio 1
	v_mfma_f32_16x16x32_bf16 v[124:127], v[128:131], v[188:191], v[124:127]
	v_mfma_f32_16x16x32_bf16 v[124:127], v[132:135], v[192:195], v[124:127]
	v_mfma_f32_16x16x32_bf16 v[120:123], v[140:143], v[192:195], v[120:123]
	v_mfma_f32_16x16x32_bf16 v[120:123], v[136:139], v[188:191], v[120:123]
	v_mfma_f32_16x16x32_bf16 v[116:119], v[144:147], v[188:191], v[116:119]
	v_mfma_f32_16x16x32_bf16 v[116:119], v[148:151], v[192:195], v[116:119]
	v_mfma_f32_16x16x32_bf16 v[112:115], v[184:187], v[192:195], v[112:115]
	v_mfma_f32_16x16x32_bf16 v[112:115], v[176:179], v[188:191], v[112:115]
	v_mfma_f32_16x16x32_bf16 v[96:99], v[176:179], v[196:199], v[96:99]
	v_mfma_f32_16x16x32_bf16 v[96:99], v[184:187], v[200:203], v[96:99]
	v_mfma_f32_16x16x32_bf16 v[100:103], v[148:151], v[200:203], v[100:103]
	v_mfma_f32_16x16x32_bf16 v[100:103], v[144:147], v[196:199], v[100:103]
	v_mfma_f32_16x16x32_bf16 v[104:107], v[136:139], v[196:199], v[104:107]
	v_mfma_f32_16x16x32_bf16 v[104:107], v[140:143], v[200:203], v[104:107]
	v_mfma_f32_16x16x32_bf16 v[108:111], v[132:135], v[200:203], v[108:111]
	v_mfma_f32_16x16x32_bf16 v[108:111], v[128:131], v[196:199], v[108:111]
	s_setprio 0
	s_setprio 1
	v_mfma_f32_16x16x32_bf16 v[92:95], v[128:131], v[208:211], v[92:95]
	v_mfma_f32_16x16x32_bf16 v[92:95], v[132:135], v[212:215], v[92:95]
	v_mfma_f32_16x16x32_bf16 v[88:91], v[140:143], v[212:215], v[88:91]
	v_mfma_f32_16x16x32_bf16 v[88:91], v[136:139], v[208:211], v[88:91]
	v_mfma_f32_16x16x32_bf16 v[84:87], v[144:147], v[208:211], v[84:87]
	v_mfma_f32_16x16x32_bf16 v[84:87], v[148:151], v[212:215], v[84:87]
	v_mfma_f32_16x16x32_bf16 v[80:83], v[184:187], v[212:215], v[80:83]
	v_mfma_f32_16x16x32_bf16 v[80:83], v[176:179], v[208:211], v[80:83]
	v_mfma_f32_16x16x32_bf16 v[64:67], v[176:179], v[216:219], v[64:67]
	v_mfma_f32_16x16x32_bf16 v[64:67], v[184:187], v[220:223], v[64:67]
	v_mfma_f32_16x16x32_bf16 v[68:71], v[148:151], v[220:223], v[68:71]
	v_mfma_f32_16x16x32_bf16 v[68:71], v[144:147], v[216:219], v[68:71]
	v_mfma_f32_16x16x32_bf16 v[72:75], v[136:139], v[216:219], v[72:75]
	v_mfma_f32_16x16x32_bf16 v[72:75], v[140:143], v[220:223], v[72:75]
	v_mfma_f32_16x16x32_bf16 v[76:79], v[132:135], v[220:223], v[76:79]
	v_mfma_f32_16x16x32_bf16 v[76:79], v[128:131], v[216:219], v[76:79]
	s_setprio 0
	s_barrier
	s_add_i32 s21, s59, s46
	v_lshl_add_u64 v[224:225], s[10:11], 0, v[154:155]
	s_mov_b32 m0, s21
	ds_read_b128 v[188:191], v181 offset:16384
	ds_read_b128 v[192:195], v181 offset:17408
	ds_read_b128 v[196:199], v181 offset:18432
	ds_read_b128 v[200:203], v181 offset:19456
	ds_read_b128 v[208:211], v181 offset:20480
	ds_read_b128 v[212:215], v181 offset:21504
	ds_read_b128 v[216:219], v181 offset:22528
	ds_read_b128 v[220:223], v181 offset:23552
	global_load_lds_dwordx4 v[224:225], off
	s_add_i32 m0, s21, 0x2000
	s_add_u32 s68, s10, 0x80000
	v_lshl_add_u64 v[226:227], s[10:11], 0, v[158:159]
	s_addc_u32 s69, s11, 0
	s_add_i32 s21, s60, s46
	global_load_lds_dwordx4 v[226:227], off
	v_lshl_add_u64 v[230:231], s[68:69], 0, v[154:155]
	s_mov_b32 m0, s21
	v_lshl_add_u64 v[232:233], s[12:13], 0, v[156:157]
	global_load_lds_dwordx4 v[230:231], off
	v_lshl_add_u64 v[230:231], s[68:69], 0, v[158:159]
	s_add_i32 m0, s21, 0x2000
	s_nop 0
	global_load_lds_dwordx4 v[230:231], off
	v_lshl_add_u64 v[230:231], s[12:13], 0, v[152:153]
	s_mov_b32 m0, s47
	s_nop 0
	global_load_lds_dwordx4 v[230:231], off
	s_mov_b32 m0, s48
	s_nop 0
	global_load_lds_dwordx4 v[232:233], off
	s_waitcnt vmcnt(8) lgkmcnt(0)
	s_barrier
; #define PG8_STAGE(bufoff, gbase, voff) do { _Pragma("unroll") for (int _i = 0; _i < 2; ++_i) \
;         __builtin_amdgcn_global_load_lds((const unsigned*)((const char*)(gbase) + (voff)[_i]), (LAS unsigned*)(lds + (bufoff) + ldsw + _i * 8192), 16, 0, 0); } while (0)
; #define PG8_LDA(dst, b, h) do { _Pragma("unroll") for (int m = 0; m < 4; ++m) _Pragma("unroll") for (int k = 0; k < 2; ++k) dst[m][k] = *(const LAS bf16x8*)(lds + PG8_SA(b, h) + aoff + m * 2048 + k * 1024); } while (0)
; #define PG8_LDB(dst, b, h) do { _Pragma("unroll") for (int n = 0; n < 2; ++n) _Pragma("unroll") for (int k = 0; k < 2; ++k) dst[n][k] = *(const LAS bf16x8*)(lds + PG8_SB(b, h) + boff + n * 2048 + k * 1024); } while (0)
; #define PG8_MMA(ai, bj, At, Bt) do { __builtin_amdgcn_s_setprio(1); _Pragma("unroll") for (int m = 0; m < 4; ++m) _Pragma("unroll") for (int n = 0; n < 2; ++n) _Pragma("unroll") for (int k = 0; k < 2; ++k) \
;         acc[ai][bj][m][n] = __builtin_amdgcn_mfma_f32_16x16x32_bf16(Bt[n][k], At[m][k], acc[ai][bj][m][n], 0, 0, 0); __builtin_amdgcn_s_setprio(0); } while (0)
; #define PG8_WAIT_V(n) asm volatile("s_waitcnt vmcnt(" #n ")" ::: "memory")
; #define PG8_WAIT_L(n) asm volatile("s_waitcnt lgkmcnt(" #n ")" ::: "memory")
; #define PG8_BAR __builtin_amdgcn_s_barrier()
; #define PG8_SCHED __builtin_amdgcn_sched_barrier(0)
; template <class Epi>
; __device__ __forceinline__ void gemm_phase(LAS unsigned char* lds, const Gemm g, const StaticOrder& S, const Epi& E) {
;     ...
;             PG8_WAIT_V(8); PG8_WAIT_L(0); PG8_BAR; PG8_MMA(1, 0, At, B0); PG8_MMA(1, 1, At, B1); PG8_BAR; PG8_SCHED;
;             PG8_LDB(B0, 1, 0); PG8_LDB(B1, 1, 1); PG8_SCHED; PG8_LDA(At, 1, 0); PG8_STAGE(PG8_SA(0, 1), a2 + hstepA, voffA);
;             PG8_WAIT_V(8); PG8_WAIT_L(0); PG8_BAR; PG8_MMA(0, 0, At, B0); PG8_MMA(0, 1, At, B1); PG8_BAR; PG8_SCHED;
	s_setprio 1
	v_mfma_f32_16x16x32_bf16 v[60:63], v[128:131], v[188:191], v[60:63]
	v_mfma_f32_16x16x32_bf16 v[60:63], v[132:135], v[192:195], v[60:63]
	v_mfma_f32_16x16x32_bf16 v[56:59], v[140:143], v[192:195], v[56:59]
	v_mfma_f32_16x16x32_bf16 v[56:59], v[136:139], v[188:191], v[56:59]
	v_mfma_f32_16x16x32_bf16 v[52:55], v[144:147], v[188:191], v[52:55]
	v_mfma_f32_16x16x32_bf16 v[52:55], v[148:151], v[192:195], v[52:55]
	v_mfma_f32_16x16x32_bf16 v[48:51], v[184:187], v[192:195], v[48:51]
	v_mfma_f32_16x16x32_bf16 v[48:51], v[176:179], v[188:191], v[48:51]
	v_mfma_f32_16x16x32_bf16 v[32:35], v[176:179], v[196:199], v[32:35]
	v_mfma_f32_16x16x32_bf16 v[32:35], v[184:187], v[200:203], v[32:35]
	v_mfma_f32_16x16x32_bf16 v[36:39], v[148:151], v[200:203], v[36:39]
	v_mfma_f32_16x16x32_bf16 v[36:39], v[144:147], v[196:199], v[36:39]
	v_mfma_f32_16x16x32_bf16 v[40:43], v[136:139], v[196:199], v[40:43]
	v_mfma_f32_16x16x32_bf16 v[40:43], v[140:143], v[200:203], v[40:43]
	v_mfma_f32_16x16x32_bf16 v[44:47], v[132:135], v[200:203], v[44:47]
	v_mfma_f32_16x16x32_bf16 v[44:47], v[128:131], v[196:199], v[44:47]
	s_setprio 0
	s_setprio 1
	v_mfma_f32_16x16x32_bf16 v[28:31], v[128:131], v[208:211], v[28:31]
	v_mfma_f32_16x16x32_bf16 v[28:31], v[132:135], v[212:215], v[28:31]
	v_mfma_f32_16x16x32_bf16 v[24:27], v[140:143], v[212:215], v[24:27]
	v_mfma_f32_16x16x32_bf16 v[24:27], v[136:139], v[208:211], v[24:27]
	v_mfma_f32_16x16x32_bf16 v[20:23], v[144:147], v[208:211], v[20:23]
	v_mfma_f32_16x16x32_bf16 v[20:23], v[148:151], v[212:215], v[20:23]
	v_mfma_f32_16x16x32_bf16 v[16:19], v[184:187], v[212:215], v[16:19]
	v_mfma_f32_16x16x32_bf16 v[16:19], v[176:179], v[208:211], v[16:19]
	v_mfma_f32_16x16x32_bf16 v[0:3], v[176:179], v[216:219], v[0:3]
	v_mfma_f32_16x16x32_bf16 v[0:3], v[184:187], v[220:223], v[0:3]
	v_mfma_f32_16x16x32_bf16 v[4:7], v[148:151], v[220:223], v[4:7]
	v_mfma_f32_16x16x32_bf16 v[4:7], v[144:147], v[216:219], v[4:7]
	v_mfma_f32_16x16x32_bf16 v[8:11], v[136:139], v[216:219], v[8:11]
	v_mfma_f32_16x16x32_bf16 v[8:11], v[140:143], v[220:223], v[8:11]
	v_mfma_f32_16x16x32_bf16 v[12:15], v[132:135], v[220:223], v[12:15]
	v_mfma_f32_16x16x32_bf16 v[12:15], v[128:131], v[216:219], v[12:15]
	s_setprio 0
	s_barrier
	s_add_i32 s21, 0, 0x18000
	s_add_i32 s33, 0, 0x1c000
	v_add_u32_e32 v140, s21, v163
	v_add_u32_e32 v172, s33, v163
	ds_read_b128 v[128:131], v140
	ds_read_b128 v[132:135], v140 offset:1024
	ds_read_b128 v[136:139], v140 offset:2048
	ds_read_b128 v[140:143], v140 offset:3072
	ds_read_b128 v[144:147], v172
	ds_read_b128 v[148:151], v172 offset:1024
	ds_read_b128 v[176:179], v172 offset:2048
	ds_read_b128 v[184:187], v172 offset:3072
	s_add_u32 s12, s12, 0x80000
	s_addc_u32 s13, s13, 0
	s_mov_b32 m0, s49
	v_lshl_add_u64 v[234:235], s[12:13], 0, v[152:153]
	ds_read_b128 v[188:191], v181 offset:32768
	ds_read_b128 v[192:195], v181 offset:33792
	ds_read_b128 v[196:199], v181 offset:34816
	ds_read_b128 v[200:203], v181 offset:35840
	ds_read_b128 v[208:211], v181 offset:36864
	ds_read_b128 v[212:215], v181 offset:37888
	ds_read_b128 v[216:219], v181 offset:38912
	ds_read_b128 v[220:223], v181 offset:39936
	global_load_lds_dwordx4 v[234:235], off
	v_lshl_add_u64 v[234:235], s[12:13], 0, v[156:157]
	s_mov_b32 m0, s50
	s_nop 0
	global_load_lds_dwordx4 v[234:235], off
	s_waitcnt vmcnt(8) lgkmcnt(0)
	s_barrier
	s_setprio 1
	v_mfma_f32_16x16x32_bf16 v[124:127], v[128:131], v[188:191], v[124:127]
	v_mfma_f32_16x16x32_bf16 v[124:127], v[132:135], v[192:195], v[124:127]
	v_mfma_f32_16x16x32_bf16 v[120:123], v[140:143], v[192:195], v[120:123]
	v_mfma_f32_16x16x32_bf16 v[120:123], v[136:139], v[188:191], v[120:123]
	v_mfma_f32_16x16x32_bf16 v[116:119], v[144:147], v[188:191], v[116:119]
	v_mfma_f32_16x16x32_bf16 v[116:119], v[148:151], v[192:195], v[116:119]
	v_mfma_f32_16x16x32_bf16 v[112:115], v[184:187], v[192:195], v[112:115]
	v_mfma_f32_16x16x32_bf16 v[112:115], v[176:179], v[188:191], v[112:115]
	v_mfma_f32_16x16x32_bf16 v[96:99], v[176:179], v[196:199], v[96:99]
	v_mfma_f32_16x16x32_bf16 v[96:99], v[184:187], v[200:203], v[96:99]
	v_mfma_f32_16x16x32_bf16 v[100:103], v[148:151], v[200:203], v[100:103]
	v_mfma_f32_16x16x32_bf16 v[100:103], v[144:147], v[196:199], v[100:103]
	v_mfma_f32_16x16x32_bf16 v[104:107], v[136:139], v[196:199], v[104:107]
	v_mfma_f32_16x16x32_bf16 v[104:107], v[140:143], v[200:203], v[104:107]
	v_mfma_f32_16x16x32_bf16 v[108:111], v[132:135], v[200:203], v[108:111]
	v_mfma_f32_16x16x32_bf16 v[108:111], v[128:131], v[196:199], v[108:111]
	s_setprio 0
	s_setprio 1
	v_mfma_f32_16x16x32_bf16 v[92:95], v[128:131], v[208:211], v[92:95]
	v_mfma_f32_16x16x32_bf16 v[92:95], v[132:135], v[212:215], v[92:95]
	v_mfma_f32_16x16x32_bf16 v[88:91], v[140:143], v[212:215], v[88:91]
	v_mfma_f32_16x16x32_bf16 v[88:91], v[136:139], v[208:211], v[88:91]
	v_mfma_f32_16x16x32_bf16 v[84:87], v[144:147], v[208:211], v[84:87]
	v_mfma_f32_16x16x32_bf16 v[84:87], v[148:151], v[212:215], v[84:87]
	v_mfma_f32_16x16x32_bf16 v[80:83], v[184:187], v[212:215], v[80:83]
	v_mfma_f32_16x16x32_bf16 v[80:83], v[176:179], v[208:211], v[80:83]
	v_mfma_f32_16x16x32_bf16 v[64:67], v[176:179], v[216:219], v[64:67]
	v_mfma_f32_16x16x32_bf16 v[64:67], v[184:187], v[220:223], v[64:67]
	v_mfma_f32_16x16x32_bf16 v[68:71], v[148:151], v[220:223], v[68:71]
	v_mfma_f32_16x16x32_bf16 v[68:71], v[144:147], v[216:219], v[68:71]
	v_mfma_f32_16x16x32_bf16 v[72:75], v[136:139], v[216:219], v[72:75]
	v_mfma_f32_16x16x32_bf16 v[72:75], v[140:143], v[220:223], v[72:75]
	v_mfma_f32_16x16x32_bf16 v[76:79], v[132:135], v[220:223], v[76:79]
	v_mfma_f32_16x16x32_bf16 v[76:79], v[128:131], v[216:219], v[76:79]
	s_setprio 0
	s_barrier
; #define PG8_STAGE(bufoff, gbase, voff) do { _Pragma("unroll") for (int _i = 0; _i < 2; ++_i) \
;         __builtin_amdgcn_global_load_lds((const unsigned*)((const char*)(gbase) + (voff)[_i]), (LAS unsigned*)(lds + (bufoff) + ldsw + _i * 8192), 16, 0, 0); } while (0)
; #define PG8_LDA(dst, b, h) do { _Pragma("unroll") for (int m = 0; m < 4; ++m) _Pragma("unroll") for (int k = 0; k < 2; ++k) dst[m][k] = *(const LAS bf16x8*)(lds + PG8_SA(b, h) + aoff + m * 2048 + k * 1024); } while (0)
; #define PG8_MMA(ai, bj, At, Bt) do { __builtin_amdgcn_s_setprio(1); _Pragma("unroll") for (int m = 0; m < 4; ++m) _Pragma("unroll") for (int n = 0; n < 2; ++n) _Pragma("unroll") for (int k = 0; k < 2; ++k) \
;         acc[ai][bj][m][n] = __builtin_amdgcn_mfma_f32_16x16x32_bf16(Bt[n][k], At[m][k], acc[ai][bj][m][n], 0, 0, 0); __builtin_amdgcn_s_setprio(0); } while (0)
; #define PG8_WAIT_V(n) asm volatile("s_waitcnt vmcnt(" #n ")" ::: "memory")
; #define PG8_WAIT_L(n) asm volatile("s_waitcnt lgkmcnt(" #n ")" ::: "memory")
; #define PG8_BAR __builtin_amdgcn_s_barrier()
; #define PG8_SCHED __builtin_amdgcn_sched_barrier(0)
; template <class Epi>
; __device__ __forceinline__ void gemm_phase(LAS unsigned char* lds, const Gemm g, const StaticOrder& S, const Epi& E) {
;     ...
;             PG8_LDA(At, 1, 1); PG8_STAGE(PG8_SB(1, 0), b3, voffB); PG8_STAGE(PG8_SB(1, 1), b3 + hstepB, voffB); PG8_STAGE(PG8_SA(1, 0), a3, voffA);
;             PG8_WAIT_V(8); PG8_WAIT_L(0); PG8_BAR; PG8_MMA(1, 0, At, B0); PG8_MMA(1, 1, At, B1); PG8_BAR; PG8_SCHED;
;         }
	s_add_i32 s12, s21, s46
	v_lshl_add_u64 v[224:225], v[224:225], 0, s[28:29]
	s_mov_b32 m0, s12
	ds_read_b128 v[188:191], v181 offset:49152
	ds_read_b128 v[192:195], v181 offset:50176
	ds_read_b128 v[196:199], v181 offset:51200
	ds_read_b128 v[200:203], v181 offset:52224
	ds_read_b128 v[208:211], v181 offset:53248
	ds_read_b128 v[212:215], v181 offset:54272
	ds_read_b128 v[216:219], v181 offset:55296
	ds_read_b128 v[220:223], v181 offset:56320
	global_load_lds_dwordx4 v[224:225], off
	s_add_i32 m0, s12, 0x2000
	s_add_u32 s10, s10, 0x80080
	v_lshl_add_u64 v[224:225], v[226:227], 0, s[28:29]
	s_addc_u32 s11, s11, 0
	s_add_i32 s12, s33, s46
	global_load_lds_dwordx4 v[224:225], off
	v_lshl_add_u64 v[224:225], s[10:11], 0, v[154:155]
	s_mov_b32 m0, s12
	s_nop 0
	global_load_lds_dwordx4 v[224:225], off
	v_lshl_add_u64 v[224:225], s[10:11], 0, v[158:159]
	s_add_i32 m0, s12, 0x2000
	s_nop 0
	global_load_lds_dwordx4 v[224:225], off
	v_lshl_add_u64 v[224:225], v[230:231], 0, s[28:29]
	s_mov_b32 m0, s54
	s_nop 0
	global_load_lds_dwordx4 v[224:225], off
	v_lshl_add_u64 v[224:225], v[232:233], 0, s[28:29]
	s_mov_b32 m0, s55
	s_nop 0
	global_load_lds_dwordx4 v[224:225], off
	s_waitcnt vmcnt(8) lgkmcnt(0)
	s_barrier
	s_setprio 1
	v_mfma_f32_16x16x32_bf16 v[60:63], v[128:131], v[188:191], v[60:63]
	v_mfma_f32_16x16x32_bf16 v[60:63], v[132:135], v[192:195], v[60:63]
	v_mfma_f32_16x16x32_bf16 v[56:59], v[140:143], v[192:195], v[56:59]
	v_mfma_f32_16x16x32_bf16 v[56:59], v[136:139], v[188:191], v[56:59]
	v_mfma_f32_16x16x32_bf16 v[52:55], v[144:147], v[188:191], v[52:55]
	v_mfma_f32_16x16x32_bf16 v[52:55], v[148:151], v[192:195], v[52:55]
	v_mfma_f32_16x16x32_bf16 v[48:51], v[184:187], v[192:195], v[48:51]
	v_mfma_f32_16x16x32_bf16 v[48:51], v[176:179], v[188:191], v[48:51]
	v_mfma_f32_16x16x32_bf16 v[32:35], v[176:179], v[196:199], v[32:35]
	v_mfma_f32_16x16x32_bf16 v[32:35], v[184:187], v[200:203], v[32:35]
	v_mfma_f32_16x16x32_bf16 v[36:39], v[148:151], v[200:203], v[36:39]
	v_mfma_f32_16x16x32_bf16 v[36:39], v[144:147], v[196:199], v[36:39]
	v_mfma_f32_16x16x32_bf16 v[40:43], v[136:139], v[196:199], v[40:43]
	v_mfma_f32_16x16x32_bf16 v[40:43], v[140:143], v[200:203], v[40:43]
	v_mfma_f32_16x16x32_bf16 v[44:47], v[132:135], v[200:203], v[44:47]
	v_mfma_f32_16x16x32_bf16 v[44:47], v[128:131], v[196:199], v[44:47]
	s_setprio 0
	s_setprio 1
	v_mfma_f32_16x16x32_bf16 v[28:31], v[128:131], v[208:211], v[28:31]
	v_mfma_f32_16x16x32_bf16 v[28:31], v[132:135], v[212:215], v[28:31]
	v_mfma_f32_16x16x32_bf16 v[24:27], v[140:143], v[212:215], v[24:27]
	v_mfma_f32_16x16x32_bf16 v[24:27], v[136:139], v[208:211], v[24:27]
	v_mfma_f32_16x16x32_bf16 v[20:23], v[144:147], v[208:211], v[20:23]
	v_mfma_f32_16x16x32_bf16 v[20:23], v[148:151], v[212:215], v[20:23]
	v_mfma_f32_16x16x32_bf16 v[16:19], v[184:187], v[212:215], v[16:19]
	v_mfma_f32_16x16x32_bf16 v[16:19], v[176:179], v[208:211], v[16:19]
	v_mfma_f32_16x16x32_bf16 v[0:3], v[176:179], v[216:219], v[0:3]
	v_mfma_f32_16x16x32_bf16 v[0:3], v[184:187], v[220:223], v[0:3]
	v_mfma_f32_16x16x32_bf16 v[4:7], v[148:151], v[220:223], v[4:7]
	v_mfma_f32_16x16x32_bf16 v[4:7], v[144:147], v[216:219], v[4:7]
	v_mfma_f32_16x16x32_bf16 v[8:11], v[136:139], v[216:219], v[8:11]
	v_mfma_f32_16x16x32_bf16 v[8:11], v[140:143], v[220:223], v[8:11]
	v_mfma_f32_16x16x32_bf16 v[12:15], v[132:135], v[220:223], v[12:15]
	v_mfma_f32_16x16x32_bf16 v[12:15], v[128:131], v[216:219], v[12:15]
	s_setprio 0
	s_barrier
	s_add_u32 s8, s8, 0x100
	s_addc_u32 s9, s9, 0
	s_add_u32 s18, s18, 0x100
	s_addc_u32 s19, s19, 0
	s_cmp_ge_i32 s20, s53
	s_mov_b32 s10, s20
	s_cbranch_scc0 .LBB0_1338
